# streaming nt stores (FFN hidden, gates, residual x) made write-through sc0 sc1 nt so the barrier L2 writeback has less dirty data
# speedup vs baseline: 1.0150x; 1.0150x over previous
; __device__ __forceinline__ void ew_post(const bf16* Y, const float* xin, float* xout, const float* gpost, const float* gnext, bf16* H, int gw, int ngw, int lane) {
;     for (int m0 = EW_NR * gw; m0 < NTOK; m0 += EW_NR * ngw) {
;         f32x4 y[EW_NR][4], xv[EW_NR][4]; float s[EW_NR];
; #pragma unroll
;         for (int q = 0; q < EW_NR; ++q) { const v2u* yr = (const v2u*)(Y + (size_t)(m0 + q) * DM) + lane; const f32x4* xr = (const f32x4*)(xin + (size_t)(m0 + q) * DM) + lane;
; #pragma unroll
;             for (int j = 0; j < 4; ++j) { const v2u w = __builtin_nontemporal_load(yr + 64 * j); y[q][j] = (f32x4){bf_lo(w.x), bf_hi(w.x), bf_lo(w.y), bf_hi(w.y)}; xv[q][j] = __builtin_nontemporal_load(xr + 64 * j); } }
; #pragma unroll
;         for (int q = 0; q < EW_NR; ++q) { s[q] = 0.f;
; #pragma unroll
;             for (int j = 0; j < 4; ++j) s[q] += (y[q][j].x * y[q][j].x + y[q][j].y * y[q][j].y) + (y[q][j].z * y[q][j].z + y[q][j].w * y[q][j].w); }
.LBB0_191:
	global_load_dwordx2 v[16:17], v[68:69], off offset:-4096 nt
	global_load_dwordx2 v[18:19], v[68:69], off offset:-2048 nt
	global_load_dwordx2 v[20:21], v[68:69], off nt
	v_add_co_u32_e32 v0, vcc, 0xfffff000, v68
	s_movk_i32 s4, 0xf000
	s_nop 0
	v_addc_co_u32_e32 v1, vcc, -1, v69, vcc
	global_load_dwordx2 v[22:23], v[0:1], off offset:-2048 nt
	global_load_dwordx2 v[24:25], v[0:1], off offset:-3584 nt
	global_load_dwordx2 v[26:27], v[0:1], off offset:-3072 nt
	global_load_dwordx2 v[28:29], v[0:1], off offset:-2560 nt
	global_load_dwordx2 v[30:31], v[0:1], off offset:-1536 nt
	global_load_dwordx2 v[42:43], v[68:69], off offset:-3584 nt
	global_load_dwordx2 v[84:85], v[68:69], off offset:-3072 nt
	global_load_dwordx2 v[94:95], v[68:69], off offset:-2560 nt
	global_load_dwordx4 v[4:7], v[70:71], off offset:-3072 nt
	global_load_dwordx2 v[38:39], v[0:1], off offset:-1024 nt
	global_load_dwordx2 v[46:47], v[68:69], off offset:-1536 nt
	global_load_dwordx2 v[86:87], v[68:69], off offset:-1024 nt
	global_load_dwordx2 v[88:89], v[68:69], off offset:-512 nt
	global_load_dwordx2 v[40:41], v[0:1], off offset:-512 nt
	v_add_co_u32_e32 v36, vcc, s4, v70
	s_movk_i32 s6, 0xe000
	s_nop 0
	v_addc_co_u32_e32 v37, vcc, -1, v71, vcc
	v_add_co_u32_e32 v48, vcc, 0xffffd000, v70
	s_mov_b64 s[4:5], vcc
	v_addc_co_u32_e64 v49, s[4:5], -1, v71, s[4:5]
	global_load_dwordx4 v[0:3], v[48:49], off offset:-3072 nt
	v_add_co_u32_e32 v50, vcc, s6, v70
	global_load_dwordx4 v[8:11], v[36:37], off offset:-3072 nt
	s_nop 0
	v_addc_co_u32_e32 v51, vcc, -1, v71, vcc
	global_load_dwordx4 v[12:15], v[50:51], off offset:-3072 nt
	s_waitcnt vmcnt(0)
	v_lshlrev_b32_e32 v79, 16, v22
	v_and_b32_e32 v59, 0xffff0000, v22
	v_lshlrev_b32_e32 v60, 16, v23
	v_and_b32_e32 v61, 0xffff0000, v23
	v_lshlrev_b32_e32 v54, 16, v17
	v_and_b32_e32 v55, 0xffff0000, v17
	v_lshlrev_b32_e32 v72, 16, v19
	v_and_b32_e32 v73, 0xffff0000, v19
	s_waitcnt vmcnt(15)
	v_and_b32_e32 v17, 0xffff0000, v24
	v_and_b32_e32 v19, 0xffff0000, v25
	v_lshlrev_b32_e32 v83, 16, v16
	v_and_b32_e32 v53, 0xffff0000, v16
	v_lshlrev_b32_e32 v81, 16, v18
	v_and_b32_e32 v63, 0xffff0000, v18
	v_lshlrev_b32_e32 v16, 16, v24
	v_lshlrev_b32_e32 v18, 16, v25
	s_waitcnt vmcnt(14)
	v_and_b32_e32 v23, 0xffff0000, v27
	v_and_b32_e32 v22, 0xffff0000, v26
	s_waitcnt vmcnt(13)
	v_lshlrev_b32_e32 v32, 16, v28
	v_and_b32_e32 v33, 0xffff0000, v28
	v_mul_f32_e32 v24, v19, v19
	v_mul_f32_e32 v28, v17, v17
	v_mov_b32_e32 v25, v79
	v_lshlrev_b32_e32 v77, 16, v20
	v_and_b32_e32 v57, 0xffff0000, v20
	v_lshlrev_b32_e32 v74, 16, v21
	v_and_b32_e32 v75, 0xffff0000, v21
	v_lshlrev_b32_e32 v21, 16, v27
	v_lshlrev_b32_e32 v20, 16, v26
	v_lshlrev_b32_e32 v34, 16, v29
	v_and_b32_e32 v35, 0xffff0000, v29
	v_pk_mul_f32 v[26:27], v[22:23], v[22:23]
	v_pk_fma_f32 v[90:91], v[18:19], v[18:19], v[24:25] op_sel_hi:[1,1,0]
	v_pk_fma_f32 v[28:29], v[16:17], v[16:17], v[28:29] op_sel_hi:[1,1,0]
	v_mul_f32_e32 v44, v33, v33
	v_mul_f32_e32 v52, v35, v35
	v_pk_fma_f32 v[26:27], v[20:21], v[20:21], v[26:27]
	v_mov_b32_e32 v78, v28
	v_mov_b32_e32 v24, v90
	v_mul_f32_e32 v56, v59, v59
	v_mul_f32_e32 v58, v60, v60
	v_mul_f32_e32 v62, v61, v61
	v_pk_fma_f32 v[44:45], v[32:33], v[32:33], v[44:45] op_sel_hi:[1,1,0]
	v_pk_fma_f32 v[92:93], v[34:35], v[34:35], v[52:53] op_sel_hi:[1,1,0]
	v_pk_add_f32 v[28:29], v[28:29], v[90:91]
	v_pk_add_f32 v[26:27], v[26:27], v[26:27] op_sel:[0,1] op_sel_hi:[1,0]
	v_pk_mul_f32 v[24:25], v[78:79], v[24:25]
	v_mov_b32_e32 v45, v58
	v_mov_b32_e32 v27, v56
	v_mov_b32_e32 v29, v25
	v_mov_b32_e32 v93, v62
	v_pk_add_f32 v[24:25], v[28:29], v[26:27]
	v_pk_add_f32 v[26:27], v[44:45], v[92:93]
	s_waitcnt vmcnt(12)
	v_and_b32_e32 v45, 0xffff0000, v30
	v_and_b32_e32 v93, 0xffff0000, v31
	v_pk_add_f32 v[102:103], v[24:25], v[26:27]
	v_lshlrev_b32_e32 v44, 16, v30
	v_lshlrev_b32_e32 v92, 16, v31
	v_mul_f32_e32 v24, v93, v93
	s_waitcnt vmcnt(7)
	v_and_b32_e32 v27, 0xffff0000, v39
	v_and_b32_e32 v26, 0xffff0000, v38
	v_mul_f32_e32 v52, v45, v45
	v_pk_fma_f32 v[28:29], v[92:93], v[92:93], v[24:25] op_sel_hi:[1,1,0]
	v_lshlrev_b32_e32 v25, 16, v39
	v_lshlrev_b32_e32 v24, 16, v38
	v_pk_mul_f32 v[30:31], v[26:27], v[26:27]
	v_pk_fma_f32 v[90:91], v[44:45], v[44:45], v[52:53] op_sel_hi:[1,1,0]
	v_pk_fma_f32 v[30:31], v[24:25], v[24:25], v[30:31]
	v_mov_b32_e32 v82, v90
	v_mov_b32_e32 v96, v28
	v_mov_b32_e32 v97, v83
	v_mul_f32_e32 v56, v53, v53
	v_pk_add_f32 v[28:29], v[90:91], v[28:29]
	v_pk_mul_f32 v[90:91], v[82:83], v[96:97]
	v_pk_add_f32 v[30:31], v[30:31], v[30:31] op_sel:[0,1] op_sel_hi:[1,0]
	s_waitcnt vmcnt(3)
; __device__ __forceinline__ void ew_post(const bf16* Y, const float* xin, float* xout, const float* gpost, const float* gnext, bf16* H, int gw, int ngw, int lane) {
;     ...
;         for (int q = 0; q < EW_NR; ++q) { const v2u* yr = (const v2u*)(Y + (size_t)(m0 + q) * DM) + lane; const f32x4* xr = (const f32x4*)(xin + (size_t)(m0 + q) * DM) + lane;
; #pragma unroll
;             for (int j = 0; j < 4; ++j) { const v2u w = __builtin_nontemporal_load(yr + 64 * j); y[q][j] = (f32x4){bf_lo(w.x), bf_hi(w.x), bf_lo(w.y), bf_hi(w.y)}; xv[q][j] = __builtin_nontemporal_load(xr + 64 * j); } }
; #pragma unroll
;         for (int q = 0; q < EW_NR; ++q) { s[q] = 0.f;
; #pragma unroll
;             for (int j = 0; j < 4; ++j) s[q] += (y[q][j].x * y[q][j].x + y[q][j].y * y[q][j].y) + (y[q][j].z * y[q][j].z + y[q][j].w * y[q][j].w); }
;         float rstd[EW_NR], s2[EW_NR];
; #pragma unroll
;         for (int q = 0; q < EW_NR; ++q) { rstd[q] = rsqrtf(wave_sum(s[q]) * (1.f / DM) + RMS_EPS); s2[q] = 0.f; }
; #pragma unroll
;         for (int j = 0; j < 4; ++j) { const f32x4 g = *((const f32x4*)gpost + lane + 64 * j);
	v_lshlrev_b32_e32 v38, 16, v40
	v_and_b32_e32 v39, 0xffff0000, v40
	v_lshlrev_b32_e32 v40, 16, v41
	v_and_b32_e32 v41, 0xffff0000, v41
	v_mov_b32_e32 v29, v91
	v_mov_b32_e32 v31, v56
	v_pk_add_f32 v[28:29], v[28:29], v[30:31]
	v_mul_f32_e32 v30, v39, v39
	v_mul_f32_e32 v52, v41, v41
	v_mul_f32_e32 v58, v54, v54
	v_mul_f32_e32 v62, v55, v55
	v_pk_fma_f32 v[30:31], v[38:39], v[38:39], v[30:31] op_sel_hi:[1,1,0]
	v_pk_fma_f32 v[90:91], v[40:41], v[40:41], v[52:53] op_sel_hi:[1,1,0]
	v_mov_b32_e32 v31, v58
	v_mov_b32_e32 v91, v62
	v_pk_add_f32 v[30:31], v[30:31], v[90:91]
	v_and_b32_e32 v97, 0xffff0000, v43
	v_pk_add_f32 v[114:115], v[28:29], v[30:31]
	v_and_b32_e32 v91, 0xffff0000, v42
	v_lshlrev_b32_e32 v96, 16, v43
	v_mul_f32_e32 v28, v97, v97
	v_and_b32_e32 v31, 0xffff0000, v85
	v_and_b32_e32 v30, 0xffff0000, v84
	v_lshlrev_b32_e32 v90, 16, v42
	v_pk_fma_f32 v[98:99], v[96:97], v[96:97], v[28:29] op_sel_hi:[1,1,0]
	v_lshlrev_b32_e32 v29, 16, v85
	v_lshlrev_b32_e32 v28, 16, v84
	v_pk_mul_f32 v[42:43], v[30:31], v[30:31]
	v_mul_f32_e32 v52, v91, v91
	v_pk_fma_f32 v[100:101], v[28:29], v[28:29], v[42:43]
	v_lshlrev_b32_e32 v42, 16, v94
	v_and_b32_e32 v43, 0xffff0000, v94
	v_lshlrev_b32_e32 v84, 16, v95
	v_and_b32_e32 v85, 0xffff0000, v95
	v_pk_fma_f32 v[94:95], v[90:91], v[90:91], v[52:53] op_sel_hi:[1,1,0]
	v_mov_b32_e32 v110, v98
	v_mov_b32_e32 v80, v94
	v_mov_b32_e32 v111, v81
	v_pk_add_f32 v[94:95], v[94:95], v[98:99]
	v_pk_mul_f32 v[98:99], v[80:81], v[110:111]
	global_load_dwordx4 v[110:113], v[64:65], off
	v_mul_f32_e32 v56, v63, v63
	v_mov_b32_e32 v95, v99
	v_pk_add_f32 v[98:99], v[100:101], v[100:101] op_sel:[0,1] op_sel_hi:[1,0]
	v_mul_f32_e32 v52, v43, v43
	v_mov_b32_e32 v99, v56
	v_pk_add_f32 v[94:95], v[94:95], v[98:99]
	v_pk_fma_f32 v[98:99], v[42:43], v[42:43], v[52:53] op_sel_hi:[1,1,0]
	v_mul_f32_e32 v52, v85, v85
	v_mul_f32_e32 v58, v72, v72
	v_mul_f32_e32 v62, v73, v73
	v_pk_fma_f32 v[100:101], v[84:85], v[84:85], v[52:53] op_sel_hi:[1,1,0]
	v_mov_b32_e32 v99, v58
	v_mov_b32_e32 v101, v62
	v_pk_add_f32 v[98:99], v[98:99], v[100:101]
	v_and_b32_e32 v101, 0xffff0000, v47
	v_pk_add_f32 v[116:117], v[94:95], v[98:99]
	v_and_b32_e32 v99, 0xffff0000, v46
	v_lshlrev_b32_e32 v98, 16, v46
	v_lshlrev_b32_e32 v100, 16, v47
	v_mul_f32_e32 v46, v101, v101
	v_mul_f32_e32 v52, v99, v99
	v_pk_fma_f32 v[118:119], v[100:101], v[100:101], v[46:47] op_sel_hi:[1,1,0]
	v_pk_fma_f32 v[122:123], v[98:99], v[98:99], v[52:53] op_sel_hi:[1,1,0]
	v_and_b32_e32 v95, 0xffff0000, v87
	v_mov_b32_e32 v76, v122
	v_pk_add_f32 v[122:123], v[122:123], v[118:119]
	v_mov_b32_e32 v119, v77
	v_pk_mul_f32 v[118:119], v[76:77], v[118:119]
	v_and_b32_e32 v94, 0xffff0000, v86
	v_mov_b32_e32 v123, v119
	v_mov_b32_e32 v118, v114
	v_mov_b32_e32 v119, v102
	v_mov_b32_e32 v102, v115
	v_pk_add_f32 v[102:103], v[118:119], v[102:103]
	ds_bpermute_b32 v115, v104, v103
	ds_bpermute_b32 v114, v104, v102
	v_lshlrev_b32_e32 v47, 16, v87
	v_lshlrev_b32_e32 v46, 16, v86
	v_pk_mul_f32 v[86:87], v[94:95], v[94:95]
	v_mul_f32_e32 v56, v57, v57
	v_pk_fma_f32 v[120:121], v[46:47], v[46:47], v[86:87]
	v_and_b32_e32 v87, 0xffff0000, v88
	s_waitcnt lgkmcnt(0)
	v_pk_add_f32 v[102:103], v[102:103], v[114:115]
	v_lshlrev_b32_e32 v86, 16, v88
	v_lshlrev_b32_e32 v88, 16, v89
	v_and_b32_e32 v89, 0xffff0000, v89
	v_pk_add_f32 v[118:119], v[120:121], v[120:121] op_sel:[0,1] op_sel_hi:[1,0]
	ds_bpermute_b32 v115, v105, v103
	ds_bpermute_b32 v114, v105, v102
	v_mul_f32_e32 v52, v87, v87
	v_mov_b32_e32 v119, v56
	v_pk_fma_f32 v[120:121], v[86:87], v[86:87], v[52:53] op_sel_hi:[1,1,0]
	v_mul_f32_e32 v52, v89, v89
	v_mul_f32_e32 v58, v74, v74
	v_mul_f32_e32 v62, v75, v75
	v_pk_add_f32 v[118:119], v[122:123], v[118:119]
	v_pk_fma_f32 v[122:123], v[88:89], v[88:89], v[52:53] op_sel_hi:[1,1,0]
	v_mov_b32_e32 v121, v58
	v_mov_b32_e32 v123, v62
	v_pk_add_f32 v[120:121], v[120:121], v[122:123]
	s_waitcnt lgkmcnt(0)
	v_pk_add_f32 v[102:103], v[102:103], v[114:115]
	v_pk_add_f32 v[118:119], v[118:119], v[120:121]
	ds_bpermute_b32 v115, v106, v103
	ds_bpermute_b32 v114, v106, v102
	v_mov_b32_e32 v120, v118
	v_mov_b32_e32 v121, v116
	v_mov_b32_e32 v116, v119
	v_pk_add_f32 v[116:117], v[120:121], v[116:117]
	ds_bpermute_b32 v119, v104, v117
	ds_bpermute_b32 v118, v104, v116
	s_waitcnt lgkmcnt(2)
	v_pk_add_f32 v[102:103], v[102:103], v[114:115]
	ds_bpermute_b32 v115, v107, v103
	ds_bpermute_b32 v114, v107, v102
	v_mov_b32_e32 v62, v81
	s_waitcnt lgkmcnt(2)
	v_pk_add_f32 v[118:119], v[116:117], v[118:119]
	ds_bpermute_b32 v121, v105, v119
	ds_bpermute_b32 v120, v105, v118
	s_waitcnt lgkmcnt(2)
	v_pk_add_f32 v[102:103], v[102:103], v[114:115]
	ds_bpermute_b32 v115, v108, v103
	ds_bpermute_b32 v114, v108, v102
	s_waitcnt lgkmcnt(2)
	v_pk_add_f32 v[118:119], v[118:119], v[120:121]
	ds_bpermute_b32 v121, v106, v119
	ds_bpermute_b32 v120, v106, v118
	s_waitcnt lgkmcnt(2)
	v_pk_add_f32 v[102:103], v[102:103], v[114:115]
	ds_bpermute_b32 v123, v109, v103
	ds_bpermute_b32 v122, v109, v102
	global_load_dwordx4 v[114:117], v[48:49], off offset:-2048 nt
	s_waitcnt lgkmcnt(2)
	v_pk_add_f32 v[118:119], v[118:119], v[120:121]
	ds_bpermute_b32 v121, v107, v119
	ds_bpermute_b32 v120, v107, v118
	s_waitcnt lgkmcnt(2)
	v_pk_add_f32 v[102:103], v[102:103], v[122:123]
	v_mov_b64_e32 v[122:123], s[24:25]
	v_pk_fma_f32 v[102:103], v[102:103], s[44:45], v[122:123] op_sel_hi:[1,0,0]
	s_waitcnt lgkmcnt(0)
	v_pk_add_f32 v[118:119], v[118:119], v[120:121]
	v_mul_f32_e32 v52, 0x4b800000, v103
	v_cmp_gt_f32_e32 vcc, s3, v103
	ds_bpermute_b32 v121, v108, v119
	ds_bpermute_b32 v120, v108, v118
	v_cndmask_b32_e32 v52, v103, v52, vcc
	v_rsq_f32_e32 v52, v52
	v_mul_f32_e32 v56, 0x4b800000, v102
	v_cmp_gt_f32_e64 s[4:5], s3, v102
	v_mul_f32_e32 v58, 0x45800000, v52
	s_nop 0
	v_cndmask_b32_e64 v56, v102, v56, s[4:5]
	s_waitcnt lgkmcnt(0)
; __device__ __forceinline__ void ew_post(const bf16* Y, const float* xin, float* xout, const float* gpost, const float* gnext, bf16* H, int gw, int ngw, int lane) {
;     ...
;         for (int q = 0; q < EW_NR; ++q) { rstd[q] = rsqrtf(wave_sum(s[q]) * (1.f / DM) + RMS_EPS); s2[q] = 0.f; }
; #pragma unroll
;         for (int j = 0; j < 4; ++j) { const f32x4 g = *((const f32x4*)gpost + lane + 64 * j);
; #pragma unroll
;             for (int q = 0; q < EW_NR; ++q) { xv[q][j] = xv[q][j] + y[q][j] * rstd[q] * g; __builtin_nontemporal_store(xv[q][j], (f32x4*)(xout + (size_t)(m0 + q) * DM) + lane + 64 * j);
;                 s2[q] += (xv[q][j].x * xv[q][j].x + xv[q][j].y * xv[q][j].y) + (xv[q][j].z * xv[q][j].z + xv[q][j].w * xv[q][j].w); } }
	v_pk_add_f32 v[102:103], v[118:119], v[120:121]
	v_cndmask_b32_e32 v76, v52, v58, vcc
	v_rsq_f32_e32 v52, v56
	ds_bpermute_b32 v119, v109, v103
	ds_bpermute_b32 v118, v109, v102
	v_pk_mul_f32 v[16:17], v[76:77], v[16:17] op_sel_hi:[0,1]
	s_waitcnt vmcnt(1)
	v_pk_fma_f32 v[0:1], v[16:17], v[110:111], v[0:1]
	v_mul_f32_e32 v16, 0x45800000, v52
	v_cndmask_b32_e64 v78, v52, v16, s[4:5]
	s_waitcnt lgkmcnt(0)
	v_pk_add_f32 v[16:17], v[102:103], v[118:119]
	v_pk_mul_f32 v[18:19], v[76:77], v[18:19] op_sel_hi:[0,1]
	v_pk_fma_f32 v[16:17], v[16:17], s[44:45], v[122:123] op_sel_hi:[1,0,0]
	v_pk_fma_f32 v[2:3], v[18:19], v[112:113], v[2:3]
	v_mul_f32_e32 v18, 0x4b800000, v17
	v_cmp_gt_f32_e32 vcc, s3, v17
	global_load_dwordx4 v[118:121], v[50:51], off offset:-2048 nt
	v_pk_mul_f32 v[34:35], v[76:77], v[34:35] op_sel_hi:[0,1]
	v_cndmask_b32_e32 v17, v17, v18, vcc
	v_rsq_f32_e32 v17, v17
	v_pk_mul_f32 v[18:19], v[78:79], v[44:45] op_sel_hi:[0,1]
	v_pk_fma_f32 v[12:13], v[18:19], v[110:111], v[12:13]
	v_pk_mul_f32 v[44:45], v[78:79], v[92:93] op_sel_hi:[0,1]
	v_mul_f32_e32 v18, 0x45800000, v17
	v_cndmask_b32_e32 v80, v17, v18, vcc
	v_mul_f32_e32 v17, 0x4b800000, v16
	v_cmp_gt_f32_e32 vcc, s3, v16
	v_pk_fma_f32 v[14:15], v[44:45], v[112:113], v[14:15]
	v_pk_mul_f32 v[18:19], v[80:81], v[96:97] op_sel_hi:[0,1]
	v_cndmask_b32_e32 v16, v16, v17, vcc
	v_rsq_f32_e32 v44, v16
	v_pk_mul_f32 v[16:17], v[80:81], v[90:91] op_sel_hi:[0,1]
	global_load_dwordx4 v[90:93], v[36:37], off offset:-2048 nt
	v_pk_fma_f32 v[16:17], v[110:111], v[16:17], v[8:9]
	v_mul_f32_e32 v8, 0x45800000, v44
	v_cndmask_b32_e32 v82, v44, v8, vcc
	v_pk_fma_f32 v[18:19], v[112:113], v[18:19], v[10:11]
	v_pk_mul_f32 v[8:9], v[82:83], v[98:99] op_sel_hi:[0,1]
	v_pk_mul_f32 v[10:11], v[82:83], v[100:101] op_sel_hi:[0,1]
	global_store_dwordx4 v[48:49], v[0:3], off offset:-3072 sc0 sc1 nt
	global_store_dwordx4 v[50:51], v[12:15], off offset:-3072 sc0 sc1 nt
	global_store_dwordx4 v[36:37], v[16:19], off offset:-3072 sc0 sc1 nt
	v_pk_fma_f32 v[6:7], v[112:113], v[10:11], v[6:7]
	v_pk_fma_f32 v[4:5], v[110:111], v[8:9], v[4:5]
	global_load_dwordx4 v[96:99], v[70:71], off offset:-2048 nt
	v_mov_b32_e32 v8, v21
	global_store_dwordx4 v[70:71], v[4:7], off offset:-3072 sc0 sc1 nt
	global_load_dwordx4 v[100:103], v[64:65], off offset:1024
	global_load_dwordx4 v[110:113], v[48:49], off offset:-1024 nt
	v_mov_b32_e32 v9, v23
	v_mov_b32_e32 v21, v22
	v_pk_mul_f32 v[10:11], v[76:77], v[8:9] op_sel_hi:[0,1]
	v_pk_mul_f32 v[8:9], v[76:77], v[20:21] op_sel_hi:[0,1]
	v_mov_b32_e32 v20, v25
	v_mov_b32_e32 v21, v27
	v_mov_b32_e32 v25, v26
	v_pk_mul_f32 v[22:23], v[78:79], v[20:21] op_sel_hi:[0,1]
	v_pk_mul_f32 v[20:21], v[78:79], v[24:25] op_sel_hi:[0,1]
	v_mov_b32_e32 v24, v29
	v_mov_b32_e32 v25, v31
	v_mov_b32_e32 v29, v30
	v_pk_mul_f32 v[26:27], v[80:81], v[24:25] op_sel_hi:[0,1]
	v_pk_mul_f32 v[24:25], v[80:81], v[28:29] op_sel_hi:[0,1]
	v_mov_b32_e32 v28, v47
	v_mov_b32_e32 v29, v95
	v_mov_b32_e32 v47, v94
	v_pk_mul_f32 v[30:31], v[82:83], v[28:29] op_sel_hi:[0,1]
	v_pk_mul_f32 v[28:29], v[82:83], v[46:47] op_sel_hi:[0,1]
	v_pk_mul_f32 v[32:33], v[76:77], v[32:33] op_sel_hi:[0,1]
	v_pk_mul_f32 v[40:41], v[78:79], v[40:41] op_sel_hi:[0,1]
	v_pk_mul_f32 v[38:39], v[78:79], v[38:39] op_sel_hi:[0,1]
	v_mov_b32_e32 v56, v77
	v_mov_b32_e32 v58, v79
	v_mov_b32_e32 v52, v83
	v_pk_mul_f32 v[74:75], v[82:83], v[74:75] op_sel_hi:[0,1]
	v_pk_mul_f32 v[58:59], v[76:77], v[58:59] op_sel_hi:[0,1]
	v_pk_mul_f32 v[72:73], v[80:81], v[72:73] op_sel_hi:[0,1]
	v_pk_mul_f32 v[54:55], v[78:79], v[54:55] op_sel_hi:[0,1]
	v_pk_mul_f32 v[52:53], v[78:79], v[52:53] op_sel_hi:[0,1]
	s_andn2_b64 vcc, exec, s[20:21]
	s_waitcnt vmcnt(1)
	v_pk_fma_f32 v[8:9], v[8:9], v[100:101], v[114:115]
	v_pk_fma_f32 v[10:11], v[10:11], v[102:103], v[116:117]
	v_pk_fma_f32 v[20:21], v[20:21], v[100:101], v[118:119]
	v_pk_fma_f32 v[22:23], v[22:23], v[102:103], v[120:121]
	v_pk_fma_f32 v[24:25], v[100:101], v[24:25], v[90:91]
	v_pk_fma_f32 v[26:27], v[102:103], v[26:27], v[92:93]
	v_pk_fma_f32 v[28:29], v[100:101], v[28:29], v[96:97]
	v_pk_fma_f32 v[30:31], v[102:103], v[30:31], v[98:99]
	global_store_dwordx4 v[48:49], v[8:11], off offset:-2048 sc0 sc1 nt
	global_store_dwordx4 v[50:51], v[20:23], off offset:-2048 sc0 sc1 nt
	global_store_dwordx4 v[36:37], v[24:27], off offset:-2048 sc0 sc1 nt
	global_store_dwordx4 v[70:71], v[28:31], off offset:-2048 sc0 sc1 nt
	global_load_dwordx4 v[90:93], v[64:65], off offset:2048
	global_load_dwordx4 v[44:47], v[50:51], off offset:-1024 nt
	global_load_dwordx4 v[94:97], v[36:37], off offset:-1024 nt
	global_load_dwordx4 v[98:101], v[70:71], off offset:-1024 nt
	global_load_dwordx4 v[114:117], v[48:49], off nt
	global_load_dwordx4 v[118:121], v[70:71], off offset:-4096 nt
	s_waitcnt vmcnt(5)
	v_pk_fma_f32 v[32:33], v[32:33], v[90:91], v[110:111]
	v_pk_fma_f32 v[34:35], v[34:35], v[92:93], v[112:113]
	s_waitcnt vmcnt(4)
	v_pk_fma_f32 v[44:45], v[38:39], v[90:91], v[44:45]
	v_pk_fma_f32 v[46:47], v[40:41], v[92:93], v[46:47]
	v_pk_mul_f32 v[38:39], v[80:81], v[84:85] op_sel_hi:[0,1]
	v_pk_mul_f32 v[40:41], v[80:81], v[42:43] op_sel_hi:[0,1]
	global_load_dwordx4 v[110:113], v[50:51], off nt
	s_waitcnt vmcnt(4)
	v_pk_fma_f32 v[40:41], v[40:41], v[90:91], v[94:95]
	v_pk_fma_f32 v[42:43], v[38:39], v[92:93], v[96:97]
	global_store_dwordx4 v[48:49], v[32:35], off offset:-1024 sc0 sc1 nt
	global_store_dwordx4 v[50:51], v[44:47], off offset:-1024 sc0 sc1 nt
	global_store_dwordx4 v[36:37], v[40:43], off offset:-1024 sc0 sc1 nt
	v_pk_mul_f32 v[38:39], v[82:83], v[88:89] op_sel_hi:[0,1]
	v_pk_mul_f32 v[36:37], v[82:83], v[86:87] op_sel_hi:[0,1]
	s_waitcnt vmcnt(6)
	v_pk_fma_f32 v[36:37], v[90:91], v[36:37], v[98:99]
	v_pk_fma_f32 v[38:39], v[92:93], v[38:39], v[100:101]
	global_store_dwordx4 v[70:71], v[36:39], off offset:-1024 sc0 sc1 nt
	global_load_dwordx4 v[88:91], v[64:65], off offset:3072
	global_load_dwordx4 v[84:87], v[70:71], off nt
	v_pk_mul_f32 v[82:83], v[82:83], v[56:57] op_sel_hi:[0,1]
	v_pk_mul_f32 v[56:57], v[76:77], v[60:61] op_sel_hi:[0,1]
	v_pk_mul_f32 v[80:81], v[80:81], v[62:63] op_sel_hi:[0,1]
	s_waitcnt vmcnt(1)
	v_pk_fma_f32 v[60:61], v[58:59], v[88:89], v[114:115]
	v_pk_fma_f32 v[62:63], v[56:57], v[90:91], v[116:117]
	v_pk_fma_f32 v[56:57], v[52:53], v[88:89], v[110:111]
	v_pk_fma_f32 v[58:59], v[54:55], v[90:91], v[112:113]
	v_pk_fma_f32 v[52:53], v[80:81], v[88:89], v[118:119]
	v_pk_fma_f32 v[54:55], v[72:73], v[90:91], v[120:121]
	global_store_dwordx4 v[48:49], v[60:63], off sc0 sc1 nt
	global_store_dwordx4 v[50:51], v[56:59], off sc0 sc1 nt
	global_store_dwordx4 v[70:71], v[52:55], off offset:-4096 sc0 sc1 nt
	s_waitcnt vmcnt(3)
	v_pk_fma_f32 v[48:49], v[82:83], v[88:89], v[84:85]
	v_pk_fma_f32 v[50:51], v[74:75], v[90:91], v[86:87]
	global_store_dwordx4 v[70:71], v[48:51], off sc0 sc1 nt
	s_cbranch_vccnz .LBB0_190
; __device__ __forceinline__ void ew_post(const bf16* Y, const float* xin, float* xout, const float* gpost, const float* gnext, bf16* H, int gw, int ngw, int lane) {
;     ...
;                 s2[q] += (xv[q][j].x * xv[q][j].x + xv[q][j].y * xv[q][j].y) + (xv[q][j].z * xv[q][j].z + xv[q][j].w * xv[q][j].w); } }
;         if (gnext) {
;             float r2[EW_NR];
; #pragma unroll
;             for (int q = 0; q < EW_NR; ++q) r2[q] = rsqrtf(wave_sum(s2[q]) * (1.f / DM) + RMS_EPS);
	v_pk_mul_f32 v[72:73], v[6:7], v[6:7]
	v_pk_mul_f32 v[74:75], v[4:5], v[4:5]
	v_mul_f32_e32 v80, v49, v49
	v_pk_mov_b32 v[76:77], v[74:75], v[72:73] op_sel:[1,0]
	v_mov_b32_e32 v75, v73
	v_pk_add_f32 v[72:73], v[76:77], v[74:75]
	v_pk_mul_f32 v[74:75], v[30:31], v[30:31]
	v_pk_mul_f32 v[76:77], v[28:29], v[28:29]
	v_mul_f32_e32 v81, v50, v50
	v_pk_mov_b32 v[78:79], v[76:77], v[74:75] op_sel:[1,0]
	v_mov_b32_e32 v77, v75
	v_pk_add_f32 v[74:75], v[78:79], v[76:77]
	v_mul_f32_e32 v76, v37, v37
	v_mul_f32_e32 v78, v48, v48
	v_pk_fma_f32 v[76:77], v[36:37], v[36:37], v[76:77] op_sel_hi:[1,1,0]
	v_mul_f32_e32 v82, v51, v51
	v_mov_b32_e32 v77, v78
	v_mul_f32_e32 v78, v39, v39
	v_pk_fma_f32 v[78:79], v[38:39], v[38:39], v[78:79] op_sel_hi:[1,1,0]
	v_pk_add_f32 v[72:73], v[72:73], v[72:73] op_sel:[0,1] op_sel_hi:[1,0]
	v_pk_add_f32 v[74:75], v[74:75], v[74:75] op_sel:[0,1] op_sel_hi:[1,0]
	v_mov_b32_e32 v79, v80
	v_mov_b32_e32 v73, v81
	v_mov_b32_e32 v75, v82
	v_pk_add_f32 v[76:77], v[76:77], v[78:79]
	v_pk_add_f32 v[72:73], v[72:73], v[74:75]
	v_pk_mul_f32 v[74:75], v[16:17], v[16:17]
	v_pk_add_f32 v[76:77], v[76:77], v[72:73]
	v_pk_mul_f32 v[72:73], v[18:19], v[18:19]
	v_mul_f32_e32 v88, v53, v53
	v_pk_mov_b32 v[78:79], v[74:75], v[72:73] op_sel:[1,0]
	v_mov_b32_e32 v75, v73
	v_pk_add_f32 v[72:73], v[78:79], v[74:75]
	v_pk_mul_f32 v[74:75], v[26:27], v[26:27]
	v_pk_mul_f32 v[78:79], v[24:25], v[24:25]
	v_mul_f32_e32 v89, v54, v54
	v_pk_mov_b32 v[80:81], v[78:79], v[74:75] op_sel:[1,0]
	v_mov_b32_e32 v79, v75
	v_pk_add_f32 v[74:75], v[80:81], v[78:79]
	v_mul_f32_e32 v80, v52, v52
	v_pk_add_f32 v[78:79], v[72:73], v[72:73] op_sel:[0,1] op_sel_hi:[1,0]
	v_pk_mul_f32 v[72:73], v[14:15], v[14:15]
	v_mov_b32_e32 v79, v80
	v_pk_mul_f32 v[80:81], v[12:13], v[12:13]
	v_mul_f32_e32 v90, v55, v55
	v_pk_mov_b32 v[82:83], v[80:81], v[72:73] op_sel:[1,0]
	v_mov_b32_e32 v81, v73
	v_pk_add_f32 v[72:73], v[82:83], v[80:81]
	v_pk_mul_f32 v[80:81], v[22:23], v[22:23]
	v_pk_mul_f32 v[82:83], v[20:21], v[20:21]
	v_pk_add_f32 v[72:73], v[72:73], v[72:73] op_sel:[0,1] op_sel_hi:[1,0]
	v_pk_mov_b32 v[84:85], v[82:83], v[80:81] op_sel:[1,0]
	v_mov_b32_e32 v83, v81
	v_pk_add_f32 v[80:81], v[84:85], v[82:83]
	v_mul_f32_e32 v82, v56, v56
	v_mul_f32_e32 v83, v57, v57
	v_pk_add_f32 v[80:81], v[80:81], v[80:81] op_sel:[0,1] op_sel_hi:[1,0]
	v_mov_b32_e32 v73, v82
	v_mov_b32_e32 v81, v83
	v_pk_add_f32 v[72:73], v[72:73], v[80:81]
	v_mul_f32_e32 v80, v45, v45
	v_mul_f32_e32 v82, v47, v47
	v_mul_f32_e32 v84, v58, v58
	v_mul_f32_e32 v85, v59, v59
	v_pk_fma_f32 v[80:81], v[44:45], v[44:45], v[80:81] op_sel_hi:[1,1,0]
	v_pk_fma_f32 v[82:83], v[46:47], v[46:47], v[82:83] op_sel_hi:[1,1,0]
	v_mov_b32_e32 v81, v84
	v_mov_b32_e32 v83, v85
	v_pk_add_f32 v[80:81], v[80:81], v[82:83]
	v_pk_mul_f32 v[82:83], v[0:1], v[0:1]
	v_pk_add_f32 v[72:73], v[72:73], v[80:81]
	v_pk_mul_f32 v[80:81], v[2:3], v[2:3]
	s_nop 0
	v_pk_mov_b32 v[84:85], v[82:83], v[80:81] op_sel:[1,0]
	v_mov_b32_e32 v83, v81
	v_pk_add_f32 v[80:81], v[84:85], v[82:83]
	v_pk_mul_f32 v[82:83], v[10:11], v[10:11]
	v_pk_mul_f32 v[84:85], v[8:9], v[8:9]
	v_pk_add_f32 v[80:81], v[80:81], v[80:81] op_sel:[0,1] op_sel_hi:[1,0]
	v_pk_mov_b32 v[86:87], v[84:85], v[82:83] op_sel:[1,0]
	v_mov_b32_e32 v85, v83
	v_pk_add_f32 v[82:83], v[86:87], v[84:85]
	v_mul_f32_e32 v84, v60, v60
	v_mul_f32_e32 v85, v61, v61
	v_pk_add_f32 v[82:83], v[82:83], v[82:83] op_sel:[0,1] op_sel_hi:[1,0]
	v_mov_b32_e32 v81, v84
	v_mov_b32_e32 v83, v85
	v_pk_add_f32 v[80:81], v[80:81], v[82:83]
	v_mul_f32_e32 v82, v33, v33
	v_mul_f32_e32 v84, v35, v35
	v_mul_f32_e32 v86, v62, v62
	v_mul_f32_e32 v87, v63, v63
	v_pk_fma_f32 v[82:83], v[32:33], v[32:33], v[82:83] op_sel_hi:[1,1,0]
	v_pk_fma_f32 v[84:85], v[34:35], v[34:35], v[84:85] op_sel_hi:[1,1,0]
	v_mov_b32_e32 v83, v86
	v_mov_b32_e32 v85, v87
	v_pk_add_f32 v[82:83], v[82:83], v[84:85]
	v_pk_add_f32 v[84:85], v[74:75], v[74:75] op_sel:[0,1] op_sel_hi:[1,0]
	v_pk_add_f32 v[80:81], v[80:81], v[82:83]
	v_mov_b32_e32 v82, v72
	v_mov_b32_e32 v83, v80
	v_mov_b32_e32 v80, v73
	global_load_dwordx4 v[72:75], v[66:67], off
	v_pk_add_f32 v[80:81], v[82:83], v[80:81]
	v_mov_b32_e32 v85, v88
	ds_bpermute_b32 v83, v104, v81
	ds_bpermute_b32 v82, v104, v80
	v_pk_add_f32 v[78:79], v[78:79], v[84:85]
	v_mul_f32_e32 v84, v41, v41
	v_mul_f32_e32 v86, v43, v43
	v_pk_fma_f32 v[84:85], v[40:41], v[40:41], v[84:85] op_sel_hi:[1,1,0]
	v_pk_fma_f32 v[86:87], v[42:43], v[42:43], v[86:87] op_sel_hi:[1,1,0]
	v_mov_b32_e32 v85, v89
	v_mov_b32_e32 v87, v90
	v_pk_add_f32 v[84:85], v[84:85], v[86:87]
	s_waitcnt lgkmcnt(0)
	v_pk_add_f32 v[80:81], v[80:81], v[82:83]
	v_pk_add_f32 v[78:79], v[78:79], v[84:85]
	v_mov_b32_e32 v84, v76
	v_mov_b32_e32 v85, v78
	v_mov_b32_e32 v78, v77
	ds_bpermute_b32 v83, v105, v81
	ds_bpermute_b32 v82, v105, v80
	v_pk_add_f32 v[76:77], v[84:85], v[78:79]
	ds_bpermute_b32 v79, v104, v77
	ds_bpermute_b32 v78, v104, v76
	s_waitcnt lgkmcnt(2)
	v_pk_add_f32 v[80:81], v[80:81], v[82:83]
	ds_bpermute_b32 v83, v106, v81
	ds_bpermute_b32 v82, v106, v80
	s_waitcnt lgkmcnt(2)
	v_pk_add_f32 v[76:77], v[76:77], v[78:79]
	ds_bpermute_b32 v79, v105, v77
	ds_bpermute_b32 v78, v105, v76
	s_waitcnt lgkmcnt(2)
	v_pk_add_f32 v[80:81], v[80:81], v[82:83]
	ds_bpermute_b32 v83, v107, v81
	ds_bpermute_b32 v82, v107, v80
	s_waitcnt lgkmcnt(2)
	v_pk_add_f32 v[76:77], v[76:77], v[78:79]
	ds_bpermute_b32 v79, v106, v77
	ds_bpermute_b32 v78, v106, v76
	s_waitcnt lgkmcnt(2)
	v_pk_add_f32 v[80:81], v[80:81], v[82:83]
	ds_bpermute_b32 v83, v108, v81
	ds_bpermute_b32 v82, v108, v80
	s_waitcnt lgkmcnt(2)
; __device__ __forceinline__ unsigned pk2(float lo, float hi) { f32v2 v = {lo, hi}; bf16v2 r = __builtin_convertvector(v, bf16v2); return __builtin_bit_cast(unsigned, r); }
; __device__ __forceinline__ void ew_post(const bf16* Y, const float* xin, float* xout, const float* gpost, const float* gnext, bf16* H, int gw, int ngw, int lane) {
;     ...
;         if (gnext) {
;             float r2[EW_NR];
; #pragma unroll
;             for (int q = 0; q < EW_NR; ++q) r2[q] = rsqrtf(wave_sum(s2[q]) * (1.f / DM) + RMS_EPS);
; #pragma unroll
;             for (int j = 0; j < 4; ++j) { const f32x4 g = *((const f32x4*)gnext + lane + 64 * j);
; #pragma unroll
;                 for (int q = 0; q < EW_NR; ++q) { v2u w; w.x = pk2(xv[q][j].x * r2[q] * g.x, xv[q][j].y * r2[q] * g.y); w.y = pk2(xv[q][j].z * r2[q] * g.z, xv[q][j].w * r2[q] * g.w);
;                     *((v2u*)(H + (size_t)(m0 + q) * DM) + lane + 64 * j) = w; } }
	v_pk_add_f32 v[76:77], v[76:77], v[78:79]
	ds_bpermute_b32 v79, v107, v77
	ds_bpermute_b32 v78, v107, v76
	s_waitcnt lgkmcnt(2)
	v_pk_add_f32 v[80:81], v[80:81], v[82:83]
	ds_bpermute_b32 v83, v109, v81
	ds_bpermute_b32 v82, v109, v80
	s_waitcnt lgkmcnt(2)
	v_pk_add_f32 v[76:77], v[76:77], v[78:79]
	ds_bpermute_b32 v79, v108, v77
	ds_bpermute_b32 v78, v108, v76
	s_waitcnt lgkmcnt(2)
	v_pk_add_f32 v[80:81], v[80:81], v[82:83]
	v_mov_b64_e32 v[82:83], s[24:25]
	v_pk_fma_f32 v[80:81], v[80:81], s[44:45], v[82:83] op_sel_hi:[1,0,0]
	s_waitcnt lgkmcnt(0)
	v_pk_add_f32 v[76:77], v[76:77], v[78:79]
	v_mul_f32_e32 v84, 0x4b800000, v81
	v_cmp_gt_f32_e32 vcc, s3, v81
	ds_bpermute_b32 v79, v109, v77
	ds_bpermute_b32 v78, v109, v76
	v_cndmask_b32_e32 v81, v81, v84, vcc
	v_rsq_f32_e32 v81, v81
	v_mul_f32_e32 v84, 0x4b800000, v80
	v_cmp_gt_f32_e64 s[4:5], s3, v80
	s_waitcnt lgkmcnt(0)
	v_pk_add_f32 v[76:77], v[76:77], v[78:79]
	v_cndmask_b32_e64 v80, v80, v84, s[4:5]
	v_rsq_f32_e32 v84, v80
	v_mul_f32_e32 v80, 0x45800000, v81
	v_pk_fma_f32 v[76:77], v[76:77], s[44:45], v[82:83] op_sel_hi:[1,0,0]
	v_cndmask_b32_e32 v80, v81, v80, vcc
	v_mul_f32_e32 v78, 0x4b800000, v77
	v_cmp_gt_f32_e32 vcc, s3, v77
	v_cmp_gt_f32_e64 s[6:7], s3, v76
	v_mul_f32_e32 v81, 0x45800000, v84
	v_cndmask_b32_e32 v77, v77, v78, vcc
	v_rsq_f32_e32 v77, v77
	v_mul_f32_e32 v78, 0x4b800000, v76
	v_cndmask_b32_e64 v76, v76, v78, s[6:7]
	v_rsq_f32_e32 v79, v76
	v_mul_f32_e32 v78, 0x45800000, v77
	v_pk_mul_f32 v[0:1], v[0:1], v[80:81] op_sel_hi:[1,0]
	v_pk_mul_f32 v[2:3], v[2:3], v[80:81] op_sel_hi:[1,0]
	v_cndmask_b32_e64 v76, v84, v81, s[4:5]
	v_cndmask_b32_e32 v78, v77, v78, vcc
	s_waitcnt vmcnt(0)
	v_pk_mul_f32 v[0:1], v[0:1], v[72:73]
	v_pk_mul_f32 v[2:3], v[2:3], v[74:75]
	v_add_co_u32_e32 v84, vcc, s22, v68
	v_mul_f32_e32 v77, 0x45800000, v79
	v_cvt_pk_bf16_f32 v0, v0, v1
	v_cvt_pk_bf16_f32 v1, v2, v3
	v_addc_co_u32_e32 v85, vcc, -1, v69, vcc
	global_store_dwordx2 v[84:85], v[0:1], off offset:-3584
	v_pk_mul_f32 v[0:1], v[12:13], v[76:77] op_sel_hi:[1,0]
	v_pk_mul_f32 v[2:3], v[14:15], v[76:77] op_sel_hi:[1,0]
	v_pk_mul_f32 v[0:1], v[0:1], v[72:73]
	v_pk_mul_f32 v[2:3], v[2:3], v[74:75]
	v_cvt_pk_bf16_f32 v0, v0, v1
	v_cvt_pk_bf16_f32 v1, v2, v3
	global_store_dwordx2 v[84:85], v[0:1], off offset:-1536
	v_pk_mul_f32 v[0:1], v[16:17], v[78:79] op_sel_hi:[1,0]
	v_pk_mul_f32 v[2:3], v[18:19], v[78:79] op_sel_hi:[1,0]
	v_pk_mul_f32 v[0:1], v[72:73], v[0:1]
	v_pk_mul_f32 v[2:3], v[74:75], v[2:3]
	v_add_co_u32_e32 v12, vcc, s23, v68
	v_cndmask_b32_e64 v82, v79, v77, s[6:7]
	v_cvt_pk_bf16_f32 v0, v0, v1
	v_cvt_pk_bf16_f32 v1, v2, v3
	v_addc_co_u32_e32 v13, vcc, -1, v69, vcc
	global_store_dwordx2 v[12:13], v[0:1], off offset:-3584
	v_pk_mul_f32 v[0:1], v[4:5], v[82:83] op_sel_hi:[1,0]
	v_pk_mul_f32 v[2:3], v[6:7], v[82:83] op_sel_hi:[1,0]
	v_pk_mul_f32 v[0:1], v[72:73], v[0:1]
	v_pk_mul_f32 v[2:3], v[74:75], v[2:3]
	v_cvt_pk_bf16_f32 v0, v0, v1
	v_cvt_pk_bf16_f32 v1, v2, v3
	global_store_dwordx2 v[12:13], v[0:1], off offset:-1536
	global_load_dwordx4 v[0:3], v[66:67], off offset:1024
	v_pk_mul_f32 v[4:5], v[8:9], v[80:81] op_sel_hi:[1,0]
	v_pk_mul_f32 v[6:7], v[10:11], v[80:81] op_sel_hi:[1,0]
	v_pk_mul_f32 v[8:9], v[56:57], v[76:77] op_sel_hi:[1,0]
	v_pk_mul_f32 v[10:11], v[58:59], v[76:77] op_sel_hi:[1,0]
	v_pk_mul_f32 v[14:15], v[52:53], v[78:79] op_sel_hi:[1,0]
	v_pk_mul_f32 v[16:17], v[54:55], v[78:79] op_sel_hi:[1,0]
	v_pk_mul_f32 v[18:19], v[48:49], v[82:83] op_sel_hi:[1,0]
	s_waitcnt vmcnt(0)
	v_pk_mul_f32 v[4:5], v[4:5], v[0:1]
	v_pk_mul_f32 v[6:7], v[6:7], v[2:3]
	v_cvt_pk_bf16_f32 v4, v4, v5
	v_cvt_pk_bf16_f32 v5, v6, v7
	global_store_dwordx2 v[84:85], v[4:5], off offset:-3072
	v_pk_mul_f32 v[4:5], v[20:21], v[76:77] op_sel_hi:[1,0]
	v_pk_mul_f32 v[6:7], v[22:23], v[76:77] op_sel_hi:[1,0]
	v_pk_mul_f32 v[4:5], v[4:5], v[0:1]
	v_pk_mul_f32 v[6:7], v[6:7], v[2:3]
	v_cvt_pk_bf16_f32 v4, v4, v5
	v_cvt_pk_bf16_f32 v5, v6, v7
	global_store_dwordx2 v[84:85], v[4:5], off offset:-1024
	v_pk_mul_f32 v[4:5], v[24:25], v[78:79] op_sel_hi:[1,0]
	v_pk_mul_f32 v[6:7], v[26:27], v[78:79] op_sel_hi:[1,0]
	v_pk_mul_f32 v[4:5], v[4:5], v[0:1]
	v_pk_mul_f32 v[6:7], v[6:7], v[2:3]
	v_cvt_pk_bf16_f32 v4, v4, v5
	v_cvt_pk_bf16_f32 v5, v6, v7
	global_store_dwordx2 v[12:13], v[4:5], off offset:-3072
	v_pk_mul_f32 v[4:5], v[28:29], v[82:83] op_sel_hi:[1,0]
	v_pk_mul_f32 v[6:7], v[34:35], v[80:81] op_sel_hi:[1,0]
	v_pk_mul_f32 v[0:1], v[0:1], v[4:5]
	v_pk_mul_f32 v[4:5], v[30:31], v[82:83] op_sel_hi:[1,0]
	v_cvt_pk_bf16_f32 v0, v0, v1
	v_pk_mul_f32 v[2:3], v[2:3], v[4:5]
	v_pk_mul_f32 v[4:5], v[32:33], v[80:81] op_sel_hi:[1,0]
	v_cvt_pk_bf16_f32 v1, v2, v3
	global_store_dwordx2 v[12:13], v[0:1], off offset:-1024
	global_load_dwordx4 v[0:3], v[66:67], off offset:2048
	v_pk_mul_f32 v[20:21], v[50:51], v[82:83] op_sel_hi:[1,0]
	s_waitcnt vmcnt(0)
	v_pk_mul_f32 v[4:5], v[4:5], v[0:1]
	v_pk_mul_f32 v[6:7], v[6:7], v[2:3]
	v_cvt_pk_bf16_f32 v4, v4, v5
	v_cvt_pk_bf16_f32 v5, v6, v7
	global_store_dwordx2 v[84:85], v[4:5], off offset:-2560
	v_pk_mul_f32 v[4:5], v[44:45], v[76:77] op_sel_hi:[1,0]
	v_pk_mul_f32 v[6:7], v[46:47], v[76:77] op_sel_hi:[1,0]
	v_pk_mul_f32 v[4:5], v[4:5], v[0:1]
	v_pk_mul_f32 v[6:7], v[6:7], v[2:3]
	v_cvt_pk_bf16_f32 v4, v4, v5
	v_cvt_pk_bf16_f32 v5, v6, v7
	global_store_dwordx2 v[84:85], v[4:5], off offset:-512
	v_pk_mul_f32 v[4:5], v[40:41], v[78:79] op_sel_hi:[1,0]
	v_pk_mul_f32 v[6:7], v[42:43], v[78:79] op_sel_hi:[1,0]
	v_pk_mul_f32 v[4:5], v[4:5], v[0:1]
	v_pk_mul_f32 v[6:7], v[6:7], v[2:3]
	v_cvt_pk_bf16_f32 v4, v4, v5
	v_cvt_pk_bf16_f32 v5, v6, v7
	global_store_dwordx2 v[12:13], v[4:5], off offset:-2560
	v_pk_mul_f32 v[4:5], v[36:37], v[82:83] op_sel_hi:[1,0]
	v_pk_mul_f32 v[6:7], v[62:63], v[80:81] op_sel_hi:[1,0]
	v_pk_mul_f32 v[0:1], v[4:5], v[0:1]
	v_pk_mul_f32 v[4:5], v[38:39], v[82:83] op_sel_hi:[1,0]
	v_cvt_pk_bf16_f32 v0, v0, v1
	v_pk_mul_f32 v[2:3], v[4:5], v[2:3]
	v_pk_mul_f32 v[4:5], v[60:61], v[80:81] op_sel_hi:[1,0]
	v_cvt_pk_bf16_f32 v1, v2, v3
	global_store_dwordx2 v[12:13], v[0:1], off offset:-512
	global_load_dwordx4 v[0:3], v[66:67], off offset:3072
	s_waitcnt vmcnt(0)
	v_pk_mul_f32 v[4:5], v[4:5], v[0:1]
	v_pk_mul_f32 v[6:7], v[6:7], v[2:3]
	v_pk_mul_f32 v[8:9], v[8:9], v[0:1]
	v_pk_mul_f32 v[10:11], v[10:11], v[2:3]
	v_pk_mul_f32 v[14:15], v[14:15], v[0:1]
	v_pk_mul_f32 v[16:17], v[16:17], v[2:3]
	v_pk_mul_f32 v[0:1], v[18:19], v[0:1]
	v_pk_mul_f32 v[2:3], v[20:21], v[2:3]
	v_cvt_pk_bf16_f32 v4, v4, v5
	v_cvt_pk_bf16_f32 v5, v6, v7
	v_cvt_pk_bf16_f32 v6, v8, v9
	v_cvt_pk_bf16_f32 v7, v10, v11
	v_cvt_pk_bf16_f32 v8, v14, v15
	v_cvt_pk_bf16_f32 v9, v16, v17
	v_cvt_pk_bf16_f32 v0, v0, v1
	v_cvt_pk_bf16_f32 v1, v2, v3
	global_store_dwordx2 v[84:85], v[4:5], off offset:-2048
	global_store_dwordx2 v[12:13], v[6:7], off offset:-4096
	global_store_dwordx2 v[12:13], v[8:9], off offset:-2048
	global_store_dwordx2 v[12:13], v[0:1], off
	s_branch .LBB0_190

; __device__ __forceinline__ void ew_post(const bf16* Y, const float* xin, float* xout, const float* gpost, const float* gnext, bf16* H, int gw, int ngw, int lane) {
;     for (int m0 = EW_NR * gw; m0 < NTOK; m0 += EW_NR * ngw) {
;         f32x4 y[EW_NR][4], xv[EW_NR][4]; float s[EW_NR];
; #pragma unroll
;         for (int q = 0; q < EW_NR; ++q) { const v2u* yr = (const v2u*)(Y + (size_t)(m0 + q) * DM) + lane; const f32x4* xr = (const f32x4*)(xin + (size_t)(m0 + q) * DM) + lane;
; #pragma unroll
;             for (int j = 0; j < 4; ++j) { const v2u w = __builtin_nontemporal_load(yr + 64 * j); y[q][j] = (f32x4){bf_lo(w.x), bf_hi(w.x), bf_lo(w.y), bf_hi(w.y)}; xv[q][j] = __builtin_nontemporal_load(xr + 64 * j); } }
; #pragma unroll
;         for (int q = 0; q < EW_NR; ++q) { s[q] = 0.f;
; #pragma unroll
;             for (int j = 0; j < 4; ++j) s[q] += (y[q][j].x * y[q][j].x + y[q][j].y * y[q][j].y) + (y[q][j].z * y[q][j].z + y[q][j].w * y[q][j].w); }
.LBB0_209:
	v_add_co_u32_e32 v8, vcc, 0xfffff000, v72
	global_load_dwordx2 v[38:39], v[72:73], off offset:-4096 nt
	global_load_dwordx2 v[40:41], v[72:73], off offset:-2048 nt
	v_addc_co_u32_e32 v9, vcc, -1, v73, vcc
	global_load_dwordx2 v[42:43], v[72:73], off nt
	global_load_dwordx2 v[48:49], v[8:9], off offset:-2048 nt
	global_load_dwordx2 v[50:51], v[8:9], off offset:-3584 nt
	global_load_dwordx2 v[52:53], v[8:9], off offset:-3072 nt
	global_load_dwordx2 v[54:55], v[8:9], off offset:-2560 nt
	v_lshl_add_u64 v[10:11], s[12:13], 0, v[178:179]
	global_load_dwordx2 v[96:97], v[72:73], off offset:-3584 nt
	global_load_dwordx2 v[106:107], v[72:73], off offset:-3072 nt
	global_load_dwordx2 v[98:99], v[72:73], off offset:-2560 nt
	global_load_dwordx2 v[108:109], v[72:73], off offset:-1536 nt
	global_load_dwordx2 v[66:67], v[72:73], off offset:-1024 nt
	global_load_dwordx2 v[46:47], v[72:73], off offset:-512 nt
	global_load_dwordx2 v[90:91], v[8:9], off offset:-1536 nt
	global_load_dwordx4 v[20:23], v[10:11], off nt
	global_load_dwordx4 v[12:15], v[10:11], off offset:1024 nt
	global_load_dwordx4 v[4:7], v[10:11], off offset:2048 nt
	global_load_dwordx4 v[0:3], v[10:11], off offset:3072 nt
	global_load_dwordx2 v[92:93], v[8:9], off offset:-1024 nt
	global_load_dwordx2 v[104:105], v[8:9], off offset:-512 nt
	v_add_co_u32_e64 v36, s[4:5], s24, v10
	v_add_co_u32_e32 v44, vcc, s22, v10
	s_nop 0
	v_addc_co_u32_e64 v37, s[4:5], 0, v11, s[4:5]
	s_mov_b64 s[4:5], vcc
	v_add_co_u32_e32 v64, vcc, s23, v10
	v_addc_co_u32_e64 v45, s[4:5], 0, v11, s[4:5]
	global_load_dwordx4 v[28:31], v[36:37], off nt
	v_addc_co_u32_e32 v65, vcc, 0, v11, vcc
	global_load_dwordx4 v[16:19], v[44:45], off offset:1024 nt
	global_load_dwordx4 v[8:11], v[44:45], off offset:2048 nt
	global_load_dwordx4 v[24:27], v[64:65], off offset:-4096 nt
	global_load_dwordx4 v[32:35], v[64:65], off nt
	global_load_dwordx4 v[136:139], v[68:69], off
	v_mov_b64_e32 v[148:149], s[26:27]
	s_waitcnt vmcnt(0)
	v_and_b32_e32 v121, 0xffff0000, v97
	v_and_b32_e32 v119, 0xffff0000, v96
	v_lshlrev_b32_e32 v120, 16, v97
	v_lshlrev_b32_e32 v118, 16, v96
	v_lshlrev_b32_e32 v59, 16, v38
	v_lshlrev_b32_e32 v77, 16, v40
	v_lshlrev_b32_e32 v87, 16, v48
	v_and_b32_e32 v101, 0xffff0000, v50
	v_and_b32_e32 v103, 0xffff0000, v51
	v_and_b32_e32 v75, 0xffff0000, v40
	v_lshlrev_b32_e32 v78, 16, v41
	v_and_b32_e32 v79, 0xffff0000, v41
	v_lshlrev_b32_e32 v83, 16, v42
	v_and_b32_e32 v81, 0xffff0000, v42
	v_lshlrev_b32_e32 v84, 16, v43
	v_and_b32_e32 v85, 0xffff0000, v43
	v_and_b32_e32 v63, 0xffff0000, v48
	v_lshlrev_b32_e32 v88, 16, v49
	v_and_b32_e32 v89, 0xffff0000, v49
	v_lshlrev_b32_e32 v100, 16, v50
	v_lshlrev_b32_e32 v102, 16, v51
	v_and_b32_e32 v41, 0xffff0000, v53
	v_and_b32_e32 v40, 0xffff0000, v52
	v_lshlrev_b32_e32 v48, 16, v54
	v_and_b32_e32 v49, 0xffff0000, v54
	v_mul_f32_e32 v42, v103, v103
	v_mul_f32_e32 v54, v101, v101
	v_mov_b32_e32 v43, v87
	v_and_b32_e32 v57, 0xffff0000, v38
	v_lshlrev_b32_e32 v60, 16, v39
	v_and_b32_e32 v61, 0xffff0000, v39
	v_lshlrev_b32_e32 v39, 16, v53
	v_lshlrev_b32_e32 v38, 16, v52
	v_lshlrev_b32_e32 v50, 16, v55
	v_and_b32_e32 v51, 0xffff0000, v55
	v_pk_mul_f32 v[52:53], v[40:41], v[40:41]
	v_pk_fma_f32 v[94:95], v[102:103], v[102:103], v[42:43] op_sel_hi:[1,1,0]
	v_pk_fma_f32 v[54:55], v[100:101], v[100:101], v[54:55] op_sel_hi:[1,1,0]
	v_pk_fma_f32 v[52:53], v[38:39], v[38:39], v[52:53]
	v_mov_b32_e32 v86, v54
	v_mov_b32_e32 v42, v94
	v_mul_f32_e32 v56, v63, v63
	v_pk_add_f32 v[54:55], v[54:55], v[94:95]
	v_pk_add_f32 v[52:53], v[52:53], v[52:53] op_sel:[0,1] op_sel_hi:[1,0]
	v_pk_mul_f32 v[42:43], v[86:87], v[42:43]
	v_mov_b32_e32 v53, v56
	v_mov_b32_e32 v55, v43
	v_pk_add_f32 v[42:43], v[54:55], v[52:53]
	v_mul_f32_e32 v52, v49, v49
	v_mul_f32_e32 v54, v51, v51
	v_mul_f32_e32 v58, v88, v88
	v_mul_f32_e32 v62, v89, v89
	v_pk_fma_f32 v[52:53], v[48:49], v[48:49], v[52:53] op_sel_hi:[1,1,0]
	v_pk_fma_f32 v[54:55], v[50:51], v[50:51], v[54:55] op_sel_hi:[1,1,0]
	v_mov_b32_e32 v53, v58
	v_mov_b32_e32 v55, v62
	v_pk_add_f32 v[52:53], v[52:53], v[54:55]
	s_waitcnt vmcnt(12)
	v_and_b32_e32 v113, 0xffff0000, v91
	v_pk_add_f32 v[52:53], v[42:43], v[52:53]
	v_and_b32_e32 v111, 0xffff0000, v90
	v_lshlrev_b32_e32 v112, 16, v91
	v_mul_f32_e32 v42, v113, v113
	s_waitcnt vmcnt(7)
	v_and_b32_e32 v95, 0xffff0000, v93
	v_and_b32_e32 v94, 0xffff0000, v92
	v_lshlrev_b32_e32 v110, 16, v90
	v_pk_fma_f32 v[54:55], v[112:113], v[112:113], v[42:43] op_sel_hi:[1,1,0]
	v_lshlrev_b32_e32 v43, 16, v93
	v_lshlrev_b32_e32 v42, 16, v92
	v_pk_mul_f32 v[90:91], v[94:95], v[94:95]
	v_mul_f32_e32 v56, v111, v111
	v_pk_fma_f32 v[114:115], v[42:43], v[42:43], v[90:91]
	s_waitcnt vmcnt(6)
	v_lshlrev_b32_e32 v90, 16, v104
	v_and_b32_e32 v91, 0xffff0000, v104
	v_lshlrev_b32_e32 v92, 16, v105
	v_and_b32_e32 v93, 0xffff0000, v105
	v_pk_fma_f32 v[104:105], v[110:111], v[110:111], v[56:57] op_sel_hi:[1,1,0]
	v_mov_b32_e32 v116, v54
	v_mov_b32_e32 v58, v104
	v_mov_b32_e32 v117, v59
	v_pk_add_f32 v[54:55], v[104:105], v[54:55]
	v_pk_mul_f32 v[104:105], v[58:59], v[116:117]
	v_mul_f32_e32 v62, v57, v57
	v_mov_b32_e32 v55, v105
	v_pk_add_f32 v[104:105], v[114:115], v[114:115] op_sel:[0,1] op_sel_hi:[1,0]
	v_mul_f32_e32 v56, v91, v91
	v_mov_b32_e32 v105, v62
	v_pk_add_f32 v[54:55], v[54:55], v[104:105]
	v_pk_fma_f32 v[104:105], v[90:91], v[90:91], v[56:57] op_sel_hi:[1,1,0]
	v_mul_f32_e32 v56, v93, v93
	v_mul_f32_e32 v74, v60, v60
	v_mul_f32_e32 v76, v61, v61
	v_pk_fma_f32 v[114:115], v[92:93], v[92:93], v[56:57] op_sel_hi:[1,1,0]
	v_mov_b32_e32 v105, v74
	v_mov_b32_e32 v115, v76
	v_pk_add_f32 v[104:105], v[104:105], v[114:115]
	v_mov_b32_e32 v143, v52
	v_pk_add_f32 v[54:55], v[54:55], v[104:105]
	v_mul_f32_e32 v56, v121, v121
	v_mov_b32_e32 v142, v54
	v_mov_b32_e32 v52, v55
	v_pk_add_f32 v[52:53], v[142:143], v[52:53]
	ds_bpermute_b32 v55, v130, v53
	ds_bpermute_b32 v54, v130, v52
	v_pk_fma_f32 v[114:115], v[120:121], v[120:121], v[56:57] op_sel_hi:[1,1,0]
	v_lshlrev_b32_e32 v105, 16, v107
	v_lshlrev_b32_e32 v104, 16, v106
	v_and_b32_e32 v107, 0xffff0000, v107
	v_and_b32_e32 v106, 0xffff0000, v106
	v_mul_f32_e32 v56, v119, v119
	v_pk_mul_f32 v[96:97], v[106:107], v[106:107]
	v_pk_fma_f32 v[122:123], v[118:119], v[118:119], v[56:57] op_sel_hi:[1,1,0]
	s_waitcnt lgkmcnt(0)
; __device__ __forceinline__ void ew_post(const bf16* Y, const float* xin, float* xout, const float* gpost, const float* gnext, bf16* H, int gw, int ngw, int lane) {
;     ...
;         for (int q = 0; q < EW_NR; ++q) { s[q] = 0.f;
; #pragma unroll
;             for (int j = 0; j < 4; ++j) s[q] += (y[q][j].x * y[q][j].x + y[q][j].y * y[q][j].y) + (y[q][j].z * y[q][j].z + y[q][j].w * y[q][j].w); }
;         float rstd[EW_NR], s2[EW_NR];
; #pragma unroll
;         for (int q = 0; q < EW_NR; ++q) { rstd[q] = rsqrtf(wave_sum(s[q]) * (1.f / DM) + RMS_EPS); s2[q] = 0.f; }
; #pragma unroll
;         for (int j = 0; j < 4; ++j) { const f32x4 g = *((const f32x4*)gpost + lane + 64 * j);
; #pragma unroll
;             for (int q = 0; q < EW_NR; ++q) { xv[q][j] = xv[q][j] + y[q][j] * rstd[q] * g; __builtin_nontemporal_store(xv[q][j], (f32x4*)(xout + (size_t)(m0 + q) * DM) + lane + 64 * j);
;                 s2[q] += (xv[q][j].x * xv[q][j].x + xv[q][j].y * xv[q][j].y) + (xv[q][j].z * xv[q][j].z + xv[q][j].w * xv[q][j].w); } }
	v_pk_add_f32 v[52:53], v[52:53], v[54:55]
	v_pk_fma_f32 v[116:117], v[104:105], v[104:105], v[96:97]
	v_mov_b32_e32 v76, v122
	v_mov_b32_e32 v124, v114
	v_mov_b32_e32 v125, v77
	ds_bpermute_b32 v55, v131, v53
	ds_bpermute_b32 v54, v131, v52
	v_and_b32_e32 v97, 0xffff0000, v98
	v_mul_f32_e32 v58, v75, v75
	v_pk_add_f32 v[114:115], v[122:123], v[114:115]
	v_pk_mul_f32 v[122:123], v[76:77], v[124:125]
	v_pk_add_f32 v[116:117], v[116:117], v[116:117] op_sel:[0,1] op_sel_hi:[1,0]
	v_lshlrev_b32_e32 v96, 16, v98
	v_lshlrev_b32_e32 v98, 16, v99
	v_and_b32_e32 v99, 0xffff0000, v99
	v_mov_b32_e32 v115, v123
	v_mov_b32_e32 v117, v58
	v_mul_f32_e32 v56, v97, v97
	v_pk_add_f32 v[114:115], v[114:115], v[116:117]
	v_pk_fma_f32 v[116:117], v[96:97], v[96:97], v[56:57] op_sel_hi:[1,1,0]
	v_mul_f32_e32 v56, v99, v99
	v_mul_f32_e32 v62, v78, v78
	v_mul_f32_e32 v74, v79, v79
	v_pk_fma_f32 v[122:123], v[98:99], v[98:99], v[56:57] op_sel_hi:[1,1,0]
	v_mov_b32_e32 v117, v62
	v_mov_b32_e32 v123, v74
	s_waitcnt lgkmcnt(0)
	v_pk_add_f32 v[52:53], v[52:53], v[54:55]
	v_pk_add_f32 v[116:117], v[116:117], v[122:123]
	v_and_b32_e32 v123, 0xffff0000, v108
	v_and_b32_e32 v125, 0xffff0000, v109
	ds_bpermute_b32 v55, v132, v53
	ds_bpermute_b32 v54, v132, v52
	v_pk_add_f32 v[128:129], v[114:115], v[116:117]
	v_lshlrev_b32_e32 v122, 16, v108
	v_lshlrev_b32_e32 v124, 16, v109
	v_mul_f32_e32 v56, v125, v125
	v_and_b32_e32 v117, 0xffff0000, v67
	v_and_b32_e32 v116, 0xffff0000, v66
	v_lshlrev_b32_e32 v108, 16, v46
	v_and_b32_e32 v109, 0xffff0000, v46
	v_mul_f32_e32 v46, v123, v123
	v_pk_fma_f32 v[140:141], v[124:125], v[124:125], v[56:57] op_sel_hi:[1,1,0]
	v_lshlrev_b32_e32 v115, 16, v67
	v_lshlrev_b32_e32 v114, 16, v66
	v_pk_mul_f32 v[66:67], v[116:117], v[116:117]
	v_lshlrev_b32_e32 v126, 16, v47
	v_and_b32_e32 v127, 0xffff0000, v47
	v_pk_fma_f32 v[46:47], v[122:123], v[122:123], v[46:47] op_sel_hi:[1,1,0]
	v_pk_fma_f32 v[66:67], v[114:115], v[114:115], v[66:67]
	v_mov_b32_e32 v82, v46
	v_mov_b32_e32 v142, v140
	v_mov_b32_e32 v143, v83
	v_mul_f32_e32 v56, v81, v81
	v_pk_add_f32 v[46:47], v[46:47], v[140:141]
	v_pk_mul_f32 v[140:141], v[82:83], v[142:143]
	v_pk_add_f32 v[66:67], v[66:67], v[66:67] op_sel:[0,1] op_sel_hi:[1,0]
	v_mov_b32_e32 v47, v141
	v_mov_b32_e32 v67, v56
	v_mul_f32_e32 v56, v109, v109
	s_waitcnt lgkmcnt(0)
	v_pk_add_f32 v[52:53], v[52:53], v[54:55]
	v_pk_add_f32 v[46:47], v[46:47], v[66:67]
	v_pk_fma_f32 v[66:67], v[108:109], v[108:109], v[56:57] op_sel_hi:[1,1,0]
	v_mul_f32_e32 v56, v127, v127
	ds_bpermute_b32 v55, v133, v53
	ds_bpermute_b32 v54, v133, v52
	v_mul_f32_e32 v58, v84, v84
	v_mul_f32_e32 v62, v85, v85
	v_pk_fma_f32 v[140:141], v[126:127], v[126:127], v[56:57] op_sel_hi:[1,1,0]
	v_mov_b32_e32 v67, v58
	v_mov_b32_e32 v141, v62
	v_pk_add_f32 v[66:67], v[66:67], v[140:141]
	v_mov_b32_e32 v74, v77
	v_pk_add_f32 v[46:47], v[46:47], v[66:67]
	s_waitcnt lgkmcnt(0)
	v_pk_add_f32 v[66:67], v[52:53], v[54:55]
	v_mov_b32_e32 v52, v46
	v_mov_b32_e32 v53, v128
	v_mov_b32_e32 v128, v47
	ds_bpermute_b32 v141, v134, v67
	ds_bpermute_b32 v140, v134, v66
	v_pk_add_f32 v[46:47], v[52:53], v[128:129]
	ds_bpermute_b32 v129, v130, v47
	ds_bpermute_b32 v128, v130, v46
	global_load_dwordx4 v[52:55], v[44:45], off offset:3072 nt
	s_waitcnt lgkmcnt(2)
	v_pk_add_f32 v[44:45], v[66:67], v[140:141]
	ds_bpermute_b32 v67, v135, v45
	ds_bpermute_b32 v66, v135, v44
	s_waitcnt lgkmcnt(2)
	v_pk_add_f32 v[46:47], v[46:47], v[128:129]
	ds_bpermute_b32 v129, v131, v47
	ds_bpermute_b32 v128, v131, v46
	global_load_dwordx4 v[140:143], v[64:65], off offset:1024 nt
	s_waitcnt lgkmcnt(2)
	v_pk_add_f32 v[44:45], v[44:45], v[66:67]
	v_mov_b32_e32 v80, v83
	v_pk_fma_f32 v[150:151], v[44:45], s[44:45], v[148:149] op_sel_hi:[1,0,0]
	s_waitcnt lgkmcnt(0)
	v_pk_add_f32 v[44:45], v[46:47], v[128:129]
	ds_bpermute_b32 v47, v132, v45
	ds_bpermute_b32 v46, v132, v44
	v_mul_f32_e32 v56, 0x4b800000, v151
	v_cmp_gt_f32_e32 vcc, s3, v151
	s_waitcnt lgkmcnt(0)
	v_pk_add_f32 v[128:129], v[44:45], v[46:47]
	ds_bpermute_b32 v145, v133, v129
	ds_bpermute_b32 v144, v133, v128
	v_cndmask_b32_e32 v56, v151, v56, vcc
	v_rsq_f32_e32 v56, v56
	global_load_dwordx4 v[44:47], v[64:65], off offset:2048 nt
	s_nop 0
	global_load_dwordx4 v[64:67], v[64:65], off offset:3072 nt
	s_waitcnt lgkmcnt(0)
	v_pk_add_f32 v[128:129], v[128:129], v[144:145]
	ds_bpermute_b32 v153, v134, v129
	ds_bpermute_b32 v152, v134, v128
	v_mul_f32_e32 v58, 0x45800000, v56
	v_cndmask_b32_e32 v56, v56, v58, vcc
	v_mul_f32_e32 v58, 0x4b800000, v150
	v_cmp_gt_f32_e32 vcc, s3, v150
	s_waitcnt lgkmcnt(0)
	v_pk_add_f32 v[128:129], v[128:129], v[152:153]
	ds_bpermute_b32 v153, v135, v129
	ds_bpermute_b32 v152, v135, v128
	v_cndmask_b32_e32 v58, v150, v58, vcc
	v_rsq_f32_e32 v58, v58
	v_pk_mul_f32 v[100:101], v[56:57], v[100:101] op_sel_hi:[0,1]
	v_pk_mul_f32 v[102:103], v[56:57], v[102:103] op_sel_hi:[0,1]
	s_waitcnt lgkmcnt(0)
	v_pk_add_f32 v[128:129], v[128:129], v[152:153]
	s_waitcnt vmcnt(4)
; __device__ __forceinline__ void ew_post(const bf16* Y, const float* xin, float* xout, const float* gpost, const float* gnext, bf16* H, int gw, int ngw, int lane) {
;     ...
;         for (int q = 0; q < EW_NR; ++q) { rstd[q] = rsqrtf(wave_sum(s[q]) * (1.f / DM) + RMS_EPS); s2[q] = 0.f; }
; #pragma unroll
;         for (int j = 0; j < 4; ++j) { const f32x4 g = *((const f32x4*)gpost + lane + 64 * j);
; #pragma unroll
;             for (int q = 0; q < EW_NR; ++q) { xv[q][j] = xv[q][j] + y[q][j] * rstd[q] * g; __builtin_nontemporal_store(xv[q][j], (f32x4*)(xout + (size_t)(m0 + q) * DM) + lane + 64 * j);
;                 s2[q] += (xv[q][j].x * xv[q][j].x + xv[q][j].y * xv[q][j].y) + (xv[q][j].z * xv[q][j].z + xv[q][j].w * xv[q][j].w); } }
	v_pk_fma_f32 v[22:23], v[102:103], v[138:139], v[22:23]
	v_pk_fma_f32 v[128:129], v[128:129], s[44:45], v[148:149] op_sel_hi:[1,0,0]
	v_pk_fma_f32 v[20:21], v[100:101], v[136:137], v[20:21]
	v_mul_f32_e32 v62, 0x4b800000, v129
	v_cmp_gt_f32_e64 s[4:5], s3, v129
	global_load_dwordx4 v[100:103], v[36:37], off offset:1024 nt
	global_load_dwordx4 v[144:147], v[36:37], off offset:2048 nt
	v_cndmask_b32_e64 v62, v129, v62, s[4:5]
	v_rsq_f32_e32 v62, v62
	global_load_dwordx4 v[148:151], v[36:37], off offset:3072 nt
	v_mul_f32_e32 v36, 0x45800000, v58
	v_cndmask_b32_e32 v58, v58, v36, vcc
	v_mul_f32_e32 v36, 0x45800000, v62
	v_cndmask_b32_e64 v76, v62, v36, s[4:5]
	v_mul_f32_e32 v36, 0x4b800000, v128
	v_cmp_gt_f32_e32 vcc, s3, v128
	v_pk_mul_f32 v[50:51], v[56:57], v[50:51] op_sel_hi:[0,1]
	v_pk_mul_f32 v[48:49], v[56:57], v[48:49] op_sel_hi:[0,1]
	v_cndmask_b32_e32 v36, v128, v36, vcc
	v_rsq_f32_e32 v62, v36
	v_pk_mul_f32 v[36:37], v[58:59], v[110:111] op_sel_hi:[0,1]
	v_pk_fma_f32 v[24:25], v[36:37], v[136:137], v[24:25]
	v_lshl_add_u64 v[128:129], s[10:11], 0, v[178:179]
	v_mul_f32_e32 v36, 0x45800000, v62
	v_pk_mul_f32 v[110:111], v[58:59], v[112:113] op_sel_hi:[0,1]
	v_cndmask_b32_e32 v82, v62, v36, vcc
	v_pk_mul_f32 v[36:37], v[76:77], v[118:119] op_sel_hi:[0,1]
	v_add_co_u32_e32 v118, vcc, s23, v128
	v_pk_fma_f32 v[26:27], v[110:111], v[138:139], v[26:27]
	v_pk_mul_f32 v[110:111], v[76:77], v[120:121] op_sel_hi:[0,1]
	v_addc_co_u32_e32 v119, vcc, 0, v129, vcc
	v_pk_fma_f32 v[34:35], v[138:139], v[110:111], v[34:35]
	v_pk_fma_f32 v[32:33], v[136:137], v[36:37], v[32:33]
	v_pk_mul_f32 v[36:37], v[82:83], v[122:123] op_sel_hi:[0,1]
	v_pk_mul_f32 v[110:111], v[82:83], v[124:125] op_sel_hi:[0,1]
	v_add_co_u32_e32 v120, vcc, s24, v128
	v_pk_fma_f32 v[30:31], v[138:139], v[110:111], v[30:31]
	v_pk_fma_f32 v[28:29], v[136:137], v[36:37], v[28:29]
	v_addc_co_u32_e32 v121, vcc, 0, v129, vcc
	global_store_dwordx4 v[128:129], v[20:23], off sc0 sc1 nt
	global_store_dwordx4 v[118:119], v[24:27], off offset:-4096 sc0 sc1 nt
	global_store_dwordx4 v[118:119], v[32:35], off sc0 sc1 nt
	global_store_dwordx4 v[120:121], v[28:31], off sc0 sc1 nt
	global_load_dwordx4 v[110:113], v[68:69], off offset:1024
	v_mov_b32_e32 v36, v39
	v_mov_b32_e32 v37, v41
	v_pk_mul_f32 v[36:37], v[56:57], v[36:37] op_sel_hi:[0,1]
	v_mov_b32_e32 v39, v40
	v_pk_mul_f32 v[38:39], v[56:57], v[38:39] op_sel_hi:[0,1]
	v_mov_b32_e32 v40, v115
	v_mov_b32_e32 v41, v117
	v_mov_b32_e32 v115, v116
	v_add_co_u32_e32 v122, vcc, s22, v128
	v_mov_b32_e32 v62, v87
	s_nop 0
	v_addc_co_u32_e32 v123, vcc, 0, v129, vcc
	v_pk_mul_f32 v[86:87], v[56:57], v[88:89] op_sel_hi:[0,1]
	v_pk_mul_f32 v[62:63], v[56:57], v[62:63] op_sel_hi:[0,1]
	v_mov_b32_e32 v56, v59
	v_pk_mul_f32 v[88:89], v[58:59], v[60:61] op_sel_hi:[0,1]
	s_andn2_b64 vcc, exec, s[30:31]
	s_waitcnt vmcnt(0)
	v_pk_fma_f32 v[14:15], v[36:37], v[112:113], v[14:15]
	v_mov_b32_e32 v36, v43
	v_mov_b32_e32 v37, v95
	v_pk_mul_f32 v[36:37], v[58:59], v[36:37] op_sel_hi:[0,1]
	v_mov_b32_e32 v43, v94
	v_pk_fma_f32 v[12:13], v[38:39], v[110:111], v[12:13]
	v_pk_mul_f32 v[38:39], v[58:59], v[42:43] op_sel_hi:[0,1]
	v_pk_fma_f32 v[18:19], v[36:37], v[112:113], v[18:19]
	v_mov_b32_e32 v36, v105
	v_mov_b32_e32 v37, v107
	v_mov_b32_e32 v105, v106
	v_pk_fma_f32 v[16:17], v[38:39], v[110:111], v[16:17]
	v_pk_mul_f32 v[38:39], v[76:77], v[36:37] op_sel_hi:[0,1]
	v_pk_mul_f32 v[36:37], v[76:77], v[104:105] op_sel_hi:[0,1]
	v_pk_mul_f32 v[42:43], v[82:83], v[40:41] op_sel_hi:[0,1]
	v_pk_mul_f32 v[40:41], v[82:83], v[114:115] op_sel_hi:[0,1]
	v_pk_fma_f32 v[36:37], v[110:111], v[36:37], v[140:141]
	v_pk_fma_f32 v[38:39], v[112:113], v[38:39], v[142:143]
	v_pk_fma_f32 v[40:41], v[110:111], v[40:41], v[100:101]
	v_pk_fma_f32 v[42:43], v[112:113], v[42:43], v[102:103]
	global_store_dwordx4 v[128:129], v[12:15], off offset:1024 sc0 sc1 nt
	global_store_dwordx4 v[122:123], v[16:19], off offset:1024 sc0 sc1 nt
	global_store_dwordx4 v[118:119], v[36:39], off offset:1024 sc0 sc1 nt
	global_store_dwordx4 v[120:121], v[40:43], off offset:1024 sc0 sc1 nt
	global_load_dwordx4 v[100:103], v[68:69], off offset:2048
	s_waitcnt vmcnt(0)
	v_pk_fma_f32 v[4:5], v[48:49], v[100:101], v[4:5]
	v_pk_fma_f32 v[6:7], v[50:51], v[102:103], v[6:7]
	v_pk_mul_f32 v[48:49], v[58:59], v[92:93] op_sel_hi:[0,1]
	v_pk_mul_f32 v[50:51], v[58:59], v[90:91] op_sel_hi:[0,1]
	v_pk_fma_f32 v[8:9], v[50:51], v[100:101], v[8:9]
	v_pk_fma_f32 v[10:11], v[48:49], v[102:103], v[10:11]
	v_pk_mul_f32 v[48:49], v[76:77], v[98:99] op_sel_hi:[0,1]
	v_pk_mul_f32 v[50:51], v[76:77], v[96:97] op_sel_hi:[0,1]
	v_pk_fma_f32 v[44:45], v[50:51], v[100:101], v[44:45]
	v_pk_fma_f32 v[46:47], v[48:49], v[102:103], v[46:47]
	v_pk_mul_f32 v[50:51], v[82:83], v[126:127] op_sel_hi:[0,1]
	v_pk_mul_f32 v[48:49], v[82:83], v[108:109] op_sel_hi:[0,1]
	v_pk_fma_f32 v[48:49], v[100:101], v[48:49], v[144:145]
	v_pk_fma_f32 v[50:51], v[102:103], v[50:51], v[146:147]
	global_store_dwordx4 v[128:129], v[4:7], off offset:2048 sc0 sc1 nt
	global_store_dwordx4 v[122:123], v[8:11], off offset:2048 sc0 sc1 nt
	global_store_dwordx4 v[118:119], v[44:47], off offset:2048 sc0 sc1 nt
	global_store_dwordx4 v[120:121], v[48:51], off offset:2048 sc0 sc1 nt
	global_load_dwordx4 v[90:93], v[68:69], off offset:3072
	s_waitcnt vmcnt(0)
	v_pk_fma_f32 v[60:61], v[62:63], v[90:91], v[0:1]
	v_pk_mul_f32 v[0:1], v[58:59], v[56:57] op_sel_hi:[0,1]
	v_pk_fma_f32 v[62:63], v[86:87], v[92:93], v[2:3]
	v_pk_fma_f32 v[56:57], v[0:1], v[90:91], v[52:53]
	v_pk_mul_f32 v[0:1], v[76:77], v[78:79] op_sel_hi:[0,1]
	v_pk_mul_f32 v[2:3], v[76:77], v[74:75] op_sel_hi:[0,1]
	v_pk_fma_f32 v[58:59], v[88:89], v[92:93], v[54:55]
	v_pk_fma_f32 v[52:53], v[2:3], v[90:91], v[64:65]
	v_pk_fma_f32 v[54:55], v[0:1], v[92:93], v[66:67]
	v_pk_mul_f32 v[2:3], v[82:83], v[84:85] op_sel_hi:[0,1]
	v_pk_mul_f32 v[0:1], v[82:83], v[80:81] op_sel_hi:[0,1]
	v_pk_fma_f32 v[0:1], v[0:1], v[90:91], v[148:149]
	v_pk_fma_f32 v[2:3], v[2:3], v[92:93], v[150:151]
	global_store_dwordx4 v[128:129], v[60:63], off offset:3072 sc0 sc1 nt
	global_store_dwordx4 v[122:123], v[56:59], off offset:3072 sc0 sc1 nt
	global_store_dwordx4 v[118:119], v[52:55], off offset:3072 sc0 sc1 nt
	global_store_dwordx4 v[120:121], v[0:3], off offset:3072 sc0 sc1 nt
	s_cbranch_vccnz .LBB0_208
; __device__ __forceinline__ void ew_post(const bf16* Y, const float* xin, float* xout, const float* gpost, const float* gnext, bf16* H, int gw, int ngw, int lane) {
;     ...
;                 s2[q] += (xv[q][j].x * xv[q][j].x + xv[q][j].y * xv[q][j].y) + (xv[q][j].z * xv[q][j].z + xv[q][j].w * xv[q][j].w); } }
;         if (gnext) {
;             float r2[EW_NR];
; #pragma unroll
;             for (int q = 0; q < EW_NR; ++q) r2[q] = rsqrtf(wave_sum(s2[q]) * (1.f / DM) + RMS_EPS);
	v_pk_mul_f32 v[64:65], v[30:31], v[30:31]
	v_pk_mul_f32 v[66:67], v[28:29], v[28:29]
	v_mul_f32_e32 v78, v1, v1
	v_pk_mov_b32 v[74:75], v[66:67], v[64:65] op_sel:[1,0]
	v_mov_b32_e32 v67, v65
	v_pk_add_f32 v[64:65], v[74:75], v[66:67]
	v_pk_mul_f32 v[66:67], v[42:43], v[42:43]
	v_pk_mul_f32 v[74:75], v[40:41], v[40:41]
	v_mul_f32_e32 v79, v2, v2
	v_pk_mov_b32 v[76:77], v[74:75], v[66:67] op_sel:[1,0]
	v_mov_b32_e32 v75, v67
	v_pk_add_f32 v[66:67], v[76:77], v[74:75]
	v_mul_f32_e32 v74, v49, v49
	v_mul_f32_e32 v76, v0, v0
	v_pk_fma_f32 v[74:75], v[48:49], v[48:49], v[74:75] op_sel_hi:[1,1,0]
	v_mul_f32_e32 v80, v3, v3
	v_mov_b32_e32 v75, v76
	v_mul_f32_e32 v76, v51, v51
	v_pk_fma_f32 v[76:77], v[50:51], v[50:51], v[76:77] op_sel_hi:[1,1,0]
	v_pk_add_f32 v[64:65], v[64:65], v[64:65] op_sel:[0,1] op_sel_hi:[1,0]
	v_pk_add_f32 v[66:67], v[66:67], v[66:67] op_sel:[0,1] op_sel_hi:[1,0]
	v_mov_b32_e32 v77, v78
	v_mov_b32_e32 v65, v79
	v_mov_b32_e32 v67, v80
	v_pk_add_f32 v[74:75], v[74:75], v[76:77]
	v_pk_add_f32 v[64:65], v[64:65], v[66:67]
	v_pk_mul_f32 v[66:67], v[34:35], v[34:35]
	v_pk_add_f32 v[64:65], v[74:75], v[64:65]
	v_pk_mul_f32 v[74:75], v[32:33], v[32:33]
	v_mul_f32_e32 v86, v53, v53
	v_pk_mov_b32 v[76:77], v[74:75], v[66:67] op_sel:[1,0]
	v_mov_b32_e32 v75, v67
	v_pk_add_f32 v[66:67], v[76:77], v[74:75]
	v_pk_mul_f32 v[74:75], v[38:39], v[38:39]
	v_pk_mul_f32 v[76:77], v[36:37], v[36:37]
	v_pk_add_f32 v[66:67], v[66:67], v[66:67] op_sel:[0,1] op_sel_hi:[1,0]
	v_pk_mov_b32 v[78:79], v[76:77], v[74:75] op_sel:[1,0]
	v_mov_b32_e32 v77, v75
	v_pk_add_f32 v[74:75], v[78:79], v[76:77]
	v_mul_f32_e32 v76, v52, v52
	v_mov_b32_e32 v67, v76
	v_pk_mul_f32 v[76:77], v[26:27], v[26:27]
	v_pk_mul_f32 v[78:79], v[24:25], v[24:25]
	v_mul_f32_e32 v87, v54, v54
	v_pk_mov_b32 v[80:81], v[78:79], v[76:77] op_sel:[1,0]
	v_mov_b32_e32 v79, v77
	v_pk_add_f32 v[76:77], v[80:81], v[78:79]
	v_pk_mul_f32 v[78:79], v[18:19], v[18:19]
	v_pk_mul_f32 v[80:81], v[16:17], v[16:17]
	v_pk_add_f32 v[76:77], v[76:77], v[76:77] op_sel:[0,1] op_sel_hi:[1,0]
	v_pk_mov_b32 v[82:83], v[80:81], v[78:79] op_sel:[1,0]
	v_mov_b32_e32 v81, v79
	v_pk_add_f32 v[78:79], v[82:83], v[80:81]
	v_mul_f32_e32 v80, v56, v56
	v_mul_f32_e32 v81, v57, v57
	v_pk_add_f32 v[78:79], v[78:79], v[78:79] op_sel:[0,1] op_sel_hi:[1,0]
	v_mov_b32_e32 v77, v80
	v_mov_b32_e32 v79, v81
	v_pk_add_f32 v[76:77], v[76:77], v[78:79]
	v_mul_f32_e32 v78, v9, v9
	v_mul_f32_e32 v80, v11, v11
	v_mul_f32_e32 v82, v58, v58
	v_mul_f32_e32 v83, v59, v59
	v_pk_fma_f32 v[78:79], v[8:9], v[8:9], v[78:79] op_sel_hi:[1,1,0]
	v_pk_fma_f32 v[80:81], v[10:11], v[10:11], v[80:81] op_sel_hi:[1,1,0]
	v_mov_b32_e32 v79, v82
	v_mov_b32_e32 v81, v83
	v_pk_add_f32 v[78:79], v[78:79], v[80:81]
	v_pk_mul_f32 v[80:81], v[20:21], v[20:21]
	v_pk_add_f32 v[76:77], v[76:77], v[78:79]
	v_pk_mul_f32 v[78:79], v[22:23], v[22:23]
	v_mul_f32_e32 v88, v55, v55
	v_pk_mov_b32 v[82:83], v[80:81], v[78:79] op_sel:[1,0]
	v_mov_b32_e32 v81, v79
	v_pk_add_f32 v[78:79], v[82:83], v[80:81]
	v_pk_mul_f32 v[80:81], v[14:15], v[14:15]
	v_pk_mul_f32 v[82:83], v[12:13], v[12:13]
	v_pk_add_f32 v[78:79], v[78:79], v[78:79] op_sel:[0,1] op_sel_hi:[1,0]
	v_pk_mov_b32 v[84:85], v[82:83], v[80:81] op_sel:[1,0]
	v_mov_b32_e32 v83, v81
	v_pk_add_f32 v[80:81], v[84:85], v[82:83]
	v_mul_f32_e32 v82, v60, v60
	v_mul_f32_e32 v83, v61, v61
	v_pk_add_f32 v[80:81], v[80:81], v[80:81] op_sel:[0,1] op_sel_hi:[1,0]
	v_mov_b32_e32 v79, v82
	v_mov_b32_e32 v81, v83
	v_pk_add_f32 v[78:79], v[78:79], v[80:81]
	v_mul_f32_e32 v80, v5, v5
	v_mul_f32_e32 v82, v7, v7
	v_mul_f32_e32 v84, v62, v62
	v_mul_f32_e32 v85, v63, v63
	v_pk_fma_f32 v[80:81], v[4:5], v[4:5], v[80:81] op_sel_hi:[1,1,0]
	v_pk_fma_f32 v[82:83], v[6:7], v[6:7], v[82:83] op_sel_hi:[1,1,0]
	v_mov_b32_e32 v81, v84
	v_mov_b32_e32 v83, v85
	v_pk_add_f32 v[80:81], v[80:81], v[82:83]
	v_pk_add_f32 v[82:83], v[74:75], v[74:75] op_sel:[0,1] op_sel_hi:[1,0]
	v_pk_add_f32 v[78:79], v[78:79], v[80:81]
	v_mov_b32_e32 v80, v76
	v_mov_b32_e32 v81, v78
	v_mov_b32_e32 v78, v77
	global_load_dwordx4 v[74:77], v[70:71], off
	v_pk_add_f32 v[78:79], v[80:81], v[78:79]
	v_mov_b32_e32 v83, v86
	ds_bpermute_b32 v81, v130, v79
	ds_bpermute_b32 v80, v130, v78
	v_pk_add_f32 v[66:67], v[66:67], v[82:83]
	v_mul_f32_e32 v82, v45, v45
	v_mul_f32_e32 v84, v47, v47
	v_pk_fma_f32 v[82:83], v[44:45], v[44:45], v[82:83] op_sel_hi:[1,1,0]
	v_pk_fma_f32 v[84:85], v[46:47], v[46:47], v[84:85] op_sel_hi:[1,1,0]
	v_mov_b32_e32 v83, v87
	v_mov_b32_e32 v85, v88
	v_pk_add_f32 v[82:83], v[82:83], v[84:85]
	s_waitcnt lgkmcnt(0)
	v_pk_add_f32 v[78:79], v[78:79], v[80:81]
	v_pk_add_f32 v[66:67], v[66:67], v[82:83]
	v_mov_b32_e32 v82, v64
	v_mov_b32_e32 v83, v66
	v_mov_b32_e32 v66, v65
	ds_bpermute_b32 v81, v131, v79
	ds_bpermute_b32 v80, v131, v78
	v_pk_add_f32 v[64:65], v[82:83], v[66:67]
	ds_bpermute_b32 v67, v130, v65
	ds_bpermute_b32 v66, v130, v64
	s_waitcnt lgkmcnt(2)
	v_pk_add_f32 v[78:79], v[78:79], v[80:81]
	ds_bpermute_b32 v81, v132, v79
	ds_bpermute_b32 v80, v132, v78
	s_waitcnt lgkmcnt(2)
	v_pk_add_f32 v[64:65], v[64:65], v[66:67]
	ds_bpermute_b32 v67, v131, v65
	ds_bpermute_b32 v66, v131, v64
	s_waitcnt lgkmcnt(2)
	v_pk_add_f32 v[78:79], v[78:79], v[80:81]
	ds_bpermute_b32 v81, v133, v79
	ds_bpermute_b32 v80, v133, v78
	s_waitcnt lgkmcnt(2)
	v_pk_add_f32 v[64:65], v[64:65], v[66:67]
	ds_bpermute_b32 v67, v132, v65
	ds_bpermute_b32 v66, v132, v64
	s_waitcnt lgkmcnt(2)
	v_pk_add_f32 v[78:79], v[78:79], v[80:81]
	ds_bpermute_b32 v81, v134, v79
	ds_bpermute_b32 v80, v134, v78
	s_waitcnt lgkmcnt(2)
; __device__ __forceinline__ unsigned pk2(float lo, float hi) { f32v2 v = {lo, hi}; bf16v2 r = __builtin_convertvector(v, bf16v2); return __builtin_bit_cast(unsigned, r); }
; __device__ __forceinline__ void ew_post(const bf16* Y, const float* xin, float* xout, const float* gpost, const float* gnext, bf16* H, int gw, int ngw, int lane) {
;     ...
;             float r2[EW_NR];
; #pragma unroll
;             for (int q = 0; q < EW_NR; ++q) r2[q] = rsqrtf(wave_sum(s2[q]) * (1.f / DM) + RMS_EPS);
; #pragma unroll
;             for (int j = 0; j < 4; ++j) { const f32x4 g = *((const f32x4*)gnext + lane + 64 * j);
; #pragma unroll
;                 for (int q = 0; q < EW_NR; ++q) { v2u w; w.x = pk2(xv[q][j].x * r2[q] * g.x, xv[q][j].y * r2[q] * g.y); w.y = pk2(xv[q][j].z * r2[q] * g.z, xv[q][j].w * r2[q] * g.w);
;                     *((v2u*)(H + (size_t)(m0 + q) * DM) + lane + 64 * j) = w; } }
	v_pk_add_f32 v[64:65], v[64:65], v[66:67]
	ds_bpermute_b32 v67, v133, v65
	ds_bpermute_b32 v66, v133, v64
	s_waitcnt lgkmcnt(2)
	v_pk_add_f32 v[78:79], v[78:79], v[80:81]
	ds_bpermute_b32 v81, v135, v79
	ds_bpermute_b32 v80, v135, v78
	s_waitcnt lgkmcnt(2)
	v_pk_add_f32 v[64:65], v[64:65], v[66:67]
	ds_bpermute_b32 v67, v134, v65
	ds_bpermute_b32 v66, v134, v64
	s_waitcnt lgkmcnt(2)
	v_pk_add_f32 v[78:79], v[78:79], v[80:81]
	v_mov_b64_e32 v[80:81], s[26:27]
	v_pk_fma_f32 v[78:79], v[78:79], s[44:45], v[80:81] op_sel_hi:[1,0,0]
	s_waitcnt lgkmcnt(0)
	v_pk_add_f32 v[64:65], v[64:65], v[66:67]
	v_mul_f32_e32 v82, 0x4b800000, v79
	v_cmp_gt_f32_e32 vcc, s3, v79
	ds_bpermute_b32 v67, v135, v65
	ds_bpermute_b32 v66, v135, v64
	v_cndmask_b32_e32 v79, v79, v82, vcc
	v_rsq_f32_e32 v79, v79
	v_mul_f32_e32 v82, 0x4b800000, v78
	v_cmp_gt_f32_e64 s[4:5], s3, v78
	s_waitcnt lgkmcnt(0)
	v_pk_add_f32 v[64:65], v[64:65], v[66:67]
	v_cndmask_b32_e64 v78, v78, v82, s[4:5]
	v_rsq_f32_e32 v82, v78
	v_mul_f32_e32 v78, 0x45800000, v79
	v_pk_fma_f32 v[64:65], v[64:65], s[44:45], v[80:81] op_sel_hi:[1,0,0]
	v_cndmask_b32_e32 v78, v79, v78, vcc
	v_mul_f32_e32 v66, 0x4b800000, v65
	v_cmp_gt_f32_e32 vcc, s3, v65
	v_mul_f32_e32 v79, 0x45800000, v82
	v_cmp_gt_f32_e64 s[6:7], s3, v64
	v_cndmask_b32_e32 v65, v65, v66, vcc
	v_rsq_f32_e32 v65, v65
	v_mul_f32_e32 v66, 0x4b800000, v64
	v_pk_mul_f32 v[20:21], v[20:21], v[78:79] op_sel_hi:[1,0]
	v_pk_mul_f32 v[22:23], v[22:23], v[78:79] op_sel_hi:[1,0]
	v_mul_f32_e32 v67, 0x45800000, v65
	v_cndmask_b32_e64 v64, v64, v66, s[6:7]
	v_cndmask_b32_e64 v66, v82, v79, s[4:5]
	v_cndmask_b32_e32 v80, v65, v67, vcc
	s_waitcnt vmcnt(0)
	v_pk_mul_f32 v[20:21], v[20:21], v[74:75]
	v_pk_mul_f32 v[22:23], v[22:23], v[76:77]
	v_add_co_u32_e32 v82, vcc, s20, v72
	v_cvt_pk_bf16_f32 v20, v20, v21
	v_cvt_pk_bf16_f32 v21, v22, v23
	v_addc_co_u32_e32 v83, vcc, -1, v73, vcc
	v_rsq_f32_e32 v64, v64
	global_store_dwordx2 v[82:83], v[20:21], off offset:-3584
	v_pk_mul_f32 v[20:21], v[24:25], v[66:67] op_sel_hi:[1,0]
	v_pk_mul_f32 v[22:23], v[26:27], v[66:67] op_sel_hi:[1,0]
	v_pk_mul_f32 v[20:21], v[20:21], v[74:75]
	v_pk_mul_f32 v[22:23], v[22:23], v[76:77]
	v_cvt_pk_bf16_f32 v20, v20, v21
	v_cvt_pk_bf16_f32 v21, v22, v23
	global_store_dwordx2 v[82:83], v[20:21], off offset:-1536
	v_pk_mul_f32 v[20:21], v[32:33], v[80:81] op_sel_hi:[1,0]
	v_pk_mul_f32 v[22:23], v[34:35], v[80:81] op_sel_hi:[1,0]
	v_mul_f32_e32 v65, 0x45800000, v64
	v_pk_mul_f32 v[20:21], v[74:75], v[20:21]
	v_pk_mul_f32 v[22:23], v[76:77], v[22:23]
	v_add_co_u32_e32 v24, vcc, s21, v72
	v_cndmask_b32_e64 v64, v64, v65, s[6:7]
	v_cvt_pk_bf16_f32 v20, v20, v21
	v_cvt_pk_bf16_f32 v21, v22, v23
	v_addc_co_u32_e32 v25, vcc, -1, v73, vcc
	global_store_dwordx2 v[24:25], v[20:21], off offset:-3584
	v_pk_mul_f32 v[20:21], v[28:29], v[64:65] op_sel_hi:[1,0]
	v_pk_mul_f32 v[22:23], v[30:31], v[64:65] op_sel_hi:[1,0]
	v_pk_mul_f32 v[20:21], v[74:75], v[20:21]
	v_pk_mul_f32 v[22:23], v[76:77], v[22:23]
	v_cvt_pk_bf16_f32 v20, v20, v21
	v_cvt_pk_bf16_f32 v21, v22, v23
	global_store_dwordx2 v[24:25], v[20:21], off offset:-1536
	global_load_dwordx4 v[20:23], v[70:71], off offset:1024
	v_pk_mul_f32 v[12:13], v[12:13], v[78:79] op_sel_hi:[1,0]
	v_pk_mul_f32 v[14:15], v[14:15], v[78:79] op_sel_hi:[1,0]
	v_pk_mul_f32 v[4:5], v[4:5], v[78:79] op_sel_hi:[1,0]
	v_pk_mul_f32 v[6:7], v[6:7], v[78:79] op_sel_hi:[1,0]
	v_pk_mul_f32 v[0:1], v[0:1], v[64:65] op_sel_hi:[1,0]
	v_pk_mul_f32 v[2:3], v[2:3], v[64:65] op_sel_hi:[1,0]
	s_waitcnt vmcnt(0)
; __device__ __forceinline__ unsigned pk2(float lo, float hi) { f32v2 v = {lo, hi}; bf16v2 r = __builtin_convertvector(v, bf16v2); return __builtin_bit_cast(unsigned, r); }
; __device__ __forceinline__ void ew_post(const bf16* Y, const float* xin, float* xout, const float* gpost, const float* gnext, bf16* H, int gw, int ngw, int lane) {
;     ...
; #pragma unroll
;             for (int j = 0; j < 4; ++j) { const f32x4 g = *((const f32x4*)gnext + lane + 64 * j);
; #pragma unroll
;                 for (int q = 0; q < EW_NR; ++q) { v2u w; w.x = pk2(xv[q][j].x * r2[q] * g.x, xv[q][j].y * r2[q] * g.y); w.y = pk2(xv[q][j].z * r2[q] * g.z, xv[q][j].w * r2[q] * g.w);
;                     *((v2u*)(H + (size_t)(m0 + q) * DM) + lane + 64 * j) = w; } }
	v_pk_mul_f32 v[12:13], v[12:13], v[20:21]
	v_pk_mul_f32 v[14:15], v[14:15], v[22:23]
	v_cvt_pk_bf16_f32 v12, v12, v13
	v_cvt_pk_bf16_f32 v13, v14, v15
	global_store_dwordx2 v[82:83], v[12:13], off offset:-3072
	v_pk_mul_f32 v[12:13], v[16:17], v[66:67] op_sel_hi:[1,0]
	v_pk_mul_f32 v[14:15], v[18:19], v[66:67] op_sel_hi:[1,0]
	v_pk_mul_f32 v[12:13], v[12:13], v[20:21]
	v_pk_mul_f32 v[14:15], v[14:15], v[22:23]
	v_cvt_pk_bf16_f32 v12, v12, v13
	v_cvt_pk_bf16_f32 v13, v14, v15
	global_store_dwordx2 v[82:83], v[12:13], off offset:-1024
	v_pk_mul_f32 v[12:13], v[36:37], v[80:81] op_sel_hi:[1,0]
	v_pk_mul_f32 v[14:15], v[38:39], v[80:81] op_sel_hi:[1,0]
	v_pk_mul_f32 v[12:13], v[12:13], v[20:21]
	v_pk_mul_f32 v[14:15], v[14:15], v[22:23]
	v_cvt_pk_bf16_f32 v12, v12, v13
	v_cvt_pk_bf16_f32 v13, v14, v15
	global_store_dwordx2 v[24:25], v[12:13], off offset:-3072
	v_pk_mul_f32 v[12:13], v[40:41], v[64:65] op_sel_hi:[1,0]
	v_pk_mul_f32 v[14:15], v[42:43], v[64:65] op_sel_hi:[1,0]
	v_pk_mul_f32 v[12:13], v[20:21], v[12:13]
	v_pk_mul_f32 v[14:15], v[22:23], v[14:15]
	v_cvt_pk_bf16_f32 v12, v12, v13
	v_cvt_pk_bf16_f32 v13, v14, v15
	global_store_dwordx2 v[24:25], v[12:13], off offset:-1024
	global_load_dwordx4 v[12:15], v[70:71], off offset:2048
	v_pk_mul_f32 v[16:17], v[52:53], v[80:81] op_sel_hi:[1,0]
	v_pk_mul_f32 v[18:19], v[54:55], v[80:81] op_sel_hi:[1,0]
	s_waitcnt vmcnt(0)
	v_pk_mul_f32 v[4:5], v[4:5], v[12:13]
	v_pk_mul_f32 v[6:7], v[6:7], v[14:15]
	v_cvt_pk_bf16_f32 v4, v4, v5
	v_cvt_pk_bf16_f32 v5, v6, v7
	global_store_dwordx2 v[82:83], v[4:5], off offset:-2560
	v_pk_mul_f32 v[4:5], v[8:9], v[66:67] op_sel_hi:[1,0]
	v_pk_mul_f32 v[6:7], v[10:11], v[66:67] op_sel_hi:[1,0]
	v_pk_mul_f32 v[4:5], v[4:5], v[12:13]
	v_pk_mul_f32 v[6:7], v[6:7], v[14:15]
	v_cvt_pk_bf16_f32 v4, v4, v5
	v_cvt_pk_bf16_f32 v5, v6, v7
	global_store_dwordx2 v[82:83], v[4:5], off offset:-512
	v_pk_mul_f32 v[4:5], v[44:45], v[80:81] op_sel_hi:[1,0]
	v_pk_mul_f32 v[6:7], v[46:47], v[80:81] op_sel_hi:[1,0]
	v_pk_mul_f32 v[4:5], v[4:5], v[12:13]
	v_pk_mul_f32 v[6:7], v[6:7], v[14:15]
	v_cvt_pk_bf16_f32 v4, v4, v5
	v_cvt_pk_bf16_f32 v5, v6, v7
	global_store_dwordx2 v[24:25], v[4:5], off offset:-2560
	v_pk_mul_f32 v[4:5], v[48:49], v[64:65] op_sel_hi:[1,0]
	v_pk_mul_f32 v[6:7], v[50:51], v[64:65] op_sel_hi:[1,0]
	v_pk_mul_f32 v[4:5], v[4:5], v[12:13]
	v_pk_mul_f32 v[6:7], v[6:7], v[14:15]
	v_cvt_pk_bf16_f32 v4, v4, v5
	v_cvt_pk_bf16_f32 v5, v6, v7
	global_store_dwordx2 v[24:25], v[4:5], off offset:-512
	global_load_dwordx4 v[4:7], v[70:71], off offset:3072
	v_pk_mul_f32 v[8:9], v[60:61], v[78:79] op_sel_hi:[1,0]
	v_pk_mul_f32 v[10:11], v[62:63], v[78:79] op_sel_hi:[1,0]
	v_pk_mul_f32 v[12:13], v[56:57], v[66:67] op_sel_hi:[1,0]
	v_pk_mul_f32 v[14:15], v[58:59], v[66:67] op_sel_hi:[1,0]
	s_waitcnt vmcnt(0)
	v_pk_mul_f32 v[8:9], v[8:9], v[4:5]
	v_pk_mul_f32 v[10:11], v[10:11], v[6:7]
	v_pk_mul_f32 v[12:13], v[12:13], v[4:5]
	v_pk_mul_f32 v[14:15], v[14:15], v[6:7]
	v_pk_mul_f32 v[16:17], v[16:17], v[4:5]
	v_pk_mul_f32 v[18:19], v[18:19], v[6:7]
	v_pk_mul_f32 v[0:1], v[0:1], v[4:5]
	v_pk_mul_f32 v[2:3], v[2:3], v[6:7]
	v_cvt_pk_bf16_f32 v4, v8, v9
	v_cvt_pk_bf16_f32 v5, v10, v11
	v_cvt_pk_bf16_f32 v6, v12, v13
	v_cvt_pk_bf16_f32 v7, v14, v15
	v_cvt_pk_bf16_f32 v8, v16, v17
	v_cvt_pk_bf16_f32 v9, v18, v19
	v_cvt_pk_bf16_f32 v0, v0, v1
	v_cvt_pk_bf16_f32 v1, v2, v3
	global_store_dwordx2 v[82:83], v[4:5], off offset:-2048
	global_store_dwordx2 v[24:25], v[6:7], off offset:-4096
	global_store_dwordx2 v[24:25], v[8:9], off offset:-2048
	global_store_dwordx2 v[24:25], v[0:1], off
	s_branch .LBB0_208

; __device__ __forceinline__ unsigned pk2(float lo, float hi) { f32v2 v = {lo, hi}; bf16v2 r = __builtin_convertvector(v, bf16v2); return __builtin_bit_cast(unsigned, r); }
; __device__ __forceinline__ float sigmoid_f(float x) { return __builtin_amdgcn_rcpf(1.0f + __builtin_amdgcn_exp2f(-1.4426950409f * x)); }
;     __device__ __forceinline__ void operator()(f32x4 (&acc)[2][2][4][2], const Unit& u, int wr, int wc, int fr, int fq) const {
;     ...
;         if constexpr (MODE == 2) {
;             if (u.pn >= 6 && u.pn < 14) {
;                 const int chb = 128 * (u.pn - 6) + cl0;
; #pragma unroll
;                 for (int ai = 0; ai < 2; ++ai)
; #pragma unroll
;                     for (int m = 0; m < 4; ++m) {
;                         const size_t row = (size_t)(row0 + ai * HALF + m * 16);
;                         float r[8], g[8];
; #pragma unroll
;                         for (int e = 0; e < 4; ++e) {
;                             const float g0a = fmaxf(sigmoid_f(acc[ai][0][m][0][e]), 1e-13f), g0b = fmaxf(sigmoid_f(acc[ai][0][m][1][e]), 1e-13f);
;                             const float g1a = fmaxf(sigmoid_f(acc[ai][1][m][0][e]), 1e-13f), g1b = fmaxf(sigmoid_f(acc[ai][1][m][1][e]), 1e-13f);
;                             g[e] = g1a; g[4 + e] = g1b; r[e] = g0a * __builtin_amdgcn_rcpf(g1a); r[4 + e] = g0b * __builtin_amdgcn_rcpf(g1b);
;                         }
;                         u32x4 wr_, wg_; wr_.x = pk2(r[0], r[1]); wr_.y = pk2(r[2], r[3]); wr_.z = pk2(r[4], r[5]); wr_.w = pk2(r[6], r[7]);
;                         wg_.x = pk2(g[0], g[1]); wg_.y = pk2(g[2], g[3]); wg_.z = pk2(g[4], g[5]); wg_.w = pk2(g[6], g[7]);
;                         __builtin_nontemporal_store(wr_, (u32x4*)(O4 + row * 3072 + chb));
;                         __builtin_nontemporal_store(wg_, (u32x4*)(O4 + row * 3072 + 1024 + chb));
.LBB0_558:
	s_and_b64 vcc, exec, s[6:7]
	s_cbranch_vccz .LBB0_560
	v_mul_f32_e32 v129, 0xbfb8aa3b, v120
	v_exp_f32_e32 v129, v129
	v_mul_f32_e32 v133, 0xbfb8aa3b, v117
	v_exp_f32_e32 v133, v133
	v_mul_f32_e32 v128, 0xbfb8aa3b, v124
	v_add_f32_e32 v129, 1.0, v129
	v_rcp_f32_e32 v129, v129
	v_add_f32_e32 v133, 1.0, v133
	v_rcp_f32_e32 v133, v133
	v_exp_f32_e32 v128, v128
	v_max_f32_e32 v130, 0x29e12e13, v129
	v_mul_f32_e32 v129, 0xbfb8aa3b, v116
	v_exp_f32_e32 v129, v129
	v_max_f32_e32 v153, 0x29e12e13, v133
	v_mul_f32_e32 v133, 0xbfb8aa3b, v113
	v_exp_f32_e32 v133, v133
	v_add_f32_e32 v129, 1.0, v129
	v_rcp_f32_e32 v129, v129
	v_add_f32_e32 v128, 1.0, v128
	v_add_f32_e32 v133, 1.0, v133
	v_rcp_f32_e32 v133, v133
	v_max_f32_e32 v147, 0x29e12e13, v129
	v_mul_f32_e32 v129, 0xbfb8aa3b, v112
	v_exp_f32_e32 v129, v129
	v_rcp_f32_e32 v128, v128
	v_rcp_f32_e32 v132, v147
	v_max_f32_e32 v154, 0x29e12e13, v133
	v_add_f32_e32 v129, 1.0, v129
	v_rcp_f32_e32 v129, v129
	v_rcp_f32_e32 v133, v153
	v_max_f32_e32 v128, 0x29e12e13, v128
	v_mul_f32_e32 v131, 0xbfb8aa3b, v121
	v_max_f32_e32 v152, 0x29e12e13, v129
	v_mul_f32_e32 v129, 0xbfb8aa3b, v125
	v_exp_f32_e32 v129, v129
	v_exp_f32_e32 v131, v131
	v_rcp_f32_e32 v134, v152
	v_rcp_f32_e32 v135, v154
	v_add_f32_e32 v129, 1.0, v129
	v_rcp_f32_e32 v129, v129
	v_add_f32_e32 v131, 1.0, v131
	v_rcp_f32_e32 v131, v131
	v_mul_f32_e32 v149, 0xbfb8aa3b, v119
	v_max_f32_e32 v129, 0x29e12e13, v129
	v_pk_mul_f32 v[128:129], v[132:133], v[128:129]
	v_mul_f32_e32 v133, 0xbfb8aa3b, v122
	v_exp_f32_e32 v133, v133
	v_max_f32_e32 v131, 0x29e12e13, v131
	v_pk_mul_f32 v[130:131], v[134:135], v[130:131]
	v_exp_f32_e32 v149, v149
	v_add_f32_e32 v133, 1.0, v133
	v_rcp_f32_e32 v133, v133
	v_mul_f32_e32 v132, 0xbfb8aa3b, v126
	v_add_f32_e32 v149, 1.0, v149
	v_rcp_f32_e32 v149, v149
	v_max_f32_e32 v134, 0x29e12e13, v133
	v_mul_f32_e32 v133, 0xbfb8aa3b, v118
	v_exp_f32_e32 v133, v133
	v_max_f32_e32 v157, 0x29e12e13, v149
	v_mul_f32_e32 v149, 0xbfb8aa3b, v115
	v_exp_f32_e32 v149, v149
	v_add_f32_e32 v133, 1.0, v133
	v_rcp_f32_e32 v133, v133
	v_mul_f32_e32 v135, 0xbfb8aa3b, v123
	v_exp_f32_e32 v132, v132
	v_exp_f32_e32 v135, v135
	v_max_f32_e32 v155, 0x29e12e13, v133
	v_mul_f32_e32 v133, 0xbfb8aa3b, v114
	v_exp_f32_e32 v133, v133
	v_add_f32_e32 v149, 1.0, v149
	v_rcp_f32_e32 v149, v149
	v_add_f32_e32 v132, 1.0, v132
	v_add_f32_e32 v133, 1.0, v133
	v_rcp_f32_e32 v133, v133
	v_add_f32_e32 v135, 1.0, v135
	v_rcp_f32_e32 v132, v132
	v_rcp_f32_e32 v135, v135
	v_max_f32_e32 v156, 0x29e12e13, v133
	v_mul_f32_e32 v133, 0xbfb8aa3b, v127
	v_exp_f32_e32 v133, v133
	v_max_f32_e32 v158, 0x29e12e13, v149
	v_rcp_f32_e32 v148, v155
	v_rcp_f32_e32 v150, v156
	v_add_f32_e32 v133, 1.0, v133
	v_rcp_f32_e32 v133, v133
	v_rcp_f32_e32 v149, v157
	v_rcp_f32_e32 v151, v158
	v_readlane_b32 s6, v253, 24
	v_max_f32_e32 v132, 0x29e12e13, v132
	v_max_f32_e32 v133, 0x29e12e13, v133
	v_max_f32_e32 v135, 0x29e12e13, v135
	v_readlane_b32 s7, v253, 25
	v_lshl_add_u32 v178, s70, 7, v163
	v_pk_mul_f32 v[148:149], v[148:149], v[132:133]
	v_pk_mul_f32 v[150:151], v[150:151], v[134:135]
	v_cvt_pk_bf16_f32 v132, v128, v129
	v_mov_b64_e32 v[128:129], s[6:7]
	v_cvt_pk_bf16_f32 v133, v148, v149
	v_cvt_pk_bf16_f32 v134, v130, v131
	v_cvt_pk_bf16_f32 v135, v150, v151
	v_cvt_pk_bf16_f32 v148, v147, v153
	v_cvt_pk_bf16_f32 v150, v152, v154
	v_mad_i64_i32 v[152:153], s[6:7], v146, s33, v[128:129]
	v_lshlrev_b64 v[130:131], 1, v[178:179]
	v_lshl_add_u64 v[152:153], v[152:153], 0, v[130:131]
	v_cvt_pk_bf16_f32 v149, v155, v157
	v_cvt_pk_bf16_f32 v151, v156, v158
	global_store_dwordx4 v[152:153], v[132:135], off sc0 sc1 nt
	global_store_dwordx4 v[152:153], v[148:151], off offset:2048 sc0 sc1 nt
	v_mul_f32_e32 v153, 0xbfb8aa3b, v103
	v_mul_f32_e32 v133, 0xbfb8aa3b, v104
	v_exp_f32_e32 v133, v133
	v_mul_f32_e32 v149, 0xbfb8aa3b, v101
	v_exp_f32_e32 v149, v149
	v_mul_f32_e32 v132, 0xbfb8aa3b, v108
	v_add_f32_e32 v133, 1.0, v133
	v_rcp_f32_e32 v133, v133
	v_add_f32_e32 v149, 1.0, v149
	v_rcp_f32_e32 v149, v149
	v_exp_f32_e32 v132, v132
	v_max_f32_e32 v134, 0x29e12e13, v133
	v_mul_f32_e32 v133, 0xbfb8aa3b, v100
	v_exp_f32_e32 v133, v133
	v_max_f32_e32 v158, 0x29e12e13, v149
	v_mul_f32_e32 v149, 0xbfb8aa3b, v97
	v_exp_f32_e32 v149, v149
	v_add_f32_e32 v133, 1.0, v133
	v_rcp_f32_e32 v133, v133
	v_add_f32_e32 v132, 1.0, v132
	v_add_f32_e32 v149, 1.0, v149
	v_rcp_f32_e32 v149, v149
	v_max_f32_e32 v156, 0x29e12e13, v133
	v_mul_f32_e32 v133, 0xbfb8aa3b, v96
	v_exp_f32_e32 v133, v133
	v_rcp_f32_e32 v132, v132
	v_rcp_f32_e32 v148, v156
	v_max_f32_e32 v159, 0x29e12e13, v149
	v_add_f32_e32 v133, 1.0, v133
	v_rcp_f32_e32 v133, v133
	v_rcp_f32_e32 v149, v158
	v_max_f32_e32 v132, 0x29e12e13, v132
	v_mul_f32_e32 v135, 0xbfb8aa3b, v105
	v_max_f32_e32 v157, 0x29e12e13, v133
	v_mul_f32_e32 v133, 0xbfb8aa3b, v109
	v_exp_f32_e32 v133, v133
	v_exp_f32_e32 v135, v135
	v_rcp_f32_e32 v150, v157
	v_rcp_f32_e32 v151, v159
	v_add_f32_e32 v133, 1.0, v133
	v_rcp_f32_e32 v133, v133
	v_add_f32_e32 v135, 1.0, v135
	v_rcp_f32_e32 v135, v135
	v_exp_f32_e32 v153, v153
	v_max_f32_e32 v133, 0x29e12e13, v133
	v_pk_mul_f32 v[132:133], v[148:149], v[132:133]
	v_mul_f32_e32 v149, 0xbfb8aa3b, v106
	v_exp_f32_e32 v149, v149
	v_max_f32_e32 v135, 0x29e12e13, v135
	v_pk_mul_f32 v[134:135], v[150:151], v[134:135]
	v_add_f32_e32 v153, 1.0, v153
	v_add_f32_e32 v149, 1.0, v149
	v_rcp_f32_e32 v149, v149
	v_rcp_f32_e32 v153, v153
	v_mul_f32_e32 v148, 0xbfb8aa3b, v110
	v_mul_f32_e32 v151, 0xbfb8aa3b, v107
	v_max_f32_e32 v150, 0x29e12e13, v149
	v_mul_f32_e32 v149, 0xbfb8aa3b, v102
	v_exp_f32_e32 v149, v149
	v_max_f32_e32 v166, 0x29e12e13, v153
; __device__ __forceinline__ unsigned pk2(float lo, float hi) { f32v2 v = {lo, hi}; bf16v2 r = __builtin_convertvector(v, bf16v2); return __builtin_bit_cast(unsigned, r); }
; __device__ __forceinline__ float sigmoid_f(float x) { return __builtin_amdgcn_rcpf(1.0f + __builtin_amdgcn_exp2f(-1.4426950409f * x)); }
;     __device__ __forceinline__ void operator()(f32x4 (&acc)[2][2][4][2], const Unit& u, int wr, int wc, int fr, int fq) const {
;     ...
;                     for (int m = 0; m < 4; ++m) {
;                         const size_t row = (size_t)(row0 + ai * HALF + m * 16);
;                         float r[8], g[8];
; #pragma unroll
;                         for (int e = 0; e < 4; ++e) {
;                             const float g0a = fmaxf(sigmoid_f(acc[ai][0][m][0][e]), 1e-13f), g0b = fmaxf(sigmoid_f(acc[ai][0][m][1][e]), 1e-13f);
;                             const float g1a = fmaxf(sigmoid_f(acc[ai][1][m][0][e]), 1e-13f), g1b = fmaxf(sigmoid_f(acc[ai][1][m][1][e]), 1e-13f);
;                             g[e] = g1a; g[4 + e] = g1b; r[e] = g0a * __builtin_amdgcn_rcpf(g1a); r[4 + e] = g0b * __builtin_amdgcn_rcpf(g1b);
;                         }
;                         u32x4 wr_, wg_; wr_.x = pk2(r[0], r[1]); wr_.y = pk2(r[2], r[3]); wr_.z = pk2(r[4], r[5]); wr_.w = pk2(r[6], r[7]);
;                         wg_.x = pk2(g[0], g[1]); wg_.y = pk2(g[2], g[3]); wg_.z = pk2(g[4], g[5]); wg_.w = pk2(g[6], g[7]);
;                         __builtin_nontemporal_store(wr_, (u32x4*)(O4 + row * 3072 + chb));
;                         __builtin_nontemporal_store(wg_, (u32x4*)(O4 + row * 3072 + 1024 + chb));
	v_mul_f32_e32 v153, 0xbfb8aa3b, v99
	v_exp_f32_e32 v153, v153
	v_add_f32_e32 v149, 1.0, v149
	v_rcp_f32_e32 v149, v149
	v_exp_f32_e32 v148, v148
	v_exp_f32_e32 v151, v151
	v_add_f32_e32 v153, 1.0, v153
	v_max_f32_e32 v160, 0x29e12e13, v149
	v_mul_f32_e32 v149, 0xbfb8aa3b, v98
	v_exp_f32_e32 v149, v149
	v_rcp_f32_e32 v153, v153
	v_add_f32_e32 v148, 1.0, v148
	v_add_f32_e32 v151, 1.0, v151
	v_add_f32_e32 v149, 1.0, v149
	v_rcp_f32_e32 v149, v149
	v_rcp_f32_e32 v148, v148
	v_rcp_f32_e32 v151, v151
	v_max_f32_e32 v167, 0x29e12e13, v153
	v_max_f32_e32 v161, 0x29e12e13, v149
	v_mul_f32_e32 v149, 0xbfb8aa3b, v111
	v_exp_f32_e32 v149, v149
	v_rcp_f32_e32 v152, v160
	v_rcp_f32_e32 v154, v161
	v_rcp_f32_e32 v153, v166
	v_add_f32_e32 v149, 1.0, v149
	v_rcp_f32_e32 v149, v149
	v_rcp_f32_e32 v155, v167
	v_or_b32_e32 v147, 16, v146
	v_max_f32_e32 v148, 0x29e12e13, v148
	v_max_f32_e32 v149, 0x29e12e13, v149
	v_max_f32_e32 v151, 0x29e12e13, v151
	v_pk_mul_f32 v[148:149], v[152:153], v[148:149]
	v_pk_mul_f32 v[150:151], v[154:155], v[150:151]
	v_mad_i64_i32 v[152:153], s[6:7], v147, s33, v[128:129]
	v_cvt_pk_bf16_f32 v132, v132, v133
	v_cvt_pk_bf16_f32 v133, v148, v149
	v_cvt_pk_bf16_f32 v134, v134, v135
	v_cvt_pk_bf16_f32 v135, v150, v151
	v_lshl_add_u64 v[152:153], v[152:153], 0, v[130:131]
	v_cvt_pk_bf16_f32 v148, v156, v158
	v_cvt_pk_bf16_f32 v149, v160, v166
	v_cvt_pk_bf16_f32 v150, v157, v159
	v_cvt_pk_bf16_f32 v151, v161, v167
	global_store_dwordx4 v[152:153], v[132:135], off sc0 sc1 nt
	global_store_dwordx4 v[152:153], v[148:151], off offset:2048 sc0 sc1 nt
	v_mul_f32_e32 v153, 0xbfb8aa3b, v87
	v_mul_f32_e32 v133, 0xbfb8aa3b, v88
	v_exp_f32_e32 v133, v133
	v_mul_f32_e32 v149, 0xbfb8aa3b, v85
	v_exp_f32_e32 v149, v149
	v_mul_f32_e32 v132, 0xbfb8aa3b, v92
	v_add_f32_e32 v133, 1.0, v133
	v_rcp_f32_e32 v133, v133
	v_add_f32_e32 v149, 1.0, v149
	v_rcp_f32_e32 v149, v149
	v_exp_f32_e32 v132, v132
	v_max_f32_e32 v134, 0x29e12e13, v133
	v_mul_f32_e32 v133, 0xbfb8aa3b, v84
	v_exp_f32_e32 v133, v133
	v_max_f32_e32 v158, 0x29e12e13, v149
	v_mul_f32_e32 v149, 0xbfb8aa3b, v81
	v_exp_f32_e32 v149, v149
	v_add_f32_e32 v133, 1.0, v133
	v_rcp_f32_e32 v133, v133
	v_add_f32_e32 v132, 1.0, v132
	v_add_f32_e32 v149, 1.0, v149
	v_rcp_f32_e32 v149, v149
	v_max_f32_e32 v156, 0x29e12e13, v133
	v_mul_f32_e32 v133, 0xbfb8aa3b, v80
	v_exp_f32_e32 v133, v133
	v_rcp_f32_e32 v132, v132
	v_rcp_f32_e32 v148, v156
	v_max_f32_e32 v159, 0x29e12e13, v149
	v_add_f32_e32 v133, 1.0, v133
	v_rcp_f32_e32 v133, v133
	v_rcp_f32_e32 v149, v158
	v_max_f32_e32 v132, 0x29e12e13, v132
	v_mul_f32_e32 v135, 0xbfb8aa3b, v89
	v_max_f32_e32 v157, 0x29e12e13, v133
	v_mul_f32_e32 v133, 0xbfb8aa3b, v93
	v_exp_f32_e32 v133, v133
	v_exp_f32_e32 v135, v135
	v_rcp_f32_e32 v150, v157
	v_rcp_f32_e32 v151, v159
	v_add_f32_e32 v133, 1.0, v133
	v_rcp_f32_e32 v133, v133
	v_add_f32_e32 v135, 1.0, v135
	v_rcp_f32_e32 v135, v135
	v_exp_f32_e32 v153, v153
	v_max_f32_e32 v133, 0x29e12e13, v133
	v_pk_mul_f32 v[132:133], v[148:149], v[132:133]
	v_mul_f32_e32 v149, 0xbfb8aa3b, v90
	v_exp_f32_e32 v149, v149
	v_max_f32_e32 v135, 0x29e12e13, v135
	v_pk_mul_f32 v[134:135], v[150:151], v[134:135]
	v_add_f32_e32 v153, 1.0, v153
	v_add_f32_e32 v149, 1.0, v149
	v_rcp_f32_e32 v149, v149
	v_rcp_f32_e32 v153, v153
	v_mul_f32_e32 v148, 0xbfb8aa3b, v94
	v_mul_f32_e32 v151, 0xbfb8aa3b, v91
	v_max_f32_e32 v150, 0x29e12e13, v149
	v_mul_f32_e32 v149, 0xbfb8aa3b, v86
	v_exp_f32_e32 v149, v149
	v_max_f32_e32 v166, 0x29e12e13, v153
	v_mul_f32_e32 v153, 0xbfb8aa3b, v83
	v_exp_f32_e32 v153, v153
	v_add_f32_e32 v149, 1.0, v149
	v_rcp_f32_e32 v149, v149
	v_exp_f32_e32 v148, v148
	v_exp_f32_e32 v151, v151
	v_add_f32_e32 v153, 1.0, v153
	v_max_f32_e32 v160, 0x29e12e13, v149
	v_mul_f32_e32 v149, 0xbfb8aa3b, v82
	v_exp_f32_e32 v149, v149
	v_rcp_f32_e32 v153, v153
	v_add_f32_e32 v148, 1.0, v148
	v_add_f32_e32 v151, 1.0, v151
	v_add_f32_e32 v149, 1.0, v149
	v_rcp_f32_e32 v149, v149
	v_rcp_f32_e32 v148, v148
	v_rcp_f32_e32 v151, v151
	v_max_f32_e32 v167, 0x29e12e13, v153
	v_max_f32_e32 v161, 0x29e12e13, v149
	v_mul_f32_e32 v149, 0xbfb8aa3b, v95
	v_exp_f32_e32 v149, v149
	v_rcp_f32_e32 v152, v160
	v_rcp_f32_e32 v154, v161
	v_rcp_f32_e32 v153, v166
	v_add_f32_e32 v149, 1.0, v149
	v_rcp_f32_e32 v149, v149
	v_rcp_f32_e32 v155, v167
	v_or_b32_e32 v147, 32, v146
	v_max_f32_e32 v148, 0x29e12e13, v148
	v_max_f32_e32 v149, 0x29e12e13, v149
	v_max_f32_e32 v151, 0x29e12e13, v151
	v_pk_mul_f32 v[148:149], v[152:153], v[148:149]
	v_pk_mul_f32 v[150:151], v[154:155], v[150:151]
	v_mad_i64_i32 v[152:153], s[6:7], v147, s33, v[128:129]
	v_cvt_pk_bf16_f32 v132, v132, v133
	v_cvt_pk_bf16_f32 v133, v148, v149
	v_cvt_pk_bf16_f32 v134, v134, v135
	v_cvt_pk_bf16_f32 v135, v150, v151
	v_lshl_add_u64 v[152:153], v[152:153], 0, v[130:131]
	v_cvt_pk_bf16_f32 v148, v156, v158
	v_cvt_pk_bf16_f32 v149, v160, v166
	v_cvt_pk_bf16_f32 v150, v157, v159
	v_cvt_pk_bf16_f32 v151, v161, v167
	global_store_dwordx4 v[152:153], v[132:135], off sc0 sc1 nt
	global_store_dwordx4 v[152:153], v[148:151], off offset:2048 sc0 sc1 nt
	v_mul_f32_e32 v153, 0xbfb8aa3b, v71
	v_mul_f32_e32 v133, 0xbfb8aa3b, v72
	v_exp_f32_e32 v133, v133
	v_mul_f32_e32 v149, 0xbfb8aa3b, v69
	v_exp_f32_e32 v149, v149
	v_mul_f32_e32 v132, 0xbfb8aa3b, v76
	v_add_f32_e32 v133, 1.0, v133
	v_rcp_f32_e32 v133, v133
	v_add_f32_e32 v149, 1.0, v149
	v_rcp_f32_e32 v149, v149
	v_exp_f32_e32 v132, v132
	v_max_f32_e32 v134, 0x29e12e13, v133
	v_mul_f32_e32 v133, 0xbfb8aa3b, v68
	v_exp_f32_e32 v133, v133
	v_max_f32_e32 v158, 0x29e12e13, v149
	v_mul_f32_e32 v149, 0xbfb8aa3b, v65
	v_exp_f32_e32 v149, v149
	v_add_f32_e32 v133, 1.0, v133
; __device__ __forceinline__ unsigned pk2(float lo, float hi) { f32v2 v = {lo, hi}; bf16v2 r = __builtin_convertvector(v, bf16v2); return __builtin_bit_cast(unsigned, r); }
; __device__ __forceinline__ float sigmoid_f(float x) { return __builtin_amdgcn_rcpf(1.0f + __builtin_amdgcn_exp2f(-1.4426950409f * x)); }
;     __device__ __forceinline__ void operator()(f32x4 (&acc)[2][2][4][2], const Unit& u, int wr, int wc, int fr, int fq) const {
;     ...
;                     for (int m = 0; m < 4; ++m) {
;                         const size_t row = (size_t)(row0 + ai * HALF + m * 16);
;                         float r[8], g[8];
; #pragma unroll
;                         for (int e = 0; e < 4; ++e) {
;                             const float g0a = fmaxf(sigmoid_f(acc[ai][0][m][0][e]), 1e-13f), g0b = fmaxf(sigmoid_f(acc[ai][0][m][1][e]), 1e-13f);
;                             const float g1a = fmaxf(sigmoid_f(acc[ai][1][m][0][e]), 1e-13f), g1b = fmaxf(sigmoid_f(acc[ai][1][m][1][e]), 1e-13f);
;                             g[e] = g1a; g[4 + e] = g1b; r[e] = g0a * __builtin_amdgcn_rcpf(g1a); r[4 + e] = g0b * __builtin_amdgcn_rcpf(g1b);
;                         }
;                         u32x4 wr_, wg_; wr_.x = pk2(r[0], r[1]); wr_.y = pk2(r[2], r[3]); wr_.z = pk2(r[4], r[5]); wr_.w = pk2(r[6], r[7]);
;                         wg_.x = pk2(g[0], g[1]); wg_.y = pk2(g[2], g[3]); wg_.z = pk2(g[4], g[5]); wg_.w = pk2(g[6], g[7]);
;                         __builtin_nontemporal_store(wr_, (u32x4*)(O4 + row * 3072 + chb));
;                         __builtin_nontemporal_store(wg_, (u32x4*)(O4 + row * 3072 + 1024 + chb));
	v_rcp_f32_e32 v133, v133
	v_add_f32_e32 v132, 1.0, v132
	v_add_f32_e32 v149, 1.0, v149
	v_rcp_f32_e32 v149, v149
	v_max_f32_e32 v156, 0x29e12e13, v133
	v_mul_f32_e32 v133, 0xbfb8aa3b, v64
	v_exp_f32_e32 v133, v133
	v_rcp_f32_e32 v132, v132
	v_rcp_f32_e32 v148, v156
	v_max_f32_e32 v159, 0x29e12e13, v149
	v_add_f32_e32 v133, 1.0, v133
	v_rcp_f32_e32 v133, v133
	v_rcp_f32_e32 v149, v158
	v_max_f32_e32 v132, 0x29e12e13, v132
	v_mul_f32_e32 v135, 0xbfb8aa3b, v73
	v_max_f32_e32 v157, 0x29e12e13, v133
	v_mul_f32_e32 v133, 0xbfb8aa3b, v77
	v_exp_f32_e32 v133, v133
	v_exp_f32_e32 v135, v135
	v_rcp_f32_e32 v150, v157
	v_rcp_f32_e32 v151, v159
	v_add_f32_e32 v133, 1.0, v133
	v_rcp_f32_e32 v133, v133
	v_add_f32_e32 v135, 1.0, v135
	v_rcp_f32_e32 v135, v135
	v_exp_f32_e32 v153, v153
	v_max_f32_e32 v133, 0x29e12e13, v133
	v_pk_mul_f32 v[132:133], v[148:149], v[132:133]
	v_mul_f32_e32 v149, 0xbfb8aa3b, v74
	v_exp_f32_e32 v149, v149
	v_max_f32_e32 v135, 0x29e12e13, v135
	v_pk_mul_f32 v[134:135], v[150:151], v[134:135]
	v_add_f32_e32 v153, 1.0, v153
	v_add_f32_e32 v149, 1.0, v149
	v_rcp_f32_e32 v149, v149
	v_rcp_f32_e32 v153, v153
	v_mul_f32_e32 v148, 0xbfb8aa3b, v78
	v_mul_f32_e32 v151, 0xbfb8aa3b, v75
	v_max_f32_e32 v150, 0x29e12e13, v149
	v_mul_f32_e32 v149, 0xbfb8aa3b, v70
	v_exp_f32_e32 v149, v149
	v_max_f32_e32 v166, 0x29e12e13, v153
	v_mul_f32_e32 v153, 0xbfb8aa3b, v67
	v_exp_f32_e32 v153, v153
	v_add_f32_e32 v149, 1.0, v149
	v_rcp_f32_e32 v149, v149
	v_exp_f32_e32 v148, v148
	v_exp_f32_e32 v151, v151
	v_add_f32_e32 v153, 1.0, v153
	v_max_f32_e32 v160, 0x29e12e13, v149
	v_mul_f32_e32 v149, 0xbfb8aa3b, v66
	v_exp_f32_e32 v149, v149
	v_rcp_f32_e32 v153, v153
	v_add_f32_e32 v148, 1.0, v148
	v_add_f32_e32 v151, 1.0, v151
	v_add_f32_e32 v149, 1.0, v149
	v_rcp_f32_e32 v149, v149
	v_rcp_f32_e32 v148, v148
	v_rcp_f32_e32 v151, v151
	v_max_f32_e32 v167, 0x29e12e13, v153
	v_max_f32_e32 v161, 0x29e12e13, v149
	v_mul_f32_e32 v149, 0xbfb8aa3b, v79
	v_exp_f32_e32 v149, v149
	v_rcp_f32_e32 v152, v160
	v_rcp_f32_e32 v154, v161
	v_rcp_f32_e32 v153, v166
	v_add_f32_e32 v149, 1.0, v149
	v_rcp_f32_e32 v149, v149
	v_rcp_f32_e32 v155, v167
	v_or_b32_e32 v147, 48, v146
	v_max_f32_e32 v148, 0x29e12e13, v148
	v_max_f32_e32 v149, 0x29e12e13, v149
	v_max_f32_e32 v151, 0x29e12e13, v151
	v_pk_mul_f32 v[148:149], v[152:153], v[148:149]
	v_pk_mul_f32 v[150:151], v[154:155], v[150:151]
	v_mad_i64_i32 v[152:153], s[6:7], v147, s33, v[128:129]
	v_cvt_pk_bf16_f32 v132, v132, v133
	v_cvt_pk_bf16_f32 v133, v148, v149
	v_cvt_pk_bf16_f32 v134, v134, v135
	v_cvt_pk_bf16_f32 v135, v150, v151
	v_lshl_add_u64 v[152:153], v[152:153], 0, v[130:131]
	v_cvt_pk_bf16_f32 v148, v156, v158
	v_cvt_pk_bf16_f32 v149, v160, v166
	v_cvt_pk_bf16_f32 v150, v157, v159
	v_cvt_pk_bf16_f32 v151, v161, v167
	global_store_dwordx4 v[152:153], v[132:135], off sc0 sc1 nt
	global_store_dwordx4 v[152:153], v[148:151], off offset:2048 sc0 sc1 nt
	v_mul_f32_e32 v153, 0xbfb8aa3b, v55
	v_mul_f32_e32 v133, 0xbfb8aa3b, v56
	v_exp_f32_e32 v133, v133
	v_mul_f32_e32 v149, 0xbfb8aa3b, v53
	v_exp_f32_e32 v149, v149
	v_mul_f32_e32 v132, 0xbfb8aa3b, v60
	v_add_f32_e32 v133, 1.0, v133
	v_rcp_f32_e32 v133, v133
	v_add_f32_e32 v149, 1.0, v149
	v_rcp_f32_e32 v149, v149
	v_exp_f32_e32 v132, v132
	v_max_f32_e32 v134, 0x29e12e13, v133
	v_mul_f32_e32 v133, 0xbfb8aa3b, v52
	v_exp_f32_e32 v133, v133
	v_max_f32_e32 v158, 0x29e12e13, v149
	v_mul_f32_e32 v149, 0xbfb8aa3b, v49
	v_exp_f32_e32 v149, v149
	v_add_f32_e32 v133, 1.0, v133
	v_rcp_f32_e32 v133, v133
	v_add_f32_e32 v132, 1.0, v132
	v_add_f32_e32 v149, 1.0, v149
	v_rcp_f32_e32 v149, v149
	v_max_f32_e32 v156, 0x29e12e13, v133
	v_mul_f32_e32 v133, 0xbfb8aa3b, v48
	v_exp_f32_e32 v133, v133
	v_rcp_f32_e32 v132, v132
	v_rcp_f32_e32 v148, v156
	v_max_f32_e32 v159, 0x29e12e13, v149
	v_add_f32_e32 v133, 1.0, v133
	v_rcp_f32_e32 v133, v133
	v_rcp_f32_e32 v149, v158
	v_max_f32_e32 v132, 0x29e12e13, v132
	v_mul_f32_e32 v135, 0xbfb8aa3b, v57
	v_max_f32_e32 v157, 0x29e12e13, v133
	v_mul_f32_e32 v133, 0xbfb8aa3b, v61
	v_exp_f32_e32 v133, v133
	v_exp_f32_e32 v135, v135
	v_rcp_f32_e32 v150, v157
	v_rcp_f32_e32 v151, v159
	v_add_f32_e32 v133, 1.0, v133
	v_rcp_f32_e32 v133, v133
	v_add_f32_e32 v135, 1.0, v135
	v_rcp_f32_e32 v135, v135
	v_exp_f32_e32 v153, v153
	v_max_f32_e32 v133, 0x29e12e13, v133
	v_pk_mul_f32 v[132:133], v[148:149], v[132:133]
	v_mul_f32_e32 v149, 0xbfb8aa3b, v58
	v_exp_f32_e32 v149, v149
	v_max_f32_e32 v135, 0x29e12e13, v135
	v_pk_mul_f32 v[134:135], v[150:151], v[134:135]
	v_add_f32_e32 v153, 1.0, v153
	v_add_f32_e32 v149, 1.0, v149
	v_rcp_f32_e32 v149, v149
	v_rcp_f32_e32 v153, v153
	v_mul_f32_e32 v148, 0xbfb8aa3b, v62
	v_mul_f32_e32 v151, 0xbfb8aa3b, v59
	v_max_f32_e32 v150, 0x29e12e13, v149
	v_mul_f32_e32 v149, 0xbfb8aa3b, v54
	v_exp_f32_e32 v149, v149
	v_max_f32_e32 v166, 0x29e12e13, v153
	v_mul_f32_e32 v153, 0xbfb8aa3b, v51
	v_exp_f32_e32 v153, v153
	v_add_f32_e32 v149, 1.0, v149
	v_rcp_f32_e32 v149, v149
	v_exp_f32_e32 v148, v148
	v_exp_f32_e32 v151, v151
	v_add_f32_e32 v153, 1.0, v153
	v_max_f32_e32 v160, 0x29e12e13, v149
	v_mul_f32_e32 v149, 0xbfb8aa3b, v50
	v_exp_f32_e32 v149, v149
	v_rcp_f32_e32 v153, v153
	v_add_f32_e32 v148, 1.0, v148
	v_add_f32_e32 v151, 1.0, v151
	v_add_f32_e32 v149, 1.0, v149
	v_rcp_f32_e32 v149, v149
	v_rcp_f32_e32 v148, v148
	v_rcp_f32_e32 v151, v151
	v_max_f32_e32 v167, 0x29e12e13, v153
	v_max_f32_e32 v161, 0x29e12e13, v149
	v_mul_f32_e32 v149, 0xbfb8aa3b, v63
	v_exp_f32_e32 v149, v149
	v_rcp_f32_e32 v152, v160
	v_rcp_f32_e32 v154, v161
	v_rcp_f32_e32 v153, v166
	v_add_f32_e32 v149, 1.0, v149
	v_rcp_f32_e32 v149, v149
	v_rcp_f32_e32 v155, v167
; __device__ __forceinline__ unsigned pk2(float lo, float hi) { f32v2 v = {lo, hi}; bf16v2 r = __builtin_convertvector(v, bf16v2); return __builtin_bit_cast(unsigned, r); }
; __device__ __forceinline__ float sigmoid_f(float x) { return __builtin_amdgcn_rcpf(1.0f + __builtin_amdgcn_exp2f(-1.4426950409f * x)); }
;     __device__ __forceinline__ void operator()(f32x4 (&acc)[2][2][4][2], const Unit& u, int wr, int wc, int fr, int fq) const {
;     ...
;                     for (int m = 0; m < 4; ++m) {
;                         const size_t row = (size_t)(row0 + ai * HALF + m * 16);
;                         float r[8], g[8];
; #pragma unroll
;                         for (int e = 0; e < 4; ++e) {
;                             const float g0a = fmaxf(sigmoid_f(acc[ai][0][m][0][e]), 1e-13f), g0b = fmaxf(sigmoid_f(acc[ai][0][m][1][e]), 1e-13f);
;                             const float g1a = fmaxf(sigmoid_f(acc[ai][1][m][0][e]), 1e-13f), g1b = fmaxf(sigmoid_f(acc[ai][1][m][1][e]), 1e-13f);
;                             g[e] = g1a; g[4 + e] = g1b; r[e] = g0a * __builtin_amdgcn_rcpf(g1a); r[4 + e] = g0b * __builtin_amdgcn_rcpf(g1b);
;                         }
;                         u32x4 wr_, wg_; wr_.x = pk2(r[0], r[1]); wr_.y = pk2(r[2], r[3]); wr_.z = pk2(r[4], r[5]); wr_.w = pk2(r[6], r[7]);
;                         wg_.x = pk2(g[0], g[1]); wg_.y = pk2(g[2], g[3]); wg_.z = pk2(g[4], g[5]); wg_.w = pk2(g[6], g[7]);
;                         __builtin_nontemporal_store(wr_, (u32x4*)(O4 + row * 3072 + chb));
;                         __builtin_nontemporal_store(wg_, (u32x4*)(O4 + row * 3072 + 1024 + chb));
	v_add_u32_e32 v147, 0x80, v146
	v_max_f32_e32 v148, 0x29e12e13, v148
	v_max_f32_e32 v149, 0x29e12e13, v149
	v_max_f32_e32 v151, 0x29e12e13, v151
	v_pk_mul_f32 v[148:149], v[152:153], v[148:149]
	v_pk_mul_f32 v[150:151], v[154:155], v[150:151]
	v_mad_i64_i32 v[152:153], s[6:7], v147, s33, v[128:129]
	v_cvt_pk_bf16_f32 v132, v132, v133
	v_cvt_pk_bf16_f32 v133, v148, v149
	v_cvt_pk_bf16_f32 v134, v134, v135
	v_cvt_pk_bf16_f32 v135, v150, v151
	v_lshl_add_u64 v[152:153], v[152:153], 0, v[130:131]
	v_cvt_pk_bf16_f32 v148, v156, v158
	v_cvt_pk_bf16_f32 v149, v160, v166
	v_cvt_pk_bf16_f32 v150, v157, v159
	v_cvt_pk_bf16_f32 v151, v161, v167
	global_store_dwordx4 v[152:153], v[132:135], off sc0 sc1 nt
	global_store_dwordx4 v[152:153], v[148:151], off offset:2048 sc0 sc1 nt
	v_mul_f32_e32 v153, 0xbfb8aa3b, v39
	v_mul_f32_e32 v133, 0xbfb8aa3b, v40
	v_exp_f32_e32 v133, v133
	v_mul_f32_e32 v149, 0xbfb8aa3b, v37
	v_exp_f32_e32 v149, v149
	v_mul_f32_e32 v132, 0xbfb8aa3b, v44
	v_add_f32_e32 v133, 1.0, v133
	v_rcp_f32_e32 v133, v133
	v_add_f32_e32 v149, 1.0, v149
	v_rcp_f32_e32 v149, v149
	v_exp_f32_e32 v132, v132
	v_max_f32_e32 v134, 0x29e12e13, v133
	v_mul_f32_e32 v133, 0xbfb8aa3b, v36
	v_exp_f32_e32 v133, v133
	v_max_f32_e32 v158, 0x29e12e13, v149
	v_mul_f32_e32 v149, 0xbfb8aa3b, v33
	v_exp_f32_e32 v149, v149
	v_add_f32_e32 v133, 1.0, v133
	v_rcp_f32_e32 v133, v133
	v_add_f32_e32 v132, 1.0, v132
	v_add_f32_e32 v149, 1.0, v149
	v_rcp_f32_e32 v149, v149
	v_max_f32_e32 v156, 0x29e12e13, v133
	v_mul_f32_e32 v133, 0xbfb8aa3b, v32
	v_exp_f32_e32 v133, v133
	v_rcp_f32_e32 v132, v132
	v_rcp_f32_e32 v148, v156
	v_max_f32_e32 v159, 0x29e12e13, v149
	v_add_f32_e32 v133, 1.0, v133
	v_rcp_f32_e32 v133, v133
	v_rcp_f32_e32 v149, v158
	v_max_f32_e32 v132, 0x29e12e13, v132
	v_mul_f32_e32 v135, 0xbfb8aa3b, v41
	v_max_f32_e32 v157, 0x29e12e13, v133
	v_mul_f32_e32 v133, 0xbfb8aa3b, v45
	v_exp_f32_e32 v133, v133
	v_exp_f32_e32 v135, v135
	v_rcp_f32_e32 v150, v157
	v_rcp_f32_e32 v151, v159
	v_add_f32_e32 v133, 1.0, v133
	v_rcp_f32_e32 v133, v133
	v_add_f32_e32 v135, 1.0, v135
	v_rcp_f32_e32 v135, v135
	v_exp_f32_e32 v153, v153
	v_max_f32_e32 v133, 0x29e12e13, v133
	v_pk_mul_f32 v[132:133], v[148:149], v[132:133]
	v_mul_f32_e32 v149, 0xbfb8aa3b, v42
	v_exp_f32_e32 v149, v149
	v_max_f32_e32 v135, 0x29e12e13, v135
	v_pk_mul_f32 v[134:135], v[150:151], v[134:135]
	v_add_f32_e32 v153, 1.0, v153
	v_add_f32_e32 v149, 1.0, v149
	v_rcp_f32_e32 v149, v149
	v_rcp_f32_e32 v153, v153
	v_mul_f32_e32 v148, 0xbfb8aa3b, v46
	v_mul_f32_e32 v151, 0xbfb8aa3b, v43
	v_max_f32_e32 v150, 0x29e12e13, v149
	v_mul_f32_e32 v149, 0xbfb8aa3b, v38
	v_exp_f32_e32 v149, v149
	v_max_f32_e32 v166, 0x29e12e13, v153
	v_mul_f32_e32 v153, 0xbfb8aa3b, v35
	v_exp_f32_e32 v153, v153
	v_add_f32_e32 v149, 1.0, v149
	v_rcp_f32_e32 v149, v149
	v_exp_f32_e32 v148, v148
	v_exp_f32_e32 v151, v151
	v_add_f32_e32 v153, 1.0, v153
	v_max_f32_e32 v160, 0x29e12e13, v149
	v_mul_f32_e32 v149, 0xbfb8aa3b, v34
	v_exp_f32_e32 v149, v149
	v_rcp_f32_e32 v153, v153
	v_add_f32_e32 v148, 1.0, v148
	v_add_f32_e32 v151, 1.0, v151
	v_add_f32_e32 v149, 1.0, v149
	v_rcp_f32_e32 v149, v149
	v_rcp_f32_e32 v148, v148
	v_rcp_f32_e32 v151, v151
	v_max_f32_e32 v167, 0x29e12e13, v153
	v_max_f32_e32 v161, 0x29e12e13, v149
	v_mul_f32_e32 v149, 0xbfb8aa3b, v47
	v_exp_f32_e32 v149, v149
	v_rcp_f32_e32 v152, v160
	v_rcp_f32_e32 v154, v161
	v_rcp_f32_e32 v153, v166
	v_add_f32_e32 v149, 1.0, v149
	v_rcp_f32_e32 v149, v149
	v_rcp_f32_e32 v155, v167
	v_add_u32_e32 v147, 0x90, v146
	v_max_f32_e32 v148, 0x29e12e13, v148
	v_max_f32_e32 v149, 0x29e12e13, v149
	v_max_f32_e32 v151, 0x29e12e13, v151
	v_pk_mul_f32 v[148:149], v[152:153], v[148:149]
	v_pk_mul_f32 v[150:151], v[154:155], v[150:151]
	v_mad_i64_i32 v[152:153], s[6:7], v147, s33, v[128:129]
	v_cvt_pk_bf16_f32 v132, v132, v133
	v_cvt_pk_bf16_f32 v133, v148, v149
	v_cvt_pk_bf16_f32 v134, v134, v135
	v_cvt_pk_bf16_f32 v135, v150, v151
	v_lshl_add_u64 v[152:153], v[152:153], 0, v[130:131]
	v_cvt_pk_bf16_f32 v148, v156, v158
	v_cvt_pk_bf16_f32 v149, v160, v166
	v_cvt_pk_bf16_f32 v150, v157, v159
	v_cvt_pk_bf16_f32 v151, v161, v167
	global_store_dwordx4 v[152:153], v[132:135], off sc0 sc1 nt
	global_store_dwordx4 v[152:153], v[148:151], off offset:2048 sc0 sc1 nt
	v_mul_f32_e32 v153, 0xbfb8aa3b, v23
	v_mul_f32_e32 v133, 0xbfb8aa3b, v24
	v_exp_f32_e32 v133, v133
	v_mul_f32_e32 v149, 0xbfb8aa3b, v21
	v_exp_f32_e32 v149, v149
	v_mul_f32_e32 v132, 0xbfb8aa3b, v28
	v_add_f32_e32 v133, 1.0, v133
	v_rcp_f32_e32 v133, v133
	v_add_f32_e32 v149, 1.0, v149
	v_rcp_f32_e32 v149, v149
	v_exp_f32_e32 v132, v132
	v_max_f32_e32 v134, 0x29e12e13, v133
	v_mul_f32_e32 v133, 0xbfb8aa3b, v20
	v_exp_f32_e32 v133, v133
	v_max_f32_e32 v158, 0x29e12e13, v149
	v_mul_f32_e32 v149, 0xbfb8aa3b, v17
	v_exp_f32_e32 v149, v149
	v_add_f32_e32 v133, 1.0, v133
	v_rcp_f32_e32 v133, v133
	v_add_f32_e32 v132, 1.0, v132
	v_add_f32_e32 v149, 1.0, v149
	v_rcp_f32_e32 v149, v149
	v_max_f32_e32 v156, 0x29e12e13, v133
	v_mul_f32_e32 v133, 0xbfb8aa3b, v16
	v_exp_f32_e32 v133, v133
	v_rcp_f32_e32 v132, v132
	v_rcp_f32_e32 v148, v156
	v_max_f32_e32 v159, 0x29e12e13, v149
	v_add_f32_e32 v133, 1.0, v133
	v_rcp_f32_e32 v133, v133
	v_rcp_f32_e32 v149, v158
	v_max_f32_e32 v132, 0x29e12e13, v132
	v_mul_f32_e32 v135, 0xbfb8aa3b, v25
	v_max_f32_e32 v157, 0x29e12e13, v133
	v_mul_f32_e32 v133, 0xbfb8aa3b, v29
	v_exp_f32_e32 v133, v133
	v_exp_f32_e32 v135, v135
	v_rcp_f32_e32 v150, v157
	v_rcp_f32_e32 v151, v159
	v_add_f32_e32 v133, 1.0, v133
	v_rcp_f32_e32 v133, v133
	v_add_f32_e32 v135, 1.0, v135
	v_rcp_f32_e32 v135, v135
	v_exp_f32_e32 v153, v153
; __device__ __forceinline__ unsigned pk2(float lo, float hi) { f32v2 v = {lo, hi}; bf16v2 r = __builtin_convertvector(v, bf16v2); return __builtin_bit_cast(unsigned, r); }
; __device__ __forceinline__ float sigmoid_f(float x) { return __builtin_amdgcn_rcpf(1.0f + __builtin_amdgcn_exp2f(-1.4426950409f * x)); }
;     __device__ __forceinline__ void operator()(f32x4 (&acc)[2][2][4][2], const Unit& u, int wr, int wc, int fr, int fq) const {
;     ...
;                     for (int m = 0; m < 4; ++m) {
;                         const size_t row = (size_t)(row0 + ai * HALF + m * 16);
;                         float r[8], g[8];
; #pragma unroll
;                         for (int e = 0; e < 4; ++e) {
;                             const float g0a = fmaxf(sigmoid_f(acc[ai][0][m][0][e]), 1e-13f), g0b = fmaxf(sigmoid_f(acc[ai][0][m][1][e]), 1e-13f);
;                             const float g1a = fmaxf(sigmoid_f(acc[ai][1][m][0][e]), 1e-13f), g1b = fmaxf(sigmoid_f(acc[ai][1][m][1][e]), 1e-13f);
;                             g[e] = g1a; g[4 + e] = g1b; r[e] = g0a * __builtin_amdgcn_rcpf(g1a); r[4 + e] = g0b * __builtin_amdgcn_rcpf(g1b);
;                         }
;                         u32x4 wr_, wg_; wr_.x = pk2(r[0], r[1]); wr_.y = pk2(r[2], r[3]); wr_.z = pk2(r[4], r[5]); wr_.w = pk2(r[6], r[7]);
;                         wg_.x = pk2(g[0], g[1]); wg_.y = pk2(g[2], g[3]); wg_.z = pk2(g[4], g[5]); wg_.w = pk2(g[6], g[7]);
;                         __builtin_nontemporal_store(wr_, (u32x4*)(O4 + row * 3072 + chb));
;                         __builtin_nontemporal_store(wg_, (u32x4*)(O4 + row * 3072 + 1024 + chb));
	v_max_f32_e32 v133, 0x29e12e13, v133
	v_pk_mul_f32 v[132:133], v[148:149], v[132:133]
	v_mul_f32_e32 v149, 0xbfb8aa3b, v26
	v_exp_f32_e32 v149, v149
	v_max_f32_e32 v135, 0x29e12e13, v135
	v_pk_mul_f32 v[134:135], v[150:151], v[134:135]
	v_add_f32_e32 v153, 1.0, v153
	v_add_f32_e32 v149, 1.0, v149
	v_rcp_f32_e32 v149, v149
	v_rcp_f32_e32 v153, v153
	v_mul_f32_e32 v148, 0xbfb8aa3b, v30
	v_mul_f32_e32 v151, 0xbfb8aa3b, v27
	v_max_f32_e32 v150, 0x29e12e13, v149
	v_mul_f32_e32 v149, 0xbfb8aa3b, v22
	v_exp_f32_e32 v149, v149
	v_max_f32_e32 v166, 0x29e12e13, v153
	v_mul_f32_e32 v153, 0xbfb8aa3b, v19
	v_exp_f32_e32 v153, v153
	v_add_f32_e32 v149, 1.0, v149
	v_rcp_f32_e32 v149, v149
	v_exp_f32_e32 v148, v148
	v_exp_f32_e32 v151, v151
	v_add_f32_e32 v153, 1.0, v153
	v_max_f32_e32 v160, 0x29e12e13, v149
	v_mul_f32_e32 v149, 0xbfb8aa3b, v18
	v_exp_f32_e32 v149, v149
	v_rcp_f32_e32 v153, v153
	v_add_f32_e32 v148, 1.0, v148
	v_add_f32_e32 v151, 1.0, v151
	v_add_f32_e32 v149, 1.0, v149
	v_rcp_f32_e32 v149, v149
	v_rcp_f32_e32 v148, v148
	v_rcp_f32_e32 v151, v151
	v_max_f32_e32 v167, 0x29e12e13, v153
	v_max_f32_e32 v161, 0x29e12e13, v149
	v_mul_f32_e32 v149, 0xbfb8aa3b, v31
	v_exp_f32_e32 v149, v149
	v_rcp_f32_e32 v152, v160
	v_rcp_f32_e32 v154, v161
	v_rcp_f32_e32 v153, v166
	v_add_f32_e32 v149, 1.0, v149
	v_rcp_f32_e32 v149, v149
	v_rcp_f32_e32 v155, v167
	v_add_u32_e32 v147, 0xa0, v146
	v_max_f32_e32 v148, 0x29e12e13, v148
	v_max_f32_e32 v149, 0x29e12e13, v149
	v_max_f32_e32 v151, 0x29e12e13, v151
	v_pk_mul_f32 v[148:149], v[152:153], v[148:149]
	v_pk_mul_f32 v[150:151], v[154:155], v[150:151]
	v_mad_i64_i32 v[152:153], s[6:7], v147, s33, v[128:129]
	v_cvt_pk_bf16_f32 v132, v132, v133
	v_cvt_pk_bf16_f32 v133, v148, v149
	v_cvt_pk_bf16_f32 v134, v134, v135
	v_cvt_pk_bf16_f32 v135, v150, v151
	v_lshl_add_u64 v[152:153], v[152:153], 0, v[130:131]
	v_cvt_pk_bf16_f32 v148, v156, v158
	v_cvt_pk_bf16_f32 v149, v160, v166
	v_cvt_pk_bf16_f32 v150, v157, v159
	v_cvt_pk_bf16_f32 v151, v161, v167
	global_store_dwordx4 v[152:153], v[132:135], off sc0 sc1 nt
	global_store_dwordx4 v[152:153], v[148:151], off offset:2048 sc0 sc1 nt
	v_mul_f32_e32 v153, 0xbfb8aa3b, v7
	v_mul_f32_e32 v133, 0xbfb8aa3b, v8
	v_exp_f32_e32 v133, v133
	v_mul_f32_e32 v149, 0xbfb8aa3b, v5
	v_exp_f32_e32 v149, v149
	v_mul_f32_e32 v132, 0xbfb8aa3b, v12
	v_add_f32_e32 v133, 1.0, v133
	v_rcp_f32_e32 v133, v133
	v_add_f32_e32 v149, 1.0, v149
	v_rcp_f32_e32 v149, v149
	v_exp_f32_e32 v132, v132
	v_max_f32_e32 v134, 0x29e12e13, v133
	v_mul_f32_e32 v133, 0xbfb8aa3b, v4
	v_exp_f32_e32 v133, v133
	v_max_f32_e32 v158, 0x29e12e13, v149
	v_mul_f32_e32 v149, 0xbfb8aa3b, v1
	v_exp_f32_e32 v149, v149
	v_add_f32_e32 v133, 1.0, v133
	v_rcp_f32_e32 v133, v133
	v_add_f32_e32 v132, 1.0, v132
	v_add_f32_e32 v149, 1.0, v149
	v_rcp_f32_e32 v149, v149
	v_max_f32_e32 v156, 0x29e12e13, v133
	v_mul_f32_e32 v133, 0xbfb8aa3b, v0
	v_exp_f32_e32 v133, v133
	v_rcp_f32_e32 v132, v132
	v_rcp_f32_e32 v148, v156
	v_max_f32_e32 v159, 0x29e12e13, v149
	v_add_f32_e32 v133, 1.0, v133
	v_rcp_f32_e32 v133, v133
	v_rcp_f32_e32 v149, v158
	v_max_f32_e32 v132, 0x29e12e13, v132
	v_mul_f32_e32 v135, 0xbfb8aa3b, v9
	v_max_f32_e32 v157, 0x29e12e13, v133
	v_mul_f32_e32 v133, 0xbfb8aa3b, v13
	v_exp_f32_e32 v133, v133
	v_exp_f32_e32 v135, v135
	v_rcp_f32_e32 v150, v157
	v_rcp_f32_e32 v151, v159
	v_add_f32_e32 v133, 1.0, v133
	v_rcp_f32_e32 v133, v133
	v_add_f32_e32 v135, 1.0, v135
	v_rcp_f32_e32 v135, v135
	v_exp_f32_e32 v153, v153
	v_max_f32_e32 v133, 0x29e12e13, v133
	v_pk_mul_f32 v[132:133], v[148:149], v[132:133]
	v_mul_f32_e32 v149, 0xbfb8aa3b, v10
	v_exp_f32_e32 v149, v149
	v_max_f32_e32 v135, 0x29e12e13, v135
	v_pk_mul_f32 v[134:135], v[150:151], v[134:135]
	v_add_f32_e32 v153, 1.0, v153
	v_add_f32_e32 v149, 1.0, v149
	v_rcp_f32_e32 v149, v149
	v_rcp_f32_e32 v153, v153
	v_mul_f32_e32 v148, 0xbfb8aa3b, v14
	v_mul_f32_e32 v151, 0xbfb8aa3b, v11
	v_max_f32_e32 v150, 0x29e12e13, v149
	v_mul_f32_e32 v149, 0xbfb8aa3b, v6
	v_exp_f32_e32 v149, v149
	v_max_f32_e32 v166, 0x29e12e13, v153
	v_mul_f32_e32 v153, 0xbfb8aa3b, v3
	v_exp_f32_e32 v153, v153
	v_add_f32_e32 v149, 1.0, v149
	v_rcp_f32_e32 v149, v149
	v_exp_f32_e32 v148, v148
	v_exp_f32_e32 v151, v151
	v_add_f32_e32 v153, 1.0, v153
	v_max_f32_e32 v160, 0x29e12e13, v149
	v_mul_f32_e32 v149, 0xbfb8aa3b, v2
	v_exp_f32_e32 v149, v149
	v_rcp_f32_e32 v153, v153
	v_add_f32_e32 v148, 1.0, v148
	v_add_f32_e32 v151, 1.0, v151
	v_add_f32_e32 v149, 1.0, v149
	v_rcp_f32_e32 v149, v149
	v_rcp_f32_e32 v148, v148
	v_rcp_f32_e32 v151, v151
	v_max_f32_e32 v167, 0x29e12e13, v153
	v_max_f32_e32 v161, 0x29e12e13, v149
	v_mul_f32_e32 v149, 0xbfb8aa3b, v15
	v_exp_f32_e32 v149, v149
	v_rcp_f32_e32 v152, v160
	v_rcp_f32_e32 v154, v161
	v_rcp_f32_e32 v153, v166
	v_add_f32_e32 v149, 1.0, v149
	v_rcp_f32_e32 v149, v149
	v_rcp_f32_e32 v155, v167
	v_add_u32_e32 v147, 0xb0, v146
	v_max_f32_e32 v148, 0x29e12e13, v148
	v_max_f32_e32 v149, 0x29e12e13, v149
	v_max_f32_e32 v151, 0x29e12e13, v151
	v_pk_mul_f32 v[148:149], v[152:153], v[148:149]
	v_pk_mul_f32 v[150:151], v[154:155], v[150:151]
	v_mad_i64_i32 v[128:129], s[6:7], v147, s33, v[128:129]
	v_cvt_pk_bf16_f32 v132, v132, v133
	v_cvt_pk_bf16_f32 v133, v148, v149
	v_cvt_pk_bf16_f32 v134, v134, v135
	v_cvt_pk_bf16_f32 v135, v150, v151
	v_lshl_add_u64 v[128:129], v[128:129], 0, v[130:131]
	v_cvt_pk_bf16_f32 v148, v156, v158
	v_cvt_pk_bf16_f32 v149, v160, v166
	v_cvt_pk_bf16_f32 v150, v157, v159
	v_cvt_pk_bf16_f32 v151, v161, v167
	global_store_dwordx4 v[128:129], v[132:135], off sc0 sc1 nt
	global_store_dwordx4 v[128:129], v[148:151], off offset:2048 sc0 sc1 nt

; __device__ __forceinline__ unsigned pk2(float lo, float hi) { f32v2 v = {lo, hi}; bf16v2 r = __builtin_convertvector(v, bf16v2); return __builtin_bit_cast(unsigned, r); }
;     __device__ __forceinline__ void operator()(f32x4 (&acc)[2][2][4][2], const Unit& u, int wr, int wc, int fr, int fq) const {
;     ...
; #pragma unroll
;         for (int ai = 0; ai < 2; ++ai)
; #pragma unroll
;             for (int m = 0; m < 4; ++m) {
;                 const size_t row = (size_t)(row0 + ai * HALF + m * 16);
; #pragma unroll
;                 for (int bj = 0; bj < 2; ++bj) {
;                     f32x4 v0 = acc[ai][bj][m][0], v1 = acc[ai][bj][m][1];
;                     const int cl = cl0 + bj * HALF;
;                     if constexpr (MODE == 0 || MODE == 1) {
;                         if (MODE == 1) {
; #pragma unroll
;                             for (int e = 0; e < 4; ++e) { const float a = fmaxf(v0[e], 0.f), b = fmaxf(v1[e], 0.f); v0[e] = a * a; v1[e] = b * b; }
;                         }
;                         u32x4 w; w.x = pk2(v0[0], v0[1]); w.y = pk2(v0[2], v0[3]); w.z = pk2(v1[0], v1[1]); w.w = pk2(v1[2], v1[3]);
;                         if constexpr (MODE == 1) __builtin_nontemporal_store(w, (u32x4*)(O + row * ldc + u.pn * BM + cl));
.LBB0_561:
	s_andn2_b64 vcc, exec, s[6:7]
	s_cbranch_vccnz .LBB0_563
	v_ashrrev_i32_e32 v147, 31, v146
	v_max_f32_e32 v131, v120, v120
	v_max_f32_e32 v135, v122, v122
	s_lshl_b32 s6, s70, 8
	v_lshlrev_b64 v[128:129], 13, v[146:147]
	v_max_f32_e32 v130, v124, v124
	v_max_f32_e32 v132, 0, v131
	v_max_f32_e32 v131, v125, v125
	v_max_f32_e32 v133, v121, v121
	v_max_f32_e32 v134, v126, v126
	v_max_f32_e32 v148, 0, v135
	v_max_f32_e32 v135, v127, v127
	v_max_f32_e32 v147, v123, v123
	s_ashr_i32 s7, s6, 31
	v_lshl_add_u64 v[128:129], s[92:93], 0, v[128:129]
	v_max_f32_e32 v130, 0, v130
	v_max_f32_e32 v131, 0, v131
	v_max_f32_e32 v133, 0, v133
	v_max_f32_e32 v134, 0, v134
	v_max_f32_e32 v135, 0, v135
	v_max_f32_e32 v149, 0, v147
	s_lshl_b64 s[6:7], s[6:7], 1
	v_pk_mul_f32 v[130:131], v[130:131], v[130:131]
	v_pk_mul_f32 v[132:133], v[132:133], v[132:133]
	v_pk_mul_f32 v[134:135], v[134:135], v[134:135]
	v_pk_mul_f32 v[148:149], v[148:149], v[148:149]
	v_lshl_add_u64 v[128:129], v[128:129], 0, s[6:7]
	v_lshlrev_b32_e32 v178, 1, v138
	v_cvt_pk_bf16_f32 v130, v130, v131
	v_cvt_pk_bf16_f32 v131, v134, v135
	v_cvt_pk_bf16_f32 v132, v132, v133
	v_cvt_pk_bf16_f32 v133, v148, v149
	v_lshl_add_u64 v[128:129], v[128:129], 0, v[178:179]
	global_store_dwordx4 v[128:129], v[130:133], off sc0 sc1 nt
	v_max_f32_e32 v135, v114, v114
	v_max_f32_e32 v134, v118, v118
	v_max_f32_e32 v131, v112, v112
	v_max_f32_e32 v130, v116, v116
	v_max_f32_e32 v132, 0, v131
	v_max_f32_e32 v131, v117, v117
	v_max_f32_e32 v133, v113, v113
	v_max_f32_e32 v148, 0, v135
	v_max_f32_e32 v135, v119, v119
	v_max_f32_e32 v147, v115, v115
	v_max_f32_e32 v130, 0, v130
	v_max_f32_e32 v131, 0, v131
	v_max_f32_e32 v133, 0, v133
	v_max_f32_e32 v134, 0, v134
	v_max_f32_e32 v135, 0, v135
	v_max_f32_e32 v149, 0, v147
	v_pk_mul_f32 v[130:131], v[130:131], v[130:131]
	v_pk_mul_f32 v[132:133], v[132:133], v[132:133]
	v_pk_mul_f32 v[134:135], v[134:135], v[134:135]
	v_pk_mul_f32 v[148:149], v[148:149], v[148:149]
	v_cvt_pk_bf16_f32 v130, v130, v131
	v_cvt_pk_bf16_f32 v131, v134, v135
	v_cvt_pk_bf16_f32 v132, v132, v133
	v_cvt_pk_bf16_f32 v133, v148, v149
	global_store_dwordx4 v[128:129], v[130:133], off offset:256 sc0 sc1 nt
	v_max_f32_e32 v147, v110, v110
	v_max_f32_e32 v148, 0, v147
	v_or_b32_e32 v130, 16, v146
	v_ashrrev_i32_e32 v131, 31, v130
	v_lshlrev_b64 v[130:131], 13, v[130:131]
	v_max_f32_e32 v147, v106, v106
	v_lshl_add_u64 v[134:135], s[92:93], 0, v[130:131]
	v_max_f32_e32 v131, v104, v104
	v_max_f32_e32 v150, 0, v147
	v_max_f32_e32 v147, v111, v111
	v_max_f32_e32 v130, v108, v108
	v_max_f32_e32 v132, 0, v131
	v_max_f32_e32 v131, v109, v109
	v_max_f32_e32 v133, v105, v105
	v_max_f32_e32 v149, 0, v147
	v_max_f32_e32 v147, v107, v107
	v_max_f32_e32 v130, 0, v130
	v_max_f32_e32 v131, 0, v131
	v_max_f32_e32 v133, 0, v133
	v_max_f32_e32 v151, 0, v147
	v_pk_mul_f32 v[130:131], v[130:131], v[130:131]
	v_pk_mul_f32 v[132:133], v[132:133], v[132:133]
	v_pk_mul_f32 v[148:149], v[148:149], v[148:149]
	v_pk_mul_f32 v[150:151], v[150:151], v[150:151]
	v_lshl_add_u64 v[134:135], v[134:135], 0, s[6:7]
	v_max_f32_e32 v147, v102, v102
	v_cvt_pk_bf16_f32 v130, v130, v131
	v_cvt_pk_bf16_f32 v131, v148, v149
	v_cvt_pk_bf16_f32 v132, v132, v133
	v_cvt_pk_bf16_f32 v133, v150, v151
	v_lshl_add_u64 v[134:135], v[134:135], 0, v[178:179]
	v_max_f32_e32 v148, 0, v147
	v_max_f32_e32 v147, v98, v98
	global_store_dwordx4 v[134:135], v[130:133], off sc0 sc1 nt
	v_max_f32_e32 v150, 0, v147
	v_max_f32_e32 v147, v103, v103
	v_max_f32_e32 v131, v96, v96
	v_max_f32_e32 v130, v100, v100
	v_max_f32_e32 v132, 0, v131
	v_max_f32_e32 v131, v101, v101
	v_max_f32_e32 v133, v97, v97
	v_max_f32_e32 v149, 0, v147
	v_max_f32_e32 v147, v99, v99
	v_max_f32_e32 v130, 0, v130
	v_max_f32_e32 v131, 0, v131
	v_max_f32_e32 v133, 0, v133
	v_max_f32_e32 v151, 0, v147
	v_pk_mul_f32 v[130:131], v[130:131], v[130:131]
	v_pk_mul_f32 v[132:133], v[132:133], v[132:133]
	v_pk_mul_f32 v[148:149], v[148:149], v[148:149]
	v_pk_mul_f32 v[150:151], v[150:151], v[150:151]
	v_cvt_pk_bf16_f32 v130, v130, v131
	v_cvt_pk_bf16_f32 v131, v148, v149
	v_cvt_pk_bf16_f32 v132, v132, v133
	v_cvt_pk_bf16_f32 v133, v150, v151
	global_store_dwordx4 v[134:135], v[130:133], off offset:256 sc0 sc1 nt
	v_max_f32_e32 v147, v94, v94
	v_max_f32_e32 v148, 0, v147
	v_or_b32_e32 v130, 32, v146
	v_ashrrev_i32_e32 v131, 31, v130
	v_lshlrev_b64 v[130:131], 13, v[130:131]
	v_max_f32_e32 v147, v90, v90
	v_lshl_add_u64 v[134:135], s[92:93], 0, v[130:131]
	v_max_f32_e32 v131, v88, v88
	v_max_f32_e32 v150, 0, v147
	v_max_f32_e32 v147, v95, v95
	v_max_f32_e32 v130, v92, v92
	v_max_f32_e32 v132, 0, v131
	v_max_f32_e32 v131, v93, v93
	v_max_f32_e32 v133, v89, v89
	v_max_f32_e32 v149, 0, v147
	v_max_f32_e32 v147, v91, v91
	v_max_f32_e32 v130, 0, v130
	v_max_f32_e32 v131, 0, v131
	v_max_f32_e32 v133, 0, v133
	v_max_f32_e32 v151, 0, v147
	v_pk_mul_f32 v[130:131], v[130:131], v[130:131]
	v_pk_mul_f32 v[132:133], v[132:133], v[132:133]
	v_pk_mul_f32 v[148:149], v[148:149], v[148:149]
	v_pk_mul_f32 v[150:151], v[150:151], v[150:151]
	v_lshl_add_u64 v[134:135], v[134:135], 0, s[6:7]
	v_max_f32_e32 v147, v86, v86
	v_cvt_pk_bf16_f32 v130, v130, v131
	v_cvt_pk_bf16_f32 v131, v148, v149
	v_cvt_pk_bf16_f32 v132, v132, v133
	v_cvt_pk_bf16_f32 v133, v150, v151
	v_lshl_add_u64 v[134:135], v[134:135], 0, v[178:179]
	v_max_f32_e32 v148, 0, v147
	v_max_f32_e32 v147, v82, v82
	global_store_dwordx4 v[134:135], v[130:133], off sc0 sc1 nt
	v_max_f32_e32 v150, 0, v147
	v_max_f32_e32 v147, v87, v87
	v_max_f32_e32 v131, v80, v80
	v_max_f32_e32 v130, v84, v84
	v_max_f32_e32 v132, 0, v131
	v_max_f32_e32 v131, v85, v85
; __device__ __forceinline__ unsigned pk2(float lo, float hi) { f32v2 v = {lo, hi}; bf16v2 r = __builtin_convertvector(v, bf16v2); return __builtin_bit_cast(unsigned, r); }
;     __device__ __forceinline__ void operator()(f32x4 (&acc)[2][2][4][2], const Unit& u, int wr, int wc, int fr, int fq) const {
;     ...
; #pragma unroll
;         for (int ai = 0; ai < 2; ++ai)
; #pragma unroll
;             for (int m = 0; m < 4; ++m) {
;                 const size_t row = (size_t)(row0 + ai * HALF + m * 16);
; #pragma unroll
;                 for (int bj = 0; bj < 2; ++bj) {
;                     f32x4 v0 = acc[ai][bj][m][0], v1 = acc[ai][bj][m][1];
;                     const int cl = cl0 + bj * HALF;
;                     if constexpr (MODE == 0 || MODE == 1) {
;                         if (MODE == 1) {
; #pragma unroll
;                             for (int e = 0; e < 4; ++e) { const float a = fmaxf(v0[e], 0.f), b = fmaxf(v1[e], 0.f); v0[e] = a * a; v1[e] = b * b; }
;                         }
;                         u32x4 w; w.x = pk2(v0[0], v0[1]); w.y = pk2(v0[2], v0[3]); w.z = pk2(v1[0], v1[1]); w.w = pk2(v1[2], v1[3]);
;                         if constexpr (MODE == 1) __builtin_nontemporal_store(w, (u32x4*)(O + row * ldc + u.pn * BM + cl));
	v_max_f32_e32 v133, v81, v81
	v_max_f32_e32 v149, 0, v147
	v_max_f32_e32 v147, v83, v83
	v_max_f32_e32 v130, 0, v130
	v_max_f32_e32 v131, 0, v131
	v_max_f32_e32 v133, 0, v133
	v_max_f32_e32 v151, 0, v147
	v_pk_mul_f32 v[130:131], v[130:131], v[130:131]
	v_pk_mul_f32 v[132:133], v[132:133], v[132:133]
	v_pk_mul_f32 v[148:149], v[148:149], v[148:149]
	v_pk_mul_f32 v[150:151], v[150:151], v[150:151]
	v_cvt_pk_bf16_f32 v130, v130, v131
	v_cvt_pk_bf16_f32 v131, v148, v149
	v_cvt_pk_bf16_f32 v132, v132, v133
	v_cvt_pk_bf16_f32 v133, v150, v151
	global_store_dwordx4 v[134:135], v[130:133], off offset:256 sc0 sc1 nt
	v_max_f32_e32 v147, v78, v78
	v_max_f32_e32 v148, 0, v147
	v_or_b32_e32 v130, 48, v146
	v_ashrrev_i32_e32 v131, 31, v130
	v_lshlrev_b64 v[130:131], 13, v[130:131]
	v_max_f32_e32 v147, v74, v74
	v_lshl_add_u64 v[134:135], s[92:93], 0, v[130:131]
	v_max_f32_e32 v131, v72, v72
	v_max_f32_e32 v150, 0, v147
	v_max_f32_e32 v147, v79, v79
	v_max_f32_e32 v130, v76, v76
	v_max_f32_e32 v132, 0, v131
	v_max_f32_e32 v131, v77, v77
	v_max_f32_e32 v133, v73, v73
	v_max_f32_e32 v149, 0, v147
	v_max_f32_e32 v147, v75, v75
	v_max_f32_e32 v130, 0, v130
	v_max_f32_e32 v131, 0, v131
	v_max_f32_e32 v133, 0, v133
	v_max_f32_e32 v151, 0, v147
	v_pk_mul_f32 v[130:131], v[130:131], v[130:131]
	v_pk_mul_f32 v[132:133], v[132:133], v[132:133]
	v_pk_mul_f32 v[148:149], v[148:149], v[148:149]
	v_pk_mul_f32 v[150:151], v[150:151], v[150:151]
	v_lshl_add_u64 v[134:135], v[134:135], 0, s[6:7]
	v_max_f32_e32 v147, v70, v70
	v_cvt_pk_bf16_f32 v130, v130, v131
	v_cvt_pk_bf16_f32 v131, v148, v149
	v_cvt_pk_bf16_f32 v132, v132, v133
	v_cvt_pk_bf16_f32 v133, v150, v151
	v_lshl_add_u64 v[134:135], v[134:135], 0, v[178:179]
	v_max_f32_e32 v148, 0, v147
	v_max_f32_e32 v147, v66, v66
	global_store_dwordx4 v[134:135], v[130:133], off sc0 sc1 nt
	v_max_f32_e32 v150, 0, v147
	v_max_f32_e32 v147, v71, v71
	v_max_f32_e32 v131, v64, v64
	v_max_f32_e32 v130, v68, v68
	v_max_f32_e32 v132, 0, v131
	v_max_f32_e32 v131, v69, v69
	v_max_f32_e32 v133, v65, v65
	v_max_f32_e32 v149, 0, v147
	v_max_f32_e32 v147, v67, v67
	v_max_f32_e32 v130, 0, v130
	v_max_f32_e32 v131, 0, v131
	v_max_f32_e32 v133, 0, v133
	v_max_f32_e32 v151, 0, v147
	v_pk_mul_f32 v[130:131], v[130:131], v[130:131]
	v_pk_mul_f32 v[132:133], v[132:133], v[132:133]
	v_pk_mul_f32 v[148:149], v[148:149], v[148:149]
	v_pk_mul_f32 v[150:151], v[150:151], v[150:151]
	v_cvt_pk_bf16_f32 v130, v130, v131
	v_cvt_pk_bf16_f32 v131, v148, v149
	v_cvt_pk_bf16_f32 v132, v132, v133
	v_cvt_pk_bf16_f32 v133, v150, v151
	global_store_dwordx4 v[134:135], v[130:133], off offset:256 sc0 sc1 nt
	v_max_f32_e32 v135, v58, v58
	v_max_f32_e32 v134, v62, v62
	v_max_f32_e32 v131, v56, v56
	v_max_f32_e32 v130, v60, v60
	v_max_f32_e32 v132, 0, v131
	v_max_f32_e32 v131, v61, v61
	v_max_f32_e32 v148, 0, v135
	v_max_f32_e32 v135, v63, v63
	v_max_f32_e32 v130, 0, v130
	v_max_f32_e32 v131, 0, v131
	v_max_f32_e32 v133, v57, v57
	v_max_f32_e32 v134, 0, v134
	v_max_f32_e32 v135, 0, v135
	v_max_f32_e32 v147, v59, v59
	v_max_f32_e32 v133, 0, v133
	v_pk_mul_f32 v[130:131], v[130:131], v[130:131]
	v_max_f32_e32 v149, 0, v147
	v_pk_mul_f32 v[134:135], v[134:135], v[134:135]
	s_mov_b64 s[6:7], 0x100000
	v_pk_mul_f32 v[132:133], v[132:133], v[132:133]
	v_pk_mul_f32 v[148:149], v[148:149], v[148:149]
	v_cvt_pk_bf16_f32 v130, v130, v131
	v_cvt_pk_bf16_f32 v131, v134, v135
	v_lshl_add_u64 v[134:135], v[128:129], 0, s[6:7]
	s_mov_b32 s6, 0x100000
	v_cvt_pk_bf16_f32 v132, v132, v133
	v_cvt_pk_bf16_f32 v133, v148, v149
	v_add_co_u32_e32 v148, vcc, s6, v128
	v_max_f32_e32 v147, v54, v54
	s_nop 0
	v_addc_co_u32_e32 v149, vcc, 0, v129, vcc
	global_store_dwordx4 v[148:149], v[130:133], off sc0 sc1 nt
	v_max_f32_e32 v148, 0, v147
	v_max_f32_e32 v147, v50, v50
	v_max_f32_e32 v131, v48, v48
	v_max_f32_e32 v150, 0, v147
	v_max_f32_e32 v147, v55, v55
	v_max_f32_e32 v130, v52, v52
	v_max_f32_e32 v132, 0, v131
	v_max_f32_e32 v131, v53, v53
	v_max_f32_e32 v133, v49, v49
	v_max_f32_e32 v149, 0, v147
	v_max_f32_e32 v147, v51, v51
	v_max_f32_e32 v130, 0, v130
	v_max_f32_e32 v131, 0, v131
	v_max_f32_e32 v133, 0, v133
	v_max_f32_e32 v151, 0, v147
	v_pk_mul_f32 v[130:131], v[130:131], v[130:131]
	v_pk_mul_f32 v[132:133], v[132:133], v[132:133]
	v_pk_mul_f32 v[148:149], v[148:149], v[148:149]
	v_pk_mul_f32 v[150:151], v[150:151], v[150:151]
	v_cvt_pk_bf16_f32 v130, v130, v131
	v_cvt_pk_bf16_f32 v131, v148, v149
	v_cvt_pk_bf16_f32 v132, v132, v133
	v_cvt_pk_bf16_f32 v133, v150, v151
	global_store_dwordx4 v[134:135], v[130:133], off offset:256 sc0 sc1 nt
	v_max_f32_e32 v135, v42, v42
	v_max_f32_e32 v134, v46, v46
	v_max_f32_e32 v131, v40, v40
	v_max_f32_e32 v130, v44, v44
	v_max_f32_e32 v132, 0, v131
	v_max_f32_e32 v131, v45, v45
	v_max_f32_e32 v148, 0, v135
	v_max_f32_e32 v135, v47, v47
	v_max_f32_e32 v130, 0, v130
	v_max_f32_e32 v131, 0, v131
	v_max_f32_e32 v133, v41, v41
	v_max_f32_e32 v134, 0, v134
	v_max_f32_e32 v135, 0, v135
	v_max_f32_e32 v147, v43, v43
	v_max_f32_e32 v133, 0, v133
	v_pk_mul_f32 v[130:131], v[130:131], v[130:131]
	v_max_f32_e32 v149, 0, v147
	v_pk_mul_f32 v[134:135], v[134:135], v[134:135]
	s_mov_b64 s[6:7], 0x120000
; __device__ __forceinline__ unsigned pk2(float lo, float hi) { f32v2 v = {lo, hi}; bf16v2 r = __builtin_convertvector(v, bf16v2); return __builtin_bit_cast(unsigned, r); }
;     __device__ __forceinline__ void operator()(f32x4 (&acc)[2][2][4][2], const Unit& u, int wr, int wc, int fr, int fq) const {
;     ...
; #pragma unroll
;         for (int ai = 0; ai < 2; ++ai)
; #pragma unroll
;             for (int m = 0; m < 4; ++m) {
;                 const size_t row = (size_t)(row0 + ai * HALF + m * 16);
; #pragma unroll
;                 for (int bj = 0; bj < 2; ++bj) {
;                     f32x4 v0 = acc[ai][bj][m][0], v1 = acc[ai][bj][m][1];
;                     const int cl = cl0 + bj * HALF;
;                     if constexpr (MODE == 0 || MODE == 1) {
;                         if (MODE == 1) {
; #pragma unroll
;                             for (int e = 0; e < 4; ++e) { const float a = fmaxf(v0[e], 0.f), b = fmaxf(v1[e], 0.f); v0[e] = a * a; v1[e] = b * b; }
;                         }
;                         u32x4 w; w.x = pk2(v0[0], v0[1]); w.y = pk2(v0[2], v0[3]); w.z = pk2(v1[0], v1[1]); w.w = pk2(v1[2], v1[3]);
;                         if constexpr (MODE == 1) __builtin_nontemporal_store(w, (u32x4*)(O + row * ldc + u.pn * BM + cl));
	v_pk_mul_f32 v[132:133], v[132:133], v[132:133]
	v_pk_mul_f32 v[148:149], v[148:149], v[148:149]
	v_cvt_pk_bf16_f32 v130, v130, v131
	v_cvt_pk_bf16_f32 v131, v134, v135
	v_lshl_add_u64 v[134:135], v[128:129], 0, s[6:7]
	s_mov_b32 s6, 0x120000
	v_cvt_pk_bf16_f32 v132, v132, v133
	v_cvt_pk_bf16_f32 v133, v148, v149
	v_add_co_u32_e32 v148, vcc, s6, v128
	v_max_f32_e32 v147, v38, v38
	s_nop 0
	v_addc_co_u32_e32 v149, vcc, 0, v129, vcc
	global_store_dwordx4 v[148:149], v[130:133], off sc0 sc1 nt
	v_max_f32_e32 v148, 0, v147
	v_max_f32_e32 v147, v34, v34
	v_max_f32_e32 v131, v32, v32
	v_max_f32_e32 v150, 0, v147
	v_max_f32_e32 v147, v39, v39
	v_max_f32_e32 v130, v36, v36
	v_max_f32_e32 v132, 0, v131
	v_max_f32_e32 v131, v37, v37
	v_max_f32_e32 v133, v33, v33
	v_max_f32_e32 v149, 0, v147
	v_max_f32_e32 v147, v35, v35
	v_max_f32_e32 v130, 0, v130
	v_max_f32_e32 v131, 0, v131
	v_max_f32_e32 v133, 0, v133
	v_max_f32_e32 v151, 0, v147
	v_pk_mul_f32 v[130:131], v[130:131], v[130:131]
	v_pk_mul_f32 v[132:133], v[132:133], v[132:133]
	v_pk_mul_f32 v[148:149], v[148:149], v[148:149]
	v_pk_mul_f32 v[150:151], v[150:151], v[150:151]
	v_cvt_pk_bf16_f32 v130, v130, v131
	v_cvt_pk_bf16_f32 v131, v148, v149
	v_cvt_pk_bf16_f32 v132, v132, v133
	v_cvt_pk_bf16_f32 v133, v150, v151
	global_store_dwordx4 v[134:135], v[130:133], off offset:256 sc0 sc1 nt
	v_max_f32_e32 v135, v26, v26
	v_max_f32_e32 v134, v30, v30
	v_max_f32_e32 v131, v24, v24
	v_max_f32_e32 v130, v28, v28
	v_max_f32_e32 v132, 0, v131
	v_max_f32_e32 v131, v29, v29
	v_max_f32_e32 v148, 0, v135
	v_max_f32_e32 v135, v31, v31
	v_max_f32_e32 v130, 0, v130
	v_max_f32_e32 v131, 0, v131
	v_max_f32_e32 v133, v25, v25
	v_max_f32_e32 v134, 0, v134
	v_max_f32_e32 v135, 0, v135
	v_max_f32_e32 v147, v27, v27
	v_max_f32_e32 v133, 0, v133
	v_pk_mul_f32 v[130:131], v[130:131], v[130:131]
	v_max_f32_e32 v149, 0, v147
	v_pk_mul_f32 v[134:135], v[134:135], v[134:135]
	s_mov_b64 s[6:7], 0x140000
	v_pk_mul_f32 v[132:133], v[132:133], v[132:133]
	v_pk_mul_f32 v[148:149], v[148:149], v[148:149]
	v_cvt_pk_bf16_f32 v130, v130, v131
	v_cvt_pk_bf16_f32 v131, v134, v135
	v_lshl_add_u64 v[134:135], v[128:129], 0, s[6:7]
	s_mov_b32 s6, 0x140000
	v_cvt_pk_bf16_f32 v132, v132, v133
	v_cvt_pk_bf16_f32 v133, v148, v149
	v_add_co_u32_e32 v148, vcc, s6, v128
	v_max_f32_e32 v147, v22, v22
	s_nop 0
	v_addc_co_u32_e32 v149, vcc, 0, v129, vcc
	global_store_dwordx4 v[148:149], v[130:133], off sc0 sc1 nt
	v_max_f32_e32 v148, 0, v147
	v_max_f32_e32 v147, v18, v18
	v_max_f32_e32 v131, v16, v16
	v_max_f32_e32 v150, 0, v147
	v_max_f32_e32 v147, v23, v23
	v_max_f32_e32 v130, v20, v20
	v_max_f32_e32 v132, 0, v131
	v_max_f32_e32 v131, v21, v21
	v_max_f32_e32 v133, v17, v17
	v_max_f32_e32 v149, 0, v147
	v_max_f32_e32 v147, v19, v19
	v_max_f32_e32 v130, 0, v130
	v_max_f32_e32 v131, 0, v131
	v_max_f32_e32 v133, 0, v133
	v_max_f32_e32 v151, 0, v147
	v_pk_mul_f32 v[130:131], v[130:131], v[130:131]
	v_pk_mul_f32 v[132:133], v[132:133], v[132:133]
	v_pk_mul_f32 v[148:149], v[148:149], v[148:149]
	v_pk_mul_f32 v[150:151], v[150:151], v[150:151]
	v_cvt_pk_bf16_f32 v130, v130, v131
	v_cvt_pk_bf16_f32 v131, v148, v149
	v_cvt_pk_bf16_f32 v132, v132, v133
	v_cvt_pk_bf16_f32 v133, v150, v151
	global_store_dwordx4 v[134:135], v[130:133], off offset:256 sc0 sc1 nt
	v_max_f32_e32 v135, v10, v10
	v_max_f32_e32 v134, v14, v14
	v_max_f32_e32 v131, v8, v8
	v_max_f32_e32 v130, v12, v12
	v_max_f32_e32 v132, 0, v131
	v_max_f32_e32 v131, v13, v13
	v_max_f32_e32 v148, 0, v135
	v_max_f32_e32 v135, v15, v15
	v_max_f32_e32 v130, 0, v130
	v_max_f32_e32 v131, 0, v131
	v_max_f32_e32 v134, 0, v134
	v_max_f32_e32 v135, 0, v135
	v_max_f32_e32 v133, v9, v9
	v_pk_mul_f32 v[130:131], v[130:131], v[130:131]
	v_max_f32_e32 v147, v11, v11
	v_pk_mul_f32 v[134:135], v[134:135], v[134:135]
	s_mov_b64 s[6:7], 0x160000
	v_max_f32_e32 v133, 0, v133
	v_max_f32_e32 v149, 0, v147
	v_cvt_pk_bf16_f32 v130, v130, v131
	v_cvt_pk_bf16_f32 v131, v134, v135
	v_lshl_add_u64 v[134:135], v[128:129], 0, s[6:7]
	s_mov_b32 s6, 0x160000
	v_pk_mul_f32 v[132:133], v[132:133], v[132:133]
	v_pk_mul_f32 v[148:149], v[148:149], v[148:149]
	v_add_co_u32_e32 v128, vcc, s6, v128
	v_cvt_pk_bf16_f32 v132, v132, v133
	v_cvt_pk_bf16_f32 v133, v148, v149
	v_addc_co_u32_e32 v129, vcc, 0, v129, vcc
	global_store_dwordx4 v[128:129], v[130:133], off sc0 sc1 nt
	v_max_f32_e32 v129, v0, v0
	v_max_f32_e32 v128, v4, v4
	v_max_f32_e32 v133, v2, v2
	v_max_f32_e32 v130, 0, v129
	v_max_f32_e32 v129, v5, v5
	v_max_f32_e32 v131, v1, v1
	v_max_f32_e32 v132, v6, v6
	v_max_f32_e32 v148, 0, v133
	v_max_f32_e32 v133, v7, v7
	v_max_f32_e32 v147, v3, v3
	v_max_f32_e32 v128, 0, v128
	v_max_f32_e32 v129, 0, v129
	v_max_f32_e32 v131, 0, v131
	v_max_f32_e32 v132, 0, v132
	v_max_f32_e32 v133, 0, v133
	v_max_f32_e32 v149, 0, v147
	v_pk_mul_f32 v[128:129], v[128:129], v[128:129]
	v_pk_mul_f32 v[130:131], v[130:131], v[130:131]
	v_pk_mul_f32 v[132:133], v[132:133], v[132:133]
	v_pk_mul_f32 v[148:149], v[148:149], v[148:149]
	v_cvt_pk_bf16_f32 v128, v128, v129
	v_cvt_pk_bf16_f32 v129, v132, v133
	v_cvt_pk_bf16_f32 v130, v130, v131
	v_cvt_pk_bf16_f32 v131, v148, v149
	global_store_dwordx4 v[134:135], v[128:131], off offset:256 sc0 sc1 nt
